# remaining wave shuffles (norm phases, attention finalize, cross-attention) via DPP/permlane-swap; removed 36 pk_add-with-zero register copies in attention tile bodies (on top of v024)
# speedup vs baseline: 1.0069x; 1.0069x over previous
; template <int N> DI void wave_sum_n(float (&v)[N]) {
; #pragma unroll
;     for (int o = 1; o < 64; o <<= 1) {
;         float t[N];
; #pragma unroll
;         for (int i = 0; i < N; ++i) t[i] = __shfl_xor(v[i], o);
; #pragma unroll
;         for (int i = 0; i < N; ++i) v[i] += t[i]; }
; }
; template <int MODE>
; DI void norm_phase(const Args& a, const Frame& F, int nslab, float sscale, float* RSTD, const float* SSP) {
;     ...
;         float ss[RB];
; #pragma unroll
;         for (int r = 0; r < RB; ++r) { ss[r] = 0.f;
; #pragma unroll
;             for (int j = 0; j < 4; ++j) ss[r] += (v[r][j][0] * v[r][j][0] + v[r][j][1] * v[r][j][1]) + (v[r][j][2] * v[r][j][2] + v[r][j][3] * v[r][j][3]); }
;         wave_sum_n<RB>(ss);
; #pragma unroll
;         for (int r = 0; r < RB; ++r) if (ok[r]) { const int row = rows[r];
;             const float rstd = 1.f / sqrtf(ss[r] * (1.f / DM) + EPS);
.LBB0_225:
	v_mul_f32_e32 v60, v15, v15
	s_waitcnt lgkmcnt(0)
	v_mul_f32_e32 v61, v13, v13
	v_fmac_f32_e32 v60, v14, v14
	v_fmac_f32_e32 v61, v12, v12
	v_add_f32_e32 v60, v60, v61
	v_mul_f32_e32 v61, v19, v19
	v_mul_f32_e32 v62, v17, v17
	v_fmac_f32_e32 v61, v18, v18
	v_fmac_f32_e32 v62, v16, v16
	v_add_f32_e32 v61, v61, v62
	v_add_f32_e32 v60, v61, v60
	v_mul_f32_e32 v61, v23, v23
	v_mul_f32_e32 v62, v21, v21
	v_fmac_f32_e32 v61, v22, v22
	v_fmac_f32_e32 v62, v20, v20
	v_add_f32_e32 v61, v61, v62
	v_add_f32_e32 v60, v61, v60
	v_mul_f32_e32 v61, v27, v27
	v_mul_f32_e32 v62, v25, v25
	v_fmac_f32_e32 v61, v26, v26
	v_fmac_f32_e32 v62, v24, v24
	v_add_f32_e32 v61, v61, v62
	v_add_f32_e32 v60, v61, v60
	v_mul_f32_e32 v61, v37, v37
	v_mul_f32_e32 v62, v33, v33
	v_fmac_f32_e32 v61, v36, v36
	v_fmac_f32_e32 v62, v32, v32
	v_add_f32_e32 v61, v61, v62
	v_mul_f32_e32 v62, v43, v43
	s_waitcnt lgkmcnt(0)
	v_mul_f32_e32 v63, v41, v41
	v_fmac_f32_e32 v62, v42, v42
	v_fmac_f32_e32 v63, v40, v40
	v_add_f32_e32 v62, v62, v63
	v_add_f32_e32 v61, v62, v61
	v_mul_f32_e32 v62, v47, v47
	v_mul_f32_e32 v63, v45, v45
	v_fmac_f32_e32 v62, v46, v46
	v_fmac_f32_e32 v63, v44, v44
	v_add_f32_e32 v62, v62, v63
	v_add_f32_e32 v61, v61, v62
	v_mul_f32_e32 v62, v51, v51
	v_mul_f32_e32 v63, v49, v49
	v_fmac_f32_e32 v62, v50, v50
	v_fmac_f32_e32 v63, v48, v48
	v_add_f32_e32 v62, v62, v63
	v_add_f32_e32 v61, v61, v62
	v_mul_f32_e32 v62, v53, v53
	v_mul_f32_e32 v63, v39, v39
	v_fmac_f32_e32 v62, v52, v52
	v_fmac_f32_e32 v63, v38, v38
	v_add_f32_e32 v62, v62, v63
	v_mul_f32_e32 v63, v55, v55
	v_mul_f32_e32 v64, v35, v35
	v_fmac_f32_e32 v63, v54, v54
	v_fmac_f32_e32 v64, v34, v34
	v_add_f32_e32 v63, v63, v64
	v_add_f32_e32 v62, v62, v63
	v_mul_f32_e32 v63, v57, v57
	v_mul_f32_e32 v64, v31, v31
	v_fmac_f32_e32 v63, v56, v56
	v_fmac_f32_e32 v64, v30, v30
	v_add_f32_e32 v63, v63, v64
	v_add_f32_e32 v62, v62, v63
	v_mul_f32_e32 v63, v59, v59
	v_mul_f32_e32 v64, v29, v29
	v_fmac_f32_e32 v63, v58, v58
	v_fmac_f32_e32 v64, v28, v28
	v_add_f32_e32 v63, v63, v64
	v_add_f32_e32 v62, v62, v63
	v_mov_b32_dpp v63, v60 quad_perm:[1,0,3,2] row_mask:0xf bank_mask:0xf
	v_mov_b32_dpp v64, v61 quad_perm:[1,0,3,2] row_mask:0xf bank_mask:0xf
	v_mov_b32_dpp v65, v62 quad_perm:[1,0,3,2] row_mask:0xf bank_mask:0xf
	s_waitcnt lgkmcnt(0)
	v_add_f32_e32 v60, v60, v63
	s_waitcnt lgkmcnt(0)
	v_add_f32_e32 v61, v61, v64
	s_waitcnt lgkmcnt(0)
	v_add_f32_e32 v62, v62, v65
	v_mov_b32_dpp v63, v60 quad_perm:[2,3,0,1] row_mask:0xf bank_mask:0xf
	v_mov_b32_dpp v64, v61 quad_perm:[2,3,0,1] row_mask:0xf bank_mask:0xf
	v_mov_b32_dpp v65, v62 quad_perm:[2,3,0,1] row_mask:0xf bank_mask:0xf
	s_waitcnt lgkmcnt(0)
	v_add_f32_e32 v60, v60, v63
	s_waitcnt lgkmcnt(0)
	v_add_f32_e32 v61, v61, v64
	s_waitcnt lgkmcnt(0)
	v_add_f32_e32 v62, v62, v65
	v_mov_b32_dpp v63, v60 row_half_mirror row_mask:0xf bank_mask:0xf
	v_mov_b32_dpp v64, v61 row_half_mirror row_mask:0xf bank_mask:0xf
	v_mov_b32_dpp v65, v62 row_half_mirror row_mask:0xf bank_mask:0xf
	s_waitcnt lgkmcnt(0)
	v_add_f32_e32 v60, v60, v63
	s_waitcnt lgkmcnt(0)
	v_add_f32_e32 v61, v61, v64
	s_waitcnt lgkmcnt(0)
	v_add_f32_e32 v62, v62, v65
	v_mov_b32_dpp v63, v60 row_ror:8 row_mask:0xf bank_mask:0xf
	v_mov_b32_dpp v64, v61 row_ror:8 row_mask:0xf bank_mask:0xf
	v_mov_b32_dpp v65, v62 row_ror:8 row_mask:0xf bank_mask:0xf
	s_waitcnt lgkmcnt(0)
	v_add_f32_e32 v60, v60, v63
	s_waitcnt lgkmcnt(0)
	v_add_f32_e32 v61, v61, v64
	s_waitcnt lgkmcnt(0)
	v_add_f32_e32 v63, v62, v65
	v_mov_b32_e32 v62, v60
	v_mov_b32_e32 v254, v60
	s_nop 1
	v_permlane16_swap_b32_e32 v62, v254
	s_nop 1
	v_mov_b32_dpp v62, v254 quad_perm:[0,1,2,3] row_mask:0x5 bank_mask:0xf
	v_mov_b32_e32 v65, v61
	v_mov_b32_e32 v255, v61
	s_nop 1
	v_permlane16_swap_b32_e32 v65, v255
	s_nop 1
	v_mov_b32_dpp v65, v255 quad_perm:[0,1,2,3] row_mask:0x5 bank_mask:0xf
	v_mov_b32_e32 v66, v63
	v_mov_b32_e32 v254, v63
	s_nop 1
	v_permlane16_swap_b32_e32 v66, v254
	s_nop 1
	v_mov_b32_dpp v66, v254 quad_perm:[0,1,2,3] row_mask:0x5 bank_mask:0xf
	s_waitcnt lgkmcnt(0)
	v_add_f32_e32 v64, v60, v62
	s_waitcnt lgkmcnt(0)
	v_add_f32_e32 v62, v61, v65
	s_waitcnt lgkmcnt(0)
	v_add_f32_e32 v60, v63, v66
	v_mov_b32_e32 v65, v64
	v_mov_b32_e32 v255, v64
	s_nop 1
	v_permlane32_swap_b32_e32 v65, v255
	s_nop 1
	v_mov_b32_dpp v65, v255 quad_perm:[0,1,2,3] row_mask:0x3 bank_mask:0xf
	v_mov_b32_e32 v63, v62
	v_mov_b32_e32 v254, v62
	s_nop 1
	v_permlane32_swap_b32_e32 v63, v254
	s_nop 1
	v_mov_b32_dpp v63, v254 quad_perm:[0,1,2,3] row_mask:0x3 bank_mask:0xf
	v_mov_b32_e32 v61, v60
	v_mov_b32_e32 v255, v60
	s_nop 1
	v_permlane32_swap_b32_e32 v61, v255
	s_nop 1
	v_mov_b32_dpp v61, v255 quad_perm:[0,1,2,3] row_mask:0x3 bank_mask:0xf
	s_and_saveexec_b64 s[16:17], s[2:3]
	s_cbranch_execz .LBB0_227
	s_waitcnt lgkmcnt(0)
	v_add_f32_e32 v64, v64, v65
	v_fmamk_f32 v64, v64, 0x3a800000, v1
	v_mul_f32_e32 v65, 0x4f800000, v64
	v_cmp_gt_f32_e32 vcc, s67, v64
	s_nop 1
	v_cndmask_b32_e32 v64, v64, v65, vcc
	v_sqrt_f32_e32 v65, v64
	s_nop 0
	v_add_u32_e32 v66, -1, v65
	v_add_u32_e32 v67, 1, v65
	v_fma_f32 v68, -v66, v65, v64
	v_fma_f32 v69, -v67, v65, v64
	v_cmp_ge_f32_e64 s[4:5], 0, v68
	s_nop 1
	v_cndmask_b32_e64 v65, v65, v66, s[4:5]
	v_cmp_lt_f32_e64 s[4:5], 0, v69
	s_nop 1
	v_cndmask_b32_e64 v65, v65, v67, s[4:5]
	v_mul_f32_e32 v66, 0x37800000, v65
	v_cndmask_b32_e32 v65, v65, v66, vcc
	v_cmp_class_f32_e32 vcc, v64, v196
	s_nop 1
	v_cndmask_b32_e32 v64, v65, v64, vcc
	v_div_scale_f32 v65, s[4:5], v64, v64, 1.0
	v_rcp_f32_e32 v66, v65
	s_nop 0
	v_fma_f32 v67, -v65, v66, 1.0
	v_fmac_f32_e32 v66, v67, v66
	v_div_scale_f32 v67, vcc, 1.0, v64, 1.0
	v_mul_f32_e32 v68, v67, v66
	v_fma_f32 v69, -v65, v68, v67
	v_fmac_f32_e32 v68, v69, v66
	v_fma_f32 v65, -v65, v68, v67
	v_div_fmas_f32 v65, v65, v66, v68
	v_div_fixup_f32 v64, v65, v64, 1.0
	global_store_dword v2, v64, s[6:7]
; DI unsigned pk2(float lo, float hi) { const f32x2 v = {lo, hi}; return __builtin_bit_cast(unsigned, __builtin_convertvector(v, hwbf16x2)); }
; template <int MODE>
; DI void norm_phase(const Args& a, const Frame& F, int nslab, float sscale, float* RSTD, const float* SSP) {
;     ...
;         for (int r = 0; r < RB; ++r) if (ok[r]) { const int row = rows[r];
;             const float rstd = 1.f / sqrtf(ss[r] * (1.f / DM) + EPS);
;             if (MODE == 2) {
;                 float* o = (row < NP) ? a.out + O_YP + (size_t)row * DM : a.out + O_YS + (size_t)(row - NP) * DM;
; #pragma unroll
;                 for (int j = 0; j < 4; ++j) { const f32x4 g = ((const f32x4*)a.in[I_FINAL])[F.lane + 64 * j]; ((f32x4*)o)[F.lane + 64 * j] = v[r][j] * rstd * g; }
;             } else {
;                 if (F.lane == 0) RSTD[row] = rstd;
; #pragma unroll
;                 for (int j = 0; j < 4; ++j) { u32x2 w; w.x = pk2(v[r][j][0], v[r][j][1]); w.y = pk2(v[r][j][2], v[r][j][3]); ((u32x2*)(X + (size_t)row * DM))[F.lane + 64 * j] = w; }
.LBB0_227:
	s_or_b64 exec, exec, s[16:17]
	v_cvt_pk_bf16_f32 v14, v14, v15
	v_cvt_pk_bf16_f32 v15, v12, v13
	v_cvt_pk_bf16_f32 v12, v18, v19
	v_cvt_pk_bf16_f32 v13, v16, v17
	global_store_dwordx2 v[6:7], v[12:13], off offset:512
	v_cvt_pk_bf16_f32 v12, v22, v23
	v_cvt_pk_bf16_f32 v13, v20, v21
	global_store_dwordx2 v[6:7], v[12:13], off offset:1024
	v_cvt_pk_bf16_f32 v12, v26, v27
	v_cvt_pk_bf16_f32 v13, v24, v25
	s_andn2_b64 vcc, exec, s[14:15]
	global_store_dwordx2 v[6:7], v[14:15], off
	global_store_dwordx2 v[6:7], v[12:13], off offset:1536
	s_cbranch_vccnz .LBB0_231
	s_and_saveexec_b64 s[14:15], s[2:3]
	s_cbranch_execz .LBB0_230
	s_waitcnt lgkmcnt(0)
	v_add_f32_e32 v12, v62, v63
	v_fmamk_f32 v12, v12, 0x3a800000, v1
	v_mul_f32_e32 v13, 0x4f800000, v12
	v_cmp_gt_f32_e32 vcc, s67, v12
	s_nop 1
	v_cndmask_b32_e32 v12, v12, v13, vcc
	v_sqrt_f32_e32 v13, v12
	s_nop 0
	v_add_u32_e32 v14, -1, v13
	v_add_u32_e32 v15, 1, v13
	v_fma_f32 v16, -v14, v13, v12
	v_fma_f32 v17, -v15, v13, v12
	v_cmp_ge_f32_e64 s[4:5], 0, v16
	s_nop 1
	v_cndmask_b32_e64 v13, v13, v14, s[4:5]
	v_cmp_lt_f32_e64 s[4:5], 0, v17
	s_nop 1
	v_cndmask_b32_e64 v13, v13, v15, s[4:5]
	v_mul_f32_e32 v14, 0x37800000, v13
	v_cndmask_b32_e32 v13, v13, v14, vcc
	v_cmp_class_f32_e32 vcc, v12, v196
	s_nop 1
	v_cndmask_b32_e32 v12, v13, v12, vcc
	v_div_scale_f32 v13, s[4:5], v12, v12, 1.0
	v_rcp_f32_e32 v14, v13
	s_lshl_b64 s[4:5], s[12:13], 2
	s_add_u32 s4, s20, s4
	s_addc_u32 s5, s21, s5
	v_fma_f32 v15, -v13, v14, 1.0
	v_fmac_f32_e32 v14, v15, v14
	v_div_scale_f32 v15, vcc, 1.0, v12, 1.0
	v_mul_f32_e32 v16, v15, v14
	v_fma_f32 v17, -v13, v16, v15
	v_fmac_f32_e32 v16, v17, v14
	v_fma_f32 v13, -v13, v16, v15
	v_div_fmas_f32 v13, v13, v14, v16
	v_div_fixup_f32 v12, v13, v12, 1.0
	global_store_dword v2, v12, s[4:5]

; template <int N> DI void wave_sum_n(float (&v)[N]) {
; #pragma unroll
;     for (int o = 1; o < 64; o <<= 1) {
;         float t[N];
; #pragma unroll
;         for (int i = 0; i < N; ++i) t[i] = __shfl_xor(v[i], o);
; #pragma unroll
;         for (int i = 0; i < N; ++i) v[i] += t[i]; }
; }
; template <int MODE>
; DI void norm_phase(const Args& a, const Frame& F, int nslab, float sscale, float* RSTD, const float* SSP) {
;     ...
;         float ss[RB];
; #pragma unroll
;         for (int r = 0; r < RB; ++r) { ss[r] = 0.f;
; #pragma unroll
;             for (int j = 0; j < 4; ++j) ss[r] += (v[r][j][0] * v[r][j][0] + v[r][j][1] * v[r][j][1]) + (v[r][j][2] * v[r][j][2] + v[r][j][3] * v[r][j][3]); }
;         wave_sum_n<RB>(ss);
; #pragma unroll
;         for (int r = 0; r < RB; ++r) if (ok[r]) { const int row = rows[r];
;             const float rstd = 1.f / sqrtf(ss[r] * (1.f / DM) + EPS);
.LBB0_508:
	v_mul_f32_e32 v28, v15, v15
	v_mul_f32_e32 v29, v13, v13
	v_fmac_f32_e32 v28, v14, v14
	v_fmac_f32_e32 v29, v12, v12
	v_add_f32_e32 v28, v28, v29
	v_mul_f32_e32 v29, v19, v19
	v_mul_f32_e32 v62, v17, v17
	v_fmac_f32_e32 v29, v18, v18
	v_fmac_f32_e32 v62, v16, v16
	v_add_f32_e32 v29, v29, v62
	v_add_f32_e32 v28, v29, v28
	v_mul_f32_e32 v29, v23, v23
	v_mul_f32_e32 v62, v21, v21
	v_fmac_f32_e32 v29, v22, v22
	v_fmac_f32_e32 v62, v20, v20
	v_add_f32_e32 v29, v29, v62
	v_add_f32_e32 v28, v29, v28
	v_mul_f32_e32 v29, v27, v27
	v_mul_f32_e32 v62, v25, v25
	v_fmac_f32_e32 v29, v26, v26
	v_fmac_f32_e32 v62, v24, v24
	v_add_f32_e32 v29, v29, v62
	v_add_f32_e32 v28, v29, v28
	v_mul_f32_e32 v29, v39, v39
	v_mul_f32_e32 v62, v37, v37
	v_fmac_f32_e32 v29, v38, v38
	v_fmac_f32_e32 v62, v36, v36
	v_add_f32_e32 v29, v29, v62
	v_mul_f32_e32 v62, v45, v45
	v_mul_f32_e32 v63, v41, v41
	v_fmac_f32_e32 v62, v44, v44
	v_fmac_f32_e32 v63, v40, v40
	v_add_f32_e32 v62, v62, v63
	v_add_f32_e32 v29, v62, v29
	v_mul_f32_e32 v62, v51, v51
	v_mul_f32_e32 v63, v49, v49
	v_fmac_f32_e32 v62, v50, v50
	v_fmac_f32_e32 v63, v48, v48
	v_add_f32_e32 v62, v62, v63
	v_add_f32_e32 v29, v29, v62
	v_mul_f32_e32 v62, v47, v47
	v_mul_f32_e32 v63, v43, v43
	v_fmac_f32_e32 v62, v46, v46
	v_fmac_f32_e32 v63, v42, v42
	v_add_f32_e32 v62, v62, v63
	v_add_f32_e32 v29, v29, v62
	v_mul_f32_e32 v62, v53, v53
	v_mul_f32_e32 v63, v35, v35
	v_fmac_f32_e32 v62, v52, v52
	v_fmac_f32_e32 v63, v34, v34
	v_add_f32_e32 v62, v62, v63
	v_mul_f32_e32 v63, v55, v55
	v_mul_f32_e32 v64, v33, v33
	v_fmac_f32_e32 v63, v54, v54
	v_fmac_f32_e32 v64, v32, v32
	v_add_f32_e32 v63, v63, v64
	v_add_f32_e32 v62, v62, v63
	v_mul_f32_e32 v63, v61, v61
	v_mul_f32_e32 v64, v59, v59
	v_fmac_f32_e32 v63, v60, v60
	v_fmac_f32_e32 v64, v58, v58
	v_add_f32_e32 v63, v63, v64
	v_add_f32_e32 v62, v62, v63
	v_mul_f32_e32 v63, v57, v57
	v_mul_f32_e32 v64, v31, v31
	v_fmac_f32_e32 v63, v56, v56
	v_fmac_f32_e32 v64, v30, v30
	v_add_f32_e32 v63, v63, v64
	v_add_f32_e32 v62, v62, v63
	v_mov_b32_dpp v63, v28 quad_perm:[1,0,3,2] row_mask:0xf bank_mask:0xf
	v_mov_b32_dpp v64, v29 quad_perm:[1,0,3,2] row_mask:0xf bank_mask:0xf
	v_mov_b32_dpp v65, v62 quad_perm:[1,0,3,2] row_mask:0xf bank_mask:0xf
	s_waitcnt lgkmcnt(0)
	v_add_f32_e32 v28, v28, v63
	s_waitcnt lgkmcnt(0)
	v_add_f32_e32 v29, v29, v64
	s_waitcnt lgkmcnt(0)
	v_add_f32_e32 v62, v62, v65
	v_mov_b32_dpp v63, v28 quad_perm:[2,3,0,1] row_mask:0xf bank_mask:0xf
	v_mov_b32_dpp v64, v29 quad_perm:[2,3,0,1] row_mask:0xf bank_mask:0xf
	v_mov_b32_dpp v65, v62 quad_perm:[2,3,0,1] row_mask:0xf bank_mask:0xf
	s_waitcnt lgkmcnt(0)
	v_add_f32_e32 v28, v28, v63
	s_waitcnt lgkmcnt(0)
	v_add_f32_e32 v29, v29, v64
	s_waitcnt lgkmcnt(0)
	v_add_f32_e32 v62, v62, v65
	v_mov_b32_dpp v63, v28 row_half_mirror row_mask:0xf bank_mask:0xf
	v_mov_b32_dpp v64, v29 row_half_mirror row_mask:0xf bank_mask:0xf
	v_mov_b32_dpp v65, v62 row_half_mirror row_mask:0xf bank_mask:0xf
	s_waitcnt lgkmcnt(0)
	v_add_f32_e32 v28, v28, v63
	s_waitcnt lgkmcnt(0)
	v_add_f32_e32 v29, v29, v64
	s_waitcnt lgkmcnt(0)
	v_add_f32_e32 v62, v62, v65
	v_mov_b32_dpp v63, v28 row_ror:8 row_mask:0xf bank_mask:0xf
	v_mov_b32_dpp v64, v29 row_ror:8 row_mask:0xf bank_mask:0xf
	v_mov_b32_dpp v65, v62 row_ror:8 row_mask:0xf bank_mask:0xf
	s_waitcnt lgkmcnt(0)
	v_add_f32_e32 v28, v28, v63
	s_waitcnt lgkmcnt(0)
	v_add_f32_e32 v29, v29, v64
	s_waitcnt lgkmcnt(0)
	v_add_f32_e32 v63, v62, v65
	v_mov_b32_e32 v62, v28
	v_mov_b32_e32 v254, v28
	s_nop 1
	v_permlane16_swap_b32_e32 v62, v254
	s_nop 1
	v_mov_b32_dpp v62, v254 quad_perm:[0,1,2,3] row_mask:0x5 bank_mask:0xf
	v_mov_b32_e32 v65, v29
	v_mov_b32_e32 v255, v29
	s_nop 1
	v_permlane16_swap_b32_e32 v65, v255
	s_nop 1
	v_mov_b32_dpp v65, v255 quad_perm:[0,1,2,3] row_mask:0x5 bank_mask:0xf
	v_mov_b32_e32 v71, v63
	v_mov_b32_e32 v254, v63
	s_nop 1
	v_permlane16_swap_b32_e32 v71, v254
	s_nop 1
	v_mov_b32_dpp v71, v254 quad_perm:[0,1,2,3] row_mask:0x5 bank_mask:0xf
	s_waitcnt lgkmcnt(0)
	v_add_f32_e32 v64, v28, v62
	s_waitcnt lgkmcnt(0)
	v_add_f32_e32 v62, v29, v65
	s_waitcnt lgkmcnt(0)
	v_add_f32_e32 v28, v63, v71
	v_mov_b32_e32 v65, v64
	v_mov_b32_e32 v255, v64
	s_nop 1
	v_permlane32_swap_b32_e32 v65, v255
	s_nop 1
	v_mov_b32_dpp v65, v255 quad_perm:[0,1,2,3] row_mask:0x3 bank_mask:0xf
	v_mov_b32_e32 v63, v62
	v_mov_b32_e32 v254, v62
	s_nop 1
	v_permlane32_swap_b32_e32 v63, v254
	s_nop 1
	v_mov_b32_dpp v63, v254 quad_perm:[0,1,2,3] row_mask:0x3 bank_mask:0xf
	v_mov_b32_e32 v29, v28
	v_mov_b32_e32 v255, v28
	s_nop 1
	v_permlane32_swap_b32_e32 v29, v255
	s_nop 1
	v_mov_b32_dpp v29, v255 quad_perm:[0,1,2,3] row_mask:0x3 bank_mask:0xf
	s_and_saveexec_b64 s[16:17], s[2:3]
	s_cbranch_execz .LBB0_510
	s_waitcnt lgkmcnt(0)
	v_add_f32_e32 v64, v64, v65
	v_fmamk_f32 v64, v64, 0x3a800000, v1
	v_mul_f32_e32 v65, 0x4f800000, v64
	v_cmp_gt_f32_e32 vcc, s67, v64
	s_nop 1
	v_cndmask_b32_e32 v64, v64, v65, vcc
	v_sqrt_f32_e32 v65, v64
	s_nop 0
	v_add_u32_e32 v71, -1, v65
	v_fma_f32 v73, -v71, v65, v64
	v_add_u32_e32 v72, 1, v65
	v_cmp_ge_f32_e64 s[4:5], 0, v73
	s_nop 1
	v_cndmask_b32_e64 v71, v65, v71, s[4:5]
	v_fma_f32 v65, -v72, v65, v64
	v_cmp_lt_f32_e64 s[4:5], 0, v65
	s_nop 1
	v_cndmask_b32_e64 v65, v71, v72, s[4:5]
	v_mul_f32_e32 v71, 0x37800000, v65
	v_cndmask_b32_e32 v65, v65, v71, vcc
	v_cmp_class_f32_e32 vcc, v64, v196
	s_nop 1
	v_cndmask_b32_e32 v64, v65, v64, vcc
	v_div_scale_f32 v65, s[4:5], v64, v64, 1.0
	v_rcp_f32_e32 v71, v65
	s_nop 0
	v_fma_f32 v72, -v65, v71, 1.0
	v_fmac_f32_e32 v71, v72, v71
	v_div_scale_f32 v72, vcc, 1.0, v64, 1.0
	v_mul_f32_e32 v73, v72, v71
	v_fma_f32 v74, -v65, v73, v72
	v_fmac_f32_e32 v73, v74, v71
	v_fma_f32 v65, -v65, v73, v72
	v_div_fmas_f32 v65, v65, v71, v73
	v_div_fixup_f32 v64, v65, v64, 1.0
	global_store_dword v2, v64, s[6:7]
; DI unsigned pk2(float lo, float hi) { const f32x2 v = {lo, hi}; return __builtin_bit_cast(unsigned, __builtin_convertvector(v, hwbf16x2)); }
; template <int MODE>
; DI void norm_phase(const Args& a, const Frame& F, int nslab, float sscale, float* RSTD, const float* SSP) {
;     ...
;         for (int r = 0; r < RB; ++r) if (ok[r]) { const int row = rows[r];
;             const float rstd = 1.f / sqrtf(ss[r] * (1.f / DM) + EPS);
;             if (MODE == 2) {
;                 float* o = (row < NP) ? a.out + O_YP + (size_t)row * DM : a.out + O_YS + (size_t)(row - NP) * DM;
; #pragma unroll
;                 for (int j = 0; j < 4; ++j) { const f32x4 g = ((const f32x4*)a.in[I_FINAL])[F.lane + 64 * j]; ((f32x4*)o)[F.lane + 64 * j] = v[r][j] * rstd * g; }
;             } else {
;                 if (F.lane == 0) RSTD[row] = rstd;
; #pragma unroll
;                 for (int j = 0; j < 4; ++j) { u32x2 w; w.x = pk2(v[r][j][0], v[r][j][1]); w.y = pk2(v[r][j][2], v[r][j][3]); ((u32x2*)(X + (size_t)row * DM))[F.lane + 64 * j] = w; }
.LBB0_510:
	s_or_b64 exec, exec, s[16:17]
	v_cvt_pk_bf16_f32 v14, v14, v15
	v_cvt_pk_bf16_f32 v15, v12, v13
	v_cvt_pk_bf16_f32 v12, v18, v19
	v_cvt_pk_bf16_f32 v13, v16, v17
	global_store_dwordx2 v[6:7], v[12:13], off offset:512
	v_cvt_pk_bf16_f32 v12, v22, v23
	v_cvt_pk_bf16_f32 v13, v20, v21
	global_store_dwordx2 v[6:7], v[12:13], off offset:1024
	v_cvt_pk_bf16_f32 v12, v26, v27
	v_cvt_pk_bf16_f32 v13, v24, v25
	s_andn2_b64 vcc, exec, s[14:15]
	global_store_dwordx2 v[6:7], v[14:15], off
	global_store_dwordx2 v[6:7], v[12:13], off offset:1536
	s_cbranch_vccnz .LBB0_514
	s_and_saveexec_b64 s[14:15], s[2:3]
	s_cbranch_execz .LBB0_513
	s_waitcnt lgkmcnt(0)
	v_add_f32_e32 v12, v62, v63
	v_fmamk_f32 v12, v12, 0x3a800000, v1
	v_mul_f32_e32 v13, 0x4f800000, v12
	v_cmp_gt_f32_e32 vcc, s67, v12
	s_nop 1
	v_cndmask_b32_e32 v12, v12, v13, vcc
	v_sqrt_f32_e32 v13, v12
	s_nop 0
	v_add_u32_e32 v14, -1, v13
	v_fma_f32 v16, -v14, v13, v12
	v_add_u32_e32 v15, 1, v13
	v_cmp_ge_f32_e64 s[4:5], 0, v16
	s_nop 1
	v_cndmask_b32_e64 v14, v13, v14, s[4:5]
	v_fma_f32 v13, -v15, v13, v12
	v_cmp_lt_f32_e64 s[4:5], 0, v13
	s_nop 1
	v_cndmask_b32_e64 v13, v14, v15, s[4:5]
	v_mul_f32_e32 v14, 0x37800000, v13
	v_cndmask_b32_e32 v13, v13, v14, vcc
	v_cmp_class_f32_e32 vcc, v12, v196
	s_nop 1
	v_cndmask_b32_e32 v12, v13, v12, vcc
	v_div_scale_f32 v13, s[4:5], v12, v12, 1.0
	v_rcp_f32_e32 v14, v13
	s_lshl_b64 s[4:5], s[12:13], 2
	s_add_u32 s4, s19, s4
	s_addc_u32 s5, s20, s5
	v_fma_f32 v15, -v13, v14, 1.0
	v_fmac_f32_e32 v14, v15, v14
	v_div_scale_f32 v15, vcc, 1.0, v12, 1.0
	v_mul_f32_e32 v16, v15, v14
	v_fma_f32 v17, -v13, v16, v15
	v_fmac_f32_e32 v16, v17, v14
	v_fma_f32 v13, -v13, v16, v15
	v_div_fmas_f32 v13, v13, v14, v16
	v_div_fixup_f32 v12, v13, v12, 1.0
	global_store_dword v2, v12, s[4:5]

; #define LAS __attribute__((address_space(3)))
; DI float fast_exp2(float x) { return __builtin_amdgcn_exp2f(x); }
; #define MFMA16(a, b, c) __builtin_amdgcn_mfma_f32_16x16x32_bf16((a), (b), (c), 0, 0, 0)
; DI void at_qk(f32x4 (&s1)[4], f32x4 (&s2)[4], const LAS unsigned char* buf, const bf16x8 q1, const bf16x8 q2, const f32x4 (&ci)[4], int hh, int fr, int fq) {
; #pragma unroll
;     for (int k4 = 0; k4 < 4; ++k4) { const LAS unsigned char* kr = buf + AT_K + (16 * k4 + fr) * 272 + hh * 128 + fq * 16;
;         s1[k4] = MFMA16(ld8l(kr), q1, ci[k4]); s2[k4] = MFMA16(ld8l(kr + 64), q2, ci[k4]); }
; }
; DI void at_exp(f32x4 (&s1)[4], f32x4 (&s2)[4], float& ps1, float& ps2) {
;     f32x4 a1 = (f32x4){0.f, 0.f, 0.f, 0.f}, a2 = a1;
; #pragma unroll
;     for (int k4 = 0; k4 < 4; ++k4) {
; #pragma unroll
;         for (int j = 0; j < 4; ++j) { s1[k4][j] = fast_exp2(s1[k4][j]); s2[k4][j] = fast_exp2(s2[k4][j]); }
;         a1 = a1 + s1[k4]; a2 = a2 + s2[k4]; }
;     ps1 = (a1[0] + a1[1]) + (a1[2] + a1[3]); ps2 = (a2[0] + a2[1]) + (a2[2] + a2[3]);
; }
; template <int VAR>
; DI void attn_tile(AtState& S, const LAS unsigned char* buf, const bf16x8 q1, const bf16x8 q2, int kt, bool diag, int qpos0, int qpos_l, float slope2, float adv, float decay, int hh, int fr, int fq) {
;     ...
;         asm volatile("; attention: fast tile" ::: "memory");
;         at_qk(s1, s2, buf, q1, q2, S.cinit, hh, fr, fq);
;         S.ref += adv;
;         at_exp(s1, s2, ps1, ps2);
;         if (__any(!(ps1 + ps2 < 0x1p60f))) {
;             asm volatile("; attention: bump" ::: "memory");
;             at_qk(s1, s2, buf, q1, q2, S.cinit, hh, fr, fq);
;             float lm = -1e30f;
; #pragma unroll
;             for (int k4 = 0; k4 < 4; ++k4)
; #pragma unroll
;                 for (int j = 0; j < 4; ++j) lm = fmaxf(lm, fmaxf(s1[k4][j], s2[k4][j]));
;             lm = fmaxf(lm, __shfl_xor(lm, 16)); lm = fmaxf(lm, __shfl_xor(lm, 32));
.LBB0_1376:
	s_add_i32 s27, s26, -1
	s_min_i32 s14, s27, s25
	s_ashr_i32 s15, s14, 31
	s_add_i32 s28, s22, s26
	s_lshl_b64 s[14:15], s[14:15], 18
	s_add_u32 s14, s0, s14
	s_addc_u32 s15, s1, s15
	global_load_dwordx4 v[28:31], v144, s[14:15] offset:1024
	global_load_dwordx4 v[32:35], v144, s[14:15] offset:1536
	global_load_dwordx4 v[36:39], v146, s[14:15] offset:1024
	global_load_dwordx4 v[40:43], v146, s[14:15] offset:1536
	s_cmpk_eq_i32 s28, 0x42
	s_cselect_b64 s[16:17], -1, 0
	s_cmp_eq_u32 s26, 3
	s_cselect_b64 s[14:15], -1, 0
	s_or_b64 s[18:19], s[14:15], s[16:17]
	s_andn2_b64 vcc, exec, s[18:19]
	s_mov_b64 s[18:19], -1
	s_cbranch_vccz .LBB0_1381
	ds_read_b128 v[76:79], v213
	ds_read_b128 v[80:83], v213 offset:64
	ds_read_b128 v[96:99], v213 offset:4352
	ds_read_b128 v[104:107], v213 offset:4416
	ds_read_b128 v[108:111], v213 offset:8704
	ds_read_b128 v[112:115], v213 offset:8768
	ds_read_b128 v[116:119], v213 offset:13056
	ds_read_b128 v[120:123], v213 offset:13120
	s_waitcnt lgkmcnt(7)
	v_mfma_f32_16x16x32_bf16 v[76:79], v[76:79], v[4:7], v[44:47]
	v_add_f32_e32 v215, v205, v214
	s_waitcnt lgkmcnt(6)
	v_mfma_f32_16x16x32_bf16 v[80:83], v[80:83], v[8:11], v[44:47]
	s_waitcnt lgkmcnt(5)
	v_mfma_f32_16x16x32_bf16 v[96:99], v[96:99], v[4:7], v[48:51]
	s_nop 2
	v_exp_f32_e32 v164, v76
	v_exp_f32_e32 v165, v77
	v_exp_f32_e32 v168, v78
	s_waitcnt lgkmcnt(4)
	v_mfma_f32_16x16x32_bf16 v[104:107], v[104:107], v[8:11], v[48:51]
	v_exp_f32_e32 v169, v79
	v_exp_f32_e32 v162, v80
	v_exp_f32_e32 v163, v81
	s_waitcnt lgkmcnt(3)
	v_mfma_f32_16x16x32_bf16 v[108:111], v[108:111], v[4:7], v[52:55]
	v_exp_f32_e32 v166, v82
	v_exp_f32_e32 v167, v83
	v_exp_f32_e32 v172, v96
	s_waitcnt lgkmcnt(2)
	v_mfma_f32_16x16x32_bf16 v[76:79], v[112:115], v[8:11], v[52:55]
	v_exp_f32_e32 v170, v104
	v_exp_f32_e32 v173, v97
	v_exp_f32_e32 v176, v98
	s_waitcnt lgkmcnt(1)
	v_mfma_f32_16x16x32_bf16 v[80:83], v[116:119], v[4:7], v[56:59]
	v_exp_f32_e32 v177, v99
	v_exp_f32_e32 v174, v106
	v_exp_f32_e32 v175, v107
	s_waitcnt lgkmcnt(0)
	v_mfma_f32_16x16x32_bf16 v[112:115], v[120:123], v[8:11], v[56:59]
	v_exp_f32_e32 v171, v105
	v_exp_f32_e32 v180, v108
	v_exp_f32_e32 v178, v76
	v_exp_f32_e32 v181, v109
	v_exp_f32_e32 v179, v77
	v_exp_f32_e32 v184, v110
	v_exp_f32_e32 v185, v111
	v_exp_f32_e32 v182, v78
	v_exp_f32_e32 v183, v79
	v_exp_f32_e32 v188, v80
	v_exp_f32_e32 v186, v112
	v_exp_f32_e32 v189, v81
	v_exp_f32_e32 v192, v82
	v_exp_f32_e32 v193, v83
	v_exp_f32_e32 v190, v114
	v_exp_f32_e32 v191, v115
	v_exp_f32_e32 v187, v113
	v_pk_add_f32 v[96:97], v[168:169], v[176:177]
	v_pk_add_f32 v[98:99], v[164:165], v[172:173]
	v_pk_add_f32 v[104:105], v[166:167], v[174:175]
	v_pk_add_f32 v[106:107], v[162:163], v[170:171]
	v_pk_add_f32 v[76:77], v[98:99], v[180:181]
	v_pk_add_f32 v[78:79], v[96:97], v[184:185]
	v_pk_add_f32 v[96:97], v[106:107], v[178:179]
	v_pk_add_f32 v[98:99], v[104:105], v[182:183]
	v_pk_add_f32 v[78:79], v[78:79], v[192:193]
	v_pk_add_f32 v[76:77], v[76:77], v[188:189]
	v_pk_add_f32 v[80:81], v[98:99], v[190:191]
	v_pk_add_f32 v[82:83], v[96:97], v[186:187]
	v_mov_b32_e32 v97, v76
	v_mov_b32_e32 v96, v82
	v_mov_b32_e32 v76, v83
	v_mov_b32_e32 v82, v80
	v_mov_b32_e32 v83, v78
	v_mov_b32_e32 v78, v81
	v_pk_add_f32 v[76:77], v[96:97], v[76:77]
	v_pk_add_f32 v[78:79], v[82:83], v[78:79]
	s_nop 0
	v_pk_add_f32 v[194:195], v[76:77], v[78:79]
	s_nop 0
	v_add_f32_e32 v3, v195, v194
	v_cmp_ngt_f32_e32 vcc, s65, v3
	s_cbranch_vccz .LBB0_1394
	ds_read_b128 v[76:79], v213
	ds_read_b128 v[80:83], v213 offset:64
	ds_read_b128 v[96:99], v213 offset:4352
	ds_read_b128 v[104:107], v213 offset:4416
	ds_read_b128 v[108:111], v213 offset:8704
	ds_read_b128 v[112:115], v213 offset:8768
	ds_read_b128 v[116:119], v213 offset:13056
	ds_read_b128 v[120:123], v213 offset:13120
	s_waitcnt lgkmcnt(7)
	v_mfma_f32_16x16x32_bf16 v[76:79], v[76:79], v[4:7], v[44:47]
	s_waitcnt lgkmcnt(6)
	v_mfma_f32_16x16x32_bf16 v[80:83], v[80:83], v[8:11], v[44:47]
	s_waitcnt lgkmcnt(5)
	v_mfma_f32_16x16x32_bf16 v[96:99], v[96:99], v[4:7], v[48:51]
	s_waitcnt lgkmcnt(4)
	v_mfma_f32_16x16x32_bf16 v[104:107], v[104:107], v[8:11], v[48:51]
	s_waitcnt lgkmcnt(3)
	v_mfma_f32_16x16x32_bf16 v[108:111], v[108:111], v[4:7], v[52:55]
	s_waitcnt lgkmcnt(2)
	v_mfma_f32_16x16x32_bf16 v[112:115], v[112:115], v[8:11], v[52:55]
	s_waitcnt lgkmcnt(1)
	v_mfma_f32_16x16x32_bf16 v[116:119], v[116:119], v[4:7], v[56:59]
	s_waitcnt lgkmcnt(0)
	v_mfma_f32_16x16x32_bf16 v[120:123], v[120:123], v[8:11], v[56:59]
	v_max3_f32 v3, v76, v80, s60
	v_max3_f32 v3, v3, v77, v81
	v_max3_f32 v3, v3, v78, v82
	v_max3_f32 v3, v3, v79, v83
	v_max3_f32 v3, v3, v96, v104
	v_max3_f32 v3, v3, v97, v105
	v_max3_f32 v3, v3, v98, v106
	v_max3_f32 v3, v3, v99, v107
	v_max3_f32 v3, v3, v108, v112
	v_max3_f32 v3, v3, v109, v113
	v_max3_f32 v3, v3, v110, v114
	v_max3_f32 v3, v3, v111, v115
	v_max3_f32 v3, v3, v116, v120
	v_max3_f32 v3, v3, v117, v121
	v_max3_f32 v3, v3, v118, v122
	v_max3_f32 v3, v3, v119, v123
	v_and_b32_e32 v125, 64, v198
	v_mov_b32_e32 v124, v3
	v_mov_b32_e32 v255, v3
	s_nop 1
	v_permlane16_swap_b32_e32 v124, v255
	s_waitcnt lgkmcnt(0)
	v_max_f32_e32 v3, v124, v255
	v_mov_b32_e32 v124, v3
	v_mov_b32_e32 v255, v3
	s_nop 1
	v_permlane32_swap_b32_e32 v124, v255
	s_waitcnt lgkmcnt(0)
; #define LAS __attribute__((address_space(3)))
; DI float fast_exp2(float x) { return __builtin_amdgcn_exp2f(x); }
; DI u32x2 tr4(const LAS unsigned char* p) { return __builtin_bit_cast(u32x2, __builtin_amdgcn_ds_read_tr16_b64_v4i16((LAS v4i16_t*)p)); }
; DI bf16x8 packp(f32x4 a, f32x4 b) { return __builtin_bit_cast(bf16x8, pack8(a, b)); }
; DI void at_exp(f32x4 (&s1)[4], f32x4 (&s2)[4], float& ps1, float& ps2) {
;     f32x4 a1 = (f32x4){0.f, 0.f, 0.f, 0.f}, a2 = a1;
; #pragma unroll
;     for (int k4 = 0; k4 < 4; ++k4) {
; #pragma unroll
;         for (int j = 0; j < 4; ++j) { s1[k4][j] = fast_exp2(s1[k4][j]); s2[k4][j] = fast_exp2(s2[k4][j]); }
;         a1 = a1 + s1[k4]; a2 = a2 + s2[k4]; }
;     ps1 = (a1[0] + a1[1]) + (a1[2] + a1[3]); ps2 = (a2[0] + a2[1]) + (a2[2] + a2[3]);
; }
; DI void at_pv(AtState& S, const f32x4 (&s1)[4], const f32x4 (&s2)[4], float alpha, float ps1, float ps2, const LAS unsigned char* buf, int hh, int fq, int tq, int tp) {
;     S.l1 = S.l1 * alpha + ps1; S.l2 = S.l2 * alpha + ps2;
; #pragma unroll
;     for (int dt = 0; dt < 4; ++dt) { S.O1[dt] = S.O1[dt] * alpha; S.O2[dt] = S.O2[dt] * alpha; }
;     bf16x8 p1[2], p2[2];
; #pragma unroll
;     for (int s = 0; s < 2; ++s) { p1[s] = packp(s1[2 * s], s1[2 * s + 1]); p2[s] = packp(s2[2 * s], s2[2 * s + 1]); }
; #pragma unroll
;     for (int dh = 0; dh < 2; ++dh) {
;         bf16x8 vt[2][2];
; #pragma unroll
;         for (int d2 = 0; d2 < 2; ++d2)
; #pragma unroll
;             for (int s = 0; s < 2; ++s) { const int dt = 2 * dh + d2; const LAS unsigned char* vr = buf + AT_V + (32 * s + 4 * fq + tq) * 288 + (hh * 64 + 16 * dt + 4 * tp) * 2; vt[d2][s] = cat44(tr4(vr), tr4(vr + 16 * 288)); }
; template <int VAR>
; DI void attn_tile(AtState& S, const LAS unsigned char* buf, const bf16x8 q1, const bf16x8 q2, int kt, bool diag, int qpos0, int qpos_l, float slope2, float adv, float decay, int hh, int fr, int fq) {
;     ...
;             const float bump = fmaxf(lm, 0.f);
;             const float alpha = decay * fast_exp2(-bump); S.ref += bump;
; #pragma unroll
;             for (int k4 = 0; k4 < 4; ++k4) { s1[k4] = s1[k4] - bump; s2[k4] = s2[k4] - bump; S.cinit[k4] = S.cinit[k4] - bump; }
;             at_exp(s1, s2, ps1, ps2);
;             at_pv(S, s1, s2, alpha, ps1, ps2, buf, hh, fq, tq, tp);
	v_max3_f32 v124, v255, v124, 0
	v_sub_f32_e32 v126, v79, v124
	v_sub_f32_e32 v127, v78, v124
	v_sub_f32_e32 v128, v77, v124
	v_sub_f32_e32 v129, v76, v124
	v_sub_f32_e32 v130, v83, v124
	v_sub_f32_e32 v131, v82, v124
	v_sub_f32_e32 v132, v81, v124
	v_sub_f32_e32 v133, v80, v124
	v_sub_f32_e32 v134, v99, v124
	v_sub_f32_e32 v135, v98, v124
	v_sub_f32_e32 v137, v97, v124
	v_sub_f32_e32 v138, v96, v124
	v_sub_f32_e32 v139, v107, v124
	v_sub_f32_e32 v151, v106, v124
	v_sub_f32_e32 v158, v105, v124
	v_sub_f32_e32 v159, v104, v124
	v_exp_f32_e32 v216, v129
	v_exp_f32_e32 v220, v133
	v_exp_f32_e32 v217, v128
	v_exp_f32_e32 v221, v132
	v_exp_f32_e32 v218, v127
	v_exp_f32_e32 v222, v131
	v_exp_f32_e32 v219, v126
	v_exp_f32_e32 v223, v130
	v_sub_f32_e32 v237, v111, v124
	v_sub_f32_e32 v236, v110, v124
	v_sub_f32_e32 v233, v109, v124
	v_sub_f32_e32 v232, v108, v124
	v_sub_f32_e32 v239, v115, v124
	v_sub_f32_e32 v238, v114, v124
	v_sub_f32_e32 v235, v113, v124
	v_sub_f32_e32 v234, v112, v124
	v_exp_f32_e32 v224, v138
	v_exp_f32_e32 v226, v159
	v_exp_f32_e32 v225, v137
	v_exp_f32_e32 v227, v158
	v_exp_f32_e32 v228, v135
	v_exp_f32_e32 v230, v151
	v_exp_f32_e32 v229, v134
	v_exp_f32_e32 v231, v139
	v_sub_f32_e32 v119, v119, v124
	v_sub_f32_e32 v118, v118, v124
	v_sub_f32_e32 v117, v117, v124
	v_sub_f32_e32 v116, v116, v124
	v_sub_f32_e32 v123, v123, v124
	v_sub_f32_e32 v122, v122, v124
	v_sub_f32_e32 v121, v121, v124
	v_sub_f32_e32 v120, v120, v124
	v_exp_f32_e32 v232, v232
	v_exp_f32_e32 v234, v234
	v_exp_f32_e32 v233, v233
	v_exp_f32_e32 v235, v235
	v_exp_f32_e32 v236, v236
	v_exp_f32_e32 v238, v238
	v_exp_f32_e32 v237, v237
	v_exp_f32_e32 v239, v239
	v_exp_f32_e32 v240, v116
	v_exp_f32_e32 v242, v120
	v_exp_f32_e32 v241, v117
	v_exp_f32_e32 v243, v121
	v_exp_f32_e32 v244, v118
	v_exp_f32_e32 v246, v122
	v_exp_f32_e32 v245, v119
	v_exp_f32_e32 v247, v123
	v_pk_add_f32 v[110:111], v[228:229], v[218:219]
	v_pk_add_f32 v[108:109], v[224:225], v[216:217]
	v_pk_add_f32 v[114:115], v[230:231], v[222:223]
	v_pk_add_f32 v[112:113], v[226:227], v[220:221]
	v_pk_add_f32 v[108:109], v[232:233], v[108:109]
	v_pk_add_f32 v[110:111], v[236:237], v[110:111]
	v_pk_add_f32 v[112:113], v[234:235], v[112:113]
	v_pk_add_f32 v[114:115], v[238:239], v[114:115]
	v_pk_add_f32 v[110:111], v[244:245], v[110:111]
	v_pk_add_f32 v[108:109], v[240:241], v[108:109]
	v_pk_add_f32 v[114:115], v[246:247], v[114:115]
	v_pk_add_f32 v[112:113], v[242:243], v[112:113]
	v_cvt_pk_bf16_f32 v216, v216, v217
	v_cvt_pk_bf16_f32 v217, v218, v219
	v_cvt_pk_bf16_f32 v218, v224, v225
	v_cvt_pk_bf16_f32 v219, v228, v229
	v_cvt_pk_bf16_f32 v220, v220, v221
	v_cvt_pk_bf16_f32 v221, v222, v223
	v_cvt_pk_bf16_f32 v222, v226, v227
	v_cvt_pk_bf16_f32 v223, v230, v231
	v_cvt_pk_bf16_f32 v224, v232, v233
	v_cvt_pk_bf16_f32 v225, v236, v237
	v_cvt_pk_bf16_f32 v226, v240, v241
	v_cvt_pk_bf16_f32 v227, v244, v245
	v_cvt_pk_bf16_f32 v228, v234, v235
	v_cvt_pk_bf16_f32 v229, v238, v239
	v_cvt_pk_bf16_f32 v230, v242, v243
	v_cvt_pk_bf16_f32 v231, v246, v247
	ds_read_b64_tr_b16 v[232:233], v208 offset:17408
	ds_read_b64_tr_b16 v[236:237], v208 offset:17440
	ds_read_b64_tr_b16 v[234:235], v208 offset:22016
	ds_read_b64_tr_b16 v[240:241], v208 offset:26624
	ds_read_b64_tr_b16 v[242:243], v208 offset:31232
	ds_read_b64_tr_b16 v[238:239], v208 offset:22048
	ds_read_b64_tr_b16 v[244:245], v208 offset:26656
	ds_read_b64_tr_b16 v[246:247], v208 offset:31264
	v_exp_f32_e64 v125, -v124
	v_mov_b32_e32 v116, v112
	v_mov_b32_e32 v117, v108
	v_mov_b32_e32 v108, v113
	v_mov_b32_e32 v112, v114
	v_mov_b32_e32 v113, v110
	v_mov_b32_e32 v110, v115
	v_pk_add_f32 v[108:109], v[116:117], v[108:109]
	v_pk_add_f32 v[110:111], v[112:113], v[110:111]
	v_mul_f32_e32 v136, v150, v125
	v_pk_add_f32 v[108:109], v[108:109], v[110:111]
	v_add_f32_e32 v3, v215, v124
	v_sub_f32_e32 v79, v47, v124
	v_sub_f32_e32 v78, v46, v124
	v_sub_f32_e32 v77, v45, v124
	v_sub_f32_e32 v76, v44, v124
	v_sub_f32_e32 v99, v51, v124
	v_sub_f32_e32 v98, v50, v124
	v_sub_f32_e32 v97, v49, v124
	v_sub_f32_e32 v96, v48, v124
	v_sub_f32_e32 v107, v55, v124
	v_sub_f32_e32 v106, v54, v124
	v_sub_f32_e32 v105, v53, v124
	v_sub_f32_e32 v104, v52, v124
	v_sub_f32_e32 v83, v59, v124
	v_sub_f32_e32 v82, v58, v124
	v_sub_f32_e32 v81, v57, v124
	v_sub_f32_e32 v80, v56, v124
	v_pk_fma_f32 v[158:159], v[156:157], v[136:137], v[108:109] op_sel_hi:[1,0,1]
	v_pk_mul_f32 v[110:111], v[66:67], v[136:137] op_sel_hi:[1,0]
	v_pk_mul_f32 v[108:109], v[64:65], v[136:137] op_sel_hi:[1,0]
	v_pk_mul_f32 v[114:115], v[74:75], v[136:137] op_sel_hi:[1,0]
	v_pk_mul_f32 v[112:113], v[72:73], v[136:137] op_sel_hi:[1,0]
	v_pk_mul_f32 v[118:119], v[62:63], v[136:137] op_sel_hi:[1,0]
	v_pk_mul_f32 v[116:117], v[60:61], v[136:137] op_sel_hi:[1,0]
	v_pk_mul_f32 v[122:123], v[70:71], v[136:137] op_sel_hi:[1,0]
	v_pk_mul_f32 v[120:121], v[68:69], v[136:137] op_sel_hi:[1,0]
	v_pk_mul_f32 v[126:127], v[90:91], v[136:137] op_sel_hi:[1,0]
	v_pk_mul_f32 v[124:125], v[88:89], v[136:137] op_sel_hi:[1,0]
	v_pk_mul_f32 v[130:131], v[102:103], v[136:137] op_sel_hi:[1,0]
	v_pk_mul_f32 v[128:129], v[100:101], v[136:137] op_sel_hi:[1,0]
	v_pk_mul_f32 v[134:135], v[86:87], v[136:137] op_sel_hi:[1,0]
	v_pk_mul_f32 v[132:133], v[84:85], v[136:137] op_sel_hi:[1,0]
	v_pk_mul_f32 v[138:139], v[94:95], v[136:137] op_sel_hi:[1,0]
	v_pk_mul_f32 v[136:137], v[92:93], v[136:137] op_sel_hi:[1,0]
	s_setprio 1
	s_waitcnt lgkmcnt(5)
; #define LAS __attribute__((address_space(3)))
; #define MFMA16(a, b, c) __builtin_amdgcn_mfma_f32_16x16x32_bf16((a), (b), (c), 0, 0, 0)
; DI u32x2 tr4(const LAS unsigned char* p) { return __builtin_bit_cast(u32x2, __builtin_amdgcn_ds_read_tr16_b64_v4i16((LAS v4i16_t*)p)); }
; DI void at_pv(AtState& S, const f32x4 (&s1)[4], const f32x4 (&s2)[4], float alpha, float ps1, float ps2, const LAS unsigned char* buf, int hh, int fq, int tq, int tp) {
;     ...
;     for (int dh = 0; dh < 2; ++dh) {
;         bf16x8 vt[2][2];
; #pragma unroll
;         for (int d2 = 0; d2 < 2; ++d2)
; #pragma unroll
;             for (int s = 0; s < 2; ++s) { const int dt = 2 * dh + d2; const LAS unsigned char* vr = buf + AT_V + (32 * s + 4 * fq + tq) * 288 + (hh * 64 + 16 * dt + 4 * tp) * 2; vt[d2][s] = cat44(tr4(vr), tr4(vr + 16 * 288)); }
;         __builtin_amdgcn_s_setprio(1);
; #pragma unroll
;         for (int s = 0; s < 2; ++s)
; #pragma unroll
;             for (int d2 = 0; d2 < 2; ++d2) { const int dt = 2 * dh + d2; S.O1[dt] = MFMA16(vt[d2][s], p1[s], S.O1[dt]); S.O2[dt] = MFMA16(vt[d2][s], p2[s], S.O2[dt]); }
;         __builtin_amdgcn_s_setprio(0);
;         __builtin_amdgcn_sched_barrier(0);
;     }
	v_mfma_f32_16x16x32_bf16 v[108:111], v[232:235], v[216:219], v[108:111]
	v_mfma_f32_16x16x32_bf16 v[112:115], v[232:235], v[220:223], v[112:115]
	s_waitcnt lgkmcnt(2)
	v_mfma_f32_16x16x32_bf16 v[232:235], v[236:239], v[216:219], v[116:119]
	v_mfma_f32_16x16x32_bf16 v[236:239], v[236:239], v[220:223], v[120:123]
	v_mfma_f32_16x16x32_bf16 v[120:123], v[240:243], v[224:227], v[108:111]
	v_mfma_f32_16x16x32_bf16 v[116:119], v[240:243], v[228:231], v[112:115]
	s_waitcnt lgkmcnt(0)
	v_mfma_f32_16x16x32_bf16 v[112:115], v[244:247], v[224:227], v[232:235]
	v_mfma_f32_16x16x32_bf16 v[108:111], v[244:247], v[228:231], v[236:239]
	s_setprio 0
	s_nop 0
	ds_read_b64_tr_b16 v[232:233], v208 offset:17472
	ds_read_b64_tr_b16 v[236:237], v208 offset:17504
	ds_read_b64_tr_b16 v[234:235], v208 offset:22080
	ds_read_b64_tr_b16 v[238:239], v208 offset:22112
	ds_read_b64_tr_b16 v[240:241], v208 offset:26688
	ds_read_b64_tr_b16 v[242:243], v208 offset:31296
	ds_read_b64_tr_b16 v[246:247], v208 offset:31328
	ds_read_b64_tr_b16 v[244:245], v208 offset:26720
	s_setprio 1
	s_waitcnt lgkmcnt(5)
	v_mfma_f32_16x16x32_bf16 v[124:127], v[232:235], v[216:219], v[124:127]
	v_mfma_f32_16x16x32_bf16 v[128:131], v[232:235], v[220:223], v[128:131]
	s_waitcnt lgkmcnt(4)
	v_mfma_f32_16x16x32_bf16 v[216:219], v[236:239], v[216:219], v[132:135]
	v_mfma_f32_16x16x32_bf16 v[220:223], v[236:239], v[220:223], v[136:139]
	s_waitcnt lgkmcnt(2)
	v_mfma_f32_16x16x32_bf16 v[136:139], v[240:243], v[224:227], v[124:127]
	v_mfma_f32_16x16x32_bf16 v[132:135], v[240:243], v[228:231], v[128:131]
	s_waitcnt lgkmcnt(0)
	v_mfma_f32_16x16x32_bf16 v[128:131], v[244:247], v[224:227], v[216:219]
	v_mfma_f32_16x16x32_bf16 v[124:127], v[244:247], v[228:231], v[220:223]
	s_setprio 0
	s_cbranch_execnz .LBB0_1380

; #define LAS __attribute__((address_space(3)))
; DI float fast_exp2(float x) { return __builtin_amdgcn_exp2f(x); }
; DI void at_exp(f32x4 (&s1)[4], f32x4 (&s2)[4], float& ps1, float& ps2) {
;     f32x4 a1 = (f32x4){0.f, 0.f, 0.f, 0.f}, a2 = a1;
; #pragma unroll
;     for (int k4 = 0; k4 < 4; ++k4) {
; #pragma unroll
;         for (int j = 0; j < 4; ++j) { s1[k4][j] = fast_exp2(s1[k4][j]); s2[k4][j] = fast_exp2(s2[k4][j]); }
;         a1 = a1 + s1[k4]; a2 = a2 + s2[k4]; }
;     ps1 = (a1[0] + a1[1]) + (a1[2] + a1[3]); ps2 = (a2[0] + a2[1]) + (a2[2] + a2[3]);
; }
; DI void at_pv(AtState& S, const f32x4 (&s1)[4], const f32x4 (&s2)[4], float alpha, float ps1, float ps2, const LAS unsigned char* buf, int hh, int fq, int tq, int tp) {
;     S.l1 = S.l1 * alpha + ps1; S.l2 = S.l2 * alpha + ps2;
; #pragma unroll
;     for (int dt = 0; dt < 4; ++dt) { S.O1[dt] = S.O1[dt] * alpha; S.O2[dt] = S.O2[dt] * alpha; }
;     bf16x8 p1[2], p2[2];
; #pragma unroll
;     for (int s = 0; s < 2; ++s) { p1[s] = packp(s1[2 * s], s1[2 * s + 1]); p2[s] = packp(s2[2 * s], s2[2 * s + 1]); }
; #pragma unroll
;     for (int dh = 0; dh < 2; ++dh) {
;         bf16x8 vt[2][2];
; #pragma unroll
;         for (int d2 = 0; d2 < 2; ++d2)
; #pragma unroll
;             for (int s = 0; s < 2; ++s) { const int dt = 2 * dh + d2; const LAS unsigned char* vr = buf + AT_V + (32 * s + 4 * fq + tq) * 288 + (hh * 64 + 16 * dt + 4 * tp) * 2; vt[d2][s] = cat44(tr4(vr), tr4(vr + 16 * 288)); }
;         __builtin_amdgcn_s_setprio(1);
; #pragma unroll
;         for (int s = 0; s < 2; ++s)
; #pragma unroll
; template <int VAR>
; DI void attn_tile(AtState& S, const LAS unsigned char* buf, const bf16x8 q1, const bf16x8 q2, int kt, bool diag, int qpos0, int qpos_l, float slope2, float adv, float decay, int hh, int fr, int fq) {
;     ...
;         const float nref = fmaxf(S.ref, mx);
;         const float alpha = fast_exp2(S.ref - nref); S.ref = nref;
; #pragma unroll
;         for (int k4 = 0; k4 < 4; ++k4) { s1[k4] = s1[k4] - nref; s2[k4] = s2[k4] - nref; }
;         if (kt == 0) { const float c0 = -slope2 * (float)qpos0 - S.ref;
; #pragma unroll
;             for (int k4 = 0; k4 < 4; ++k4)
; #pragma unroll
;                 for (int j = 0; j < 4; ++j) S.cinit[k4][j] = slope2 * (float)(16 * k4 + j - ql) + c0; }
;         at_exp(s1, s2, ps1, ps2);
;         at_pv(S, s1, s2, alpha, ps1, ps2, buf, hh, fq, tq, tp);
.LBB0_1384:
	v_sub_f32_e32 v77, v125, v3
	v_sub_f32_e32 v83, v123, v3
	v_sub_f32_e32 v97, v121, v3
	v_sub_f32_e32 v98, v118, v3
	v_sub_f32_e32 v109, v124, v3
	v_sub_f32_e32 v108, v122, v3
	v_sub_f32_e32 v110, v120, v3
	v_sub_f32_e32 v99, v119, v3
	v_sub_f32_e32 v113, v133, v3
	v_sub_f32_e32 v114, v131, v3
	v_sub_f32_e32 v111, v129, v3
	v_sub_f32_e32 v112, v127, v3
	v_sub_f32_e32 v117, v132, v3
	v_sub_f32_e32 v116, v130, v3
	v_sub_f32_e32 v118, v128, v3
	v_sub_f32_e32 v115, v126, v3
	v_sub_f32_e32 v124, v107, v3
	v_sub_f32_e32 v125, v106, v3
	v_sub_f32_e32 v121, v105, v3
	v_sub_f32_e32 v126, v104, v3
	v_exp_f32_e32 v98, v98
	v_exp_f32_e32 v104, v99
	v_exp_f32_e32 v99, v97
	v_exp_f32_e32 v105, v110
	v_exp_f32_e32 v106, v83
	v_exp_f32_e32 v107, v77
	v_exp_f32_e32 v108, v108
	v_exp_f32_e32 v109, v109
	v_sub_f32_e32 v123, v137, v3
	v_sub_f32_e32 v122, v136, v3
	v_sub_f32_e32 v119, v135, v3
	v_sub_f32_e32 v120, v134, v3
	v_exp_f32_e32 v110, v112
	v_exp_f32_e32 v112, v115
	v_exp_f32_e32 v111, v111
	v_exp_f32_e32 v114, v114
	v_exp_f32_e32 v115, v113
	v_exp_f32_e32 v116, v116
	v_exp_f32_e32 v117, v117
	v_exp_f32_e32 v113, v118
	v_sub_f32_e32 v127, v82, v3
	v_sub_f32_e32 v131, v151, v3
	v_sub_f32_e32 v132, v139, v3
	v_sub_f32_e32 v130, v138, v3
	v_sub_f32_e32 v133, v79, v3
	v_sub_f32_e32 v134, v78, v3
	v_sub_f32_e32 v135, v81, v3
	v_sub_f32_e32 v136, v80, v3
	v_exp_f32_e32 v118, v120
	v_exp_f32_e32 v120, v126
	v_exp_f32_e32 v119, v119
	v_exp_f32_e32 v121, v121
	v_exp_f32_e32 v122, v122
	v_exp_f32_e32 v123, v123
	v_exp_f32_e32 v128, v125
	v_exp_f32_e32 v129, v124
	v_sub_f32_e32 v76, v214, v3
	v_exp_f32_e32 v124, v130
	v_exp_f32_e32 v130, v136
	v_exp_f32_e32 v125, v132
	v_exp_f32_e32 v126, v131
	v_exp_f32_e32 v127, v127
	v_exp_f32_e32 v132, v134
	v_exp_f32_e32 v133, v133
	v_exp_f32_e32 v131, v135
	v_exp_f32_e32 v96, v76
	v_pk_add_f32 v[78:79], v[114:115], v[106:107]
	v_pk_add_f32 v[76:77], v[110:111], v[98:99]
	v_pk_add_f32 v[82:83], v[116:117], v[108:109]
	v_pk_add_f32 v[80:81], v[112:113], v[104:105]
	v_pk_add_f32 v[76:77], v[118:119], v[76:77]
	v_pk_add_f32 v[78:79], v[122:123], v[78:79]
	v_pk_add_f32 v[80:81], v[120:121], v[80:81]
	v_pk_add_f32 v[82:83], v[128:129], v[82:83]
	v_pk_add_f32 v[78:79], v[126:127], v[78:79]
	v_pk_add_f32 v[76:77], v[124:125], v[76:77]
	v_pk_add_f32 v[82:83], v[132:133], v[82:83]
	v_pk_add_f32 v[80:81], v[130:131], v[80:81]
	v_mov_b32_e32 v135, v76
	v_mov_b32_e32 v134, v80
	v_mov_b32_e32 v76, v81
	v_mov_b32_e32 v80, v82
	v_mov_b32_e32 v81, v78
	v_mov_b32_e32 v78, v83
	v_pk_add_f32 v[76:77], v[134:135], v[76:77]
	v_pk_add_f32 v[78:79], v[80:81], v[78:79]
	v_pk_mul_f32 v[66:67], v[66:67], v[96:97] op_sel_hi:[1,0]
	v_pk_add_f32 v[76:77], v[76:77], v[78:79]
	v_pk_mul_f32 v[64:65], v[64:65], v[96:97] op_sel_hi:[1,0]
	v_pk_fma_f32 v[158:159], v[156:157], v[96:97], v[76:77] op_sel_hi:[1,0,1]
	v_pk_mul_f32 v[74:75], v[74:75], v[96:97] op_sel_hi:[1,0]
	v_pk_mul_f32 v[72:73], v[72:73], v[96:97] op_sel_hi:[1,0]
	v_pk_mul_f32 v[62:63], v[62:63], v[96:97] op_sel_hi:[1,0]
	v_pk_mul_f32 v[60:61], v[60:61], v[96:97] op_sel_hi:[1,0]
	v_pk_mul_f32 v[70:71], v[70:71], v[96:97] op_sel_hi:[1,0]
	v_pk_mul_f32 v[68:69], v[68:69], v[96:97] op_sel_hi:[1,0]
	v_pk_mul_f32 v[78:79], v[90:91], v[96:97] op_sel_hi:[1,0]
	v_pk_mul_f32 v[76:77], v[88:89], v[96:97] op_sel_hi:[1,0]
	v_pk_mul_f32 v[82:83], v[102:103], v[96:97] op_sel_hi:[1,0]
	v_pk_mul_f32 v[80:81], v[100:101], v[96:97] op_sel_hi:[1,0]
	v_pk_mul_f32 v[86:87], v[86:87], v[96:97] op_sel_hi:[1,0]
	v_pk_mul_f32 v[84:85], v[84:85], v[96:97] op_sel_hi:[1,0]
	v_pk_mul_f32 v[90:91], v[94:95], v[96:97] op_sel_hi:[1,0]
	v_pk_mul_f32 v[88:89], v[92:93], v[96:97] op_sel_hi:[1,0]
	v_cvt_pk_bf16_f32 v92, v98, v99
	v_cvt_pk_bf16_f32 v93, v106, v107
	v_cvt_pk_bf16_f32 v94, v110, v111
	v_cvt_pk_bf16_f32 v95, v114, v115
	v_cvt_pk_bf16_f32 v96, v104, v105
	v_cvt_pk_bf16_f32 v97, v108, v109
	v_cvt_pk_bf16_f32 v98, v112, v113
	v_cvt_pk_bf16_f32 v102, v124, v125
	v_cvt_pk_bf16_f32 v103, v126, v127
	ds_read_b64_tr_b16 v[104:105], v208 offset:17408
	ds_read_b64_tr_b16 v[108:109], v208 offset:17440
	ds_read_b64_tr_b16 v[106:107], v208 offset:22016
	ds_read_b64_tr_b16 v[110:111], v208 offset:22048
	ds_read_b64_tr_b16 v[112:113], v208 offset:26624
	ds_read_b64_tr_b16 v[114:115], v208 offset:31232
	ds_read_b64_tr_b16 v[126:127], v208 offset:31264
	ds_read_b64_tr_b16 v[124:125], v208 offset:26656
	v_cvt_pk_bf16_f32 v99, v116, v117
	v_cvt_pk_bf16_f32 v100, v118, v119
	v_cvt_pk_bf16_f32 v101, v122, v123
	v_cvt_pk_bf16_f32 v162, v120, v121
	v_cvt_pk_bf16_f32 v163, v128, v129
	v_cvt_pk_bf16_f32 v164, v130, v131
	v_cvt_pk_bf16_f32 v165, v132, v133
	s_setprio 1
	s_waitcnt lgkmcnt(5)
	v_mfma_f32_16x16x32_bf16 v[64:67], v[104:107], v[92:95], v[64:67]
	v_mfma_f32_16x16x32_bf16 v[72:75], v[104:107], v[96:99], v[72:75]
	s_waitcnt lgkmcnt(4)
	v_mfma_f32_16x16x32_bf16 v[60:63], v[108:111], v[92:95], v[60:63]
	v_mfma_f32_16x16x32_bf16 v[68:71], v[108:111], v[96:99], v[68:71]
	s_waitcnt lgkmcnt(2)
	v_mfma_f32_16x16x32_bf16 v[120:123], v[112:115], v[100:103], v[64:67]
	v_mfma_f32_16x16x32_bf16 v[116:119], v[112:115], v[162:165], v[72:75]
	s_waitcnt lgkmcnt(0)
	v_mfma_f32_16x16x32_bf16 v[112:115], v[124:127], v[100:103], v[60:63]
	v_mfma_f32_16x16x32_bf16 v[108:111], v[124:127], v[162:165], v[68:71]
	s_setprio 0
	s_nop 0
	ds_read_b64_tr_b16 v[60:61], v208 offset:17472
	ds_read_b64_tr_b16 v[64:65], v208 offset:17504
	ds_read_b64_tr_b16 v[62:63], v208 offset:22080
	ds_read_b64_tr_b16 v[66:67], v208 offset:22112
	ds_read_b64_tr_b16 v[68:69], v208 offset:26688
	ds_read_b64_tr_b16 v[70:71], v208 offset:31296
	ds_read_b64_tr_b16 v[74:75], v208 offset:31328
	ds_read_b64_tr_b16 v[72:73], v208 offset:26720
	s_setprio 1
	s_waitcnt lgkmcnt(5)
	v_mfma_f32_16x16x32_bf16 v[76:79], v[60:63], v[92:95], v[76:79]
	v_mfma_f32_16x16x32_bf16 v[60:63], v[60:63], v[96:99], v[80:83]
	s_waitcnt lgkmcnt(4)
	v_mfma_f32_16x16x32_bf16 v[80:83], v[64:67], v[92:95], v[84:87]
	v_mfma_f32_16x16x32_bf16 v[64:67], v[64:67], v[96:99], v[88:91]
	s_waitcnt lgkmcnt(2)
	v_mfma_f32_16x16x32_bf16 v[136:139], v[68:71], v[100:103], v[76:79]
	v_mfma_f32_16x16x32_bf16 v[132:135], v[68:71], v[162:165], v[60:63]
	s_waitcnt lgkmcnt(0)
	v_mfma_f32_16x16x32_bf16 v[128:131], v[72:75], v[100:103], v[80:83]
	v_mfma_f32_16x16x32_bf16 v[124:127], v[72:75], v[162:165], v[64:67]
	s_setprio 0
	s_nop 0
	v_mov_b64_e32 v[82:83], v[58:59]
	v_mov_b64_e32 v[78:79], v[46:47]
	v_mov_b64_e32 v[98:99], v[50:51]
	v_mov_b64_e32 v[106:107], v[54:55]
	v_mov_b64_e32 v[80:81], v[56:57]
	v_mov_b64_e32 v[76:77], v[44:45]
	v_mov_b64_e32 v[96:97], v[48:49]
	v_mov_b64_e32 v[104:105], v[52:53]

; DI void lds_barrier() { asm volatile("s_waitcnt lgkmcnt(0)" ::: "memory"); __builtin_amdgcn_s_barrier(); asm volatile("" ::: "memory"); }
; template <int VAR>
; DI void attn_tile(AtState& S, const LAS unsigned char* buf, const bf16x8 q1, const bf16x8 q2, int kt, bool diag, int qpos0, int qpos_l, float slope2, float adv, float decay, int hh, int fr, int fq) {
;     ...
;         asm volatile("; attention: fast tile" ::: "memory");
;         at_qk(s1, s2, buf, q1, q2, S.cinit, hh, fr, fq);
;         S.ref += adv;
;         at_exp(s1, s2, ps1, ps2);
;         if (__any(!(ps1 + ps2 < 0x1p60f))) {
;             asm volatile("; attention: bump" ::: "memory");
;             at_qk(s1, s2, buf, q1, q2, S.cinit, hh, fr, fq);
;             float lm = -1e30f;
; #pragma unroll
;             for (int k4 = 0; k4 < 4; ++k4)
; #pragma unroll
;                 for (int j = 0; j < 4; ++j) lm = fmaxf(lm, fmaxf(s1[k4][j], s2[k4][j]));
;             lm = fmaxf(lm, __shfl_xor(lm, 16)); lm = fmaxf(lm, __shfl_xor(lm, 32));
; template <int VAR>
; DI void attn_segment(const Args& a, const Frame& F, int l, int qrow0, int qpos0, int hp, int ntile, int nf32, const float* ck, const float* cv, int prow0) {
;     ...
;         for (int kt = 0; kt < ntile; kt += 2) {
;             atb_issue(rb, pb + (size_t)(kt + 2 < nl ? kt + 2 : nl) * TSTR, voff);
;             attn_tile<VAR>(S, F.lds + (kt & 1) * AT_BUF, q1, q2, kt, kt + 1 == ntile, qpos0, qpos_l, slope2, adv, decay, hh, fr, fq);
;             atb_commit(ra, F.lds + ((kt + 1) & 1) * AT_BUF, tid);
;             lds_barrier();
;             if (kt + 1 >= ntile) break;
;             atb_issue(ra, pb + (size_t)(kt + 3 < nl ? kt + 3 : nl) * TSTR, voff);
;             attn_tile<VAR>(S, F.lds + ((kt + 1) & 1) * AT_BUF, q1, q2, kt + 1, kt + 2 == ntile, qpos0, qpos_l, slope2, adv, decay, hh, fr, fq);
;             atb_commit(rb, F.lds + (kt & 1) * AT_BUF, tid);
;             lds_barrier();
;         }
.Lcommit_done_A:
	s_waitcnt lgkmcnt(0)
	s_barrier
	s_add_i32 s14, s26, -2
	s_cmp_ge_i32 s14, s24
	s_mov_b64 s[14:15], -1
	s_cbranch_scc1 .LBB0_1375
	s_min_i32 s14, s26, s25
	s_ashr_i32 s15, s14, 31
	s_lshl_b64 s[14:15], s[14:15], 18
	s_add_u32 s14, s0, s14
	s_addc_u32 s15, s1, s15
	v_lshl_add_u64 v[16:17], s[14:15], 0, v[144:145]
	v_lshl_add_u64 v[24:25], s[14:15], 0, v[146:147]
	global_load_dwordx4 v[12:15], v[16:17], off offset:1024
	s_nop 0
	global_load_dwordx4 v[16:19], v[16:17], off offset:1536
	s_nop 0
	global_load_dwordx4 v[20:23], v[24:25], off offset:1024
	s_nop 0
	global_load_dwordx4 v[24:27], v[24:25], off offset:1536
	s_cmpk_lg_i32 s28, 0x41
	s_mov_b64 s[14:15], -1
	s_cbranch_scc0 .LBB0_1391
	ds_read_b128 v[44:47], v213 offset:35840
	ds_read_b128 v[48:51], v213 offset:35904
	ds_read_b128 v[52:55], v213 offset:40192
	ds_read_b128 v[56:59], v213 offset:40256
	ds_read_b128 v[60:63], v213 offset:44544
	ds_read_b128 v[64:67], v213 offset:44608
	ds_read_b128 v[68:71], v213 offset:48896
	ds_read_b128 v[72:75], v213 offset:48960
	s_waitcnt lgkmcnt(7)
	v_mfma_f32_16x16x32_bf16 v[44:47], v[44:47], v[4:7], v[76:79]
	v_add_f32_e32 v215, v205, v3
	s_waitcnt lgkmcnt(6)
	v_mfma_f32_16x16x32_bf16 v[48:51], v[48:51], v[8:11], v[76:79]
	s_waitcnt lgkmcnt(5)
	v_mfma_f32_16x16x32_bf16 v[52:55], v[52:55], v[4:7], v[96:99]
	s_nop 2
	v_exp_f32_e32 v164, v44
	v_exp_f32_e32 v165, v45
	v_exp_f32_e32 v168, v46
	s_waitcnt lgkmcnt(4)
	v_mfma_f32_16x16x32_bf16 v[56:59], v[56:59], v[8:11], v[96:99]
	v_exp_f32_e32 v169, v47
	v_exp_f32_e32 v162, v48
	v_exp_f32_e32 v163, v49
	s_waitcnt lgkmcnt(3)
	v_mfma_f32_16x16x32_bf16 v[60:63], v[60:63], v[4:7], v[104:107]
	v_exp_f32_e32 v166, v50
	v_exp_f32_e32 v167, v51
	v_exp_f32_e32 v172, v52
	s_waitcnt lgkmcnt(2)
	v_mfma_f32_16x16x32_bf16 v[44:47], v[64:67], v[8:11], v[104:107]
	v_exp_f32_e32 v170, v56
	v_exp_f32_e32 v173, v53
	v_exp_f32_e32 v176, v54
	s_waitcnt lgkmcnt(1)
	v_mfma_f32_16x16x32_bf16 v[48:51], v[68:71], v[4:7], v[80:83]
	v_exp_f32_e32 v177, v55
	v_exp_f32_e32 v174, v58
	v_exp_f32_e32 v175, v59
	s_waitcnt lgkmcnt(0)
	v_mfma_f32_16x16x32_bf16 v[64:67], v[72:75], v[8:11], v[80:83]
	v_exp_f32_e32 v171, v57
	v_exp_f32_e32 v180, v60
	v_exp_f32_e32 v178, v44
	v_exp_f32_e32 v181, v61
	v_exp_f32_e32 v179, v45
	v_exp_f32_e32 v184, v62
	v_exp_f32_e32 v185, v63
	v_exp_f32_e32 v182, v46
	v_exp_f32_e32 v183, v47
	v_exp_f32_e32 v188, v48
	v_exp_f32_e32 v186, v64
	v_exp_f32_e32 v189, v49
	v_exp_f32_e32 v192, v50
	v_exp_f32_e32 v193, v51
	v_exp_f32_e32 v190, v66
	v_exp_f32_e32 v191, v67
	v_exp_f32_e32 v187, v65
	v_pk_add_f32 v[52:53], v[168:169], v[176:177]
	v_pk_add_f32 v[54:55], v[164:165], v[172:173]
	v_pk_add_f32 v[56:57], v[166:167], v[174:175]
	v_pk_add_f32 v[58:59], v[162:163], v[170:171]
	v_pk_add_f32 v[44:45], v[54:55], v[180:181]
	v_pk_add_f32 v[46:47], v[52:53], v[184:185]
	v_pk_add_f32 v[52:53], v[58:59], v[178:179]
	v_pk_add_f32 v[54:55], v[56:57], v[182:183]
	v_pk_add_f32 v[46:47], v[46:47], v[192:193]
	v_pk_add_f32 v[44:45], v[44:45], v[188:189]
	v_pk_add_f32 v[48:49], v[54:55], v[190:191]
	v_pk_add_f32 v[50:51], v[52:53], v[186:187]
	v_mov_b32_e32 v53, v44
	v_mov_b32_e32 v52, v50
	v_mov_b32_e32 v44, v51
	v_mov_b32_e32 v50, v48
	v_mov_b32_e32 v51, v46
	v_mov_b32_e32 v46, v49
	v_pk_add_f32 v[44:45], v[52:53], v[44:45]
	v_pk_add_f32 v[46:47], v[50:51], v[46:47]
	s_nop 0
	v_pk_add_f32 v[194:195], v[44:45], v[46:47]
	s_nop 0
	v_add_f32_e32 v44, v195, v194
	v_cmp_ngt_f32_e32 vcc, s65, v44
	s_cbranch_vccz .LBB0_1395
	ds_read_b128 v[44:47], v213 offset:35840
	ds_read_b128 v[48:51], v213 offset:35904
	ds_read_b128 v[52:55], v213 offset:40192
	ds_read_b128 v[56:59], v213 offset:40256
	ds_read_b128 v[60:63], v213 offset:44544
	ds_read_b128 v[64:67], v213 offset:44608
	ds_read_b128 v[68:71], v213 offset:48896
	ds_read_b128 v[72:75], v213 offset:48960
	s_waitcnt lgkmcnt(7)
	v_mfma_f32_16x16x32_bf16 v[44:47], v[44:47], v[4:7], v[76:79]
	s_waitcnt lgkmcnt(6)
	v_mfma_f32_16x16x32_bf16 v[48:51], v[48:51], v[8:11], v[76:79]
	s_waitcnt lgkmcnt(5)
	v_mfma_f32_16x16x32_bf16 v[52:55], v[52:55], v[4:7], v[96:99]
	s_waitcnt lgkmcnt(4)
	v_mfma_f32_16x16x32_bf16 v[56:59], v[56:59], v[8:11], v[96:99]
	s_waitcnt lgkmcnt(3)
	v_mfma_f32_16x16x32_bf16 v[60:63], v[60:63], v[4:7], v[104:107]
	s_waitcnt lgkmcnt(2)
	v_mfma_f32_16x16x32_bf16 v[64:67], v[64:67], v[8:11], v[104:107]
	s_waitcnt lgkmcnt(1)
	v_mfma_f32_16x16x32_bf16 v[68:71], v[68:71], v[4:7], v[80:83]
	s_waitcnt lgkmcnt(0)
	v_mfma_f32_16x16x32_bf16 v[72:75], v[72:75], v[8:11], v[80:83]
	v_max3_f32 v84, v44, v48, s60
	v_max3_f32 v84, v84, v45, v49
	v_max3_f32 v84, v84, v46, v50
	v_max3_f32 v84, v84, v47, v51
	v_max3_f32 v84, v84, v52, v56
	v_max3_f32 v84, v84, v53, v57
	v_max3_f32 v84, v84, v54, v58
	v_max3_f32 v84, v84, v55, v59
	v_max3_f32 v84, v84, v60, v64
	v_max3_f32 v84, v84, v61, v65
	v_max3_f32 v84, v84, v62, v66
	v_max3_f32 v84, v84, v63, v67
	v_max3_f32 v84, v84, v68, v72
	v_max3_f32 v84, v84, v69, v73
	v_max3_f32 v84, v84, v70, v74
	v_max3_f32 v84, v84, v71, v75
	v_and_b32_e32 v86, 64, v198
	v_mov_b32_e32 v85, v84
	v_mov_b32_e32 v255, v84
	s_nop 1
	v_permlane16_swap_b32_e32 v85, v255
	s_waitcnt lgkmcnt(0)
	v_max_f32_e32 v84, v85, v255
	v_mov_b32_e32 v85, v84
	v_mov_b32_e32 v255, v84
	s_nop 1
	v_permlane32_swap_b32_e32 v85, v255
	s_waitcnt lgkmcnt(0)
; #define LAS __attribute__((address_space(3)))
; DI void at_exp(f32x4 (&s1)[4], f32x4 (&s2)[4], float& ps1, float& ps2) {
;     f32x4 a1 = (f32x4){0.f, 0.f, 0.f, 0.f}, a2 = a1;
; #pragma unroll
;     for (int k4 = 0; k4 < 4; ++k4) {
; #pragma unroll
;         for (int j = 0; j < 4; ++j) { s1[k4][j] = fast_exp2(s1[k4][j]); s2[k4][j] = fast_exp2(s2[k4][j]); }
;         a1 = a1 + s1[k4]; a2 = a2 + s2[k4]; }
;     ps1 = (a1[0] + a1[1]) + (a1[2] + a1[3]); ps2 = (a2[0] + a2[1]) + (a2[2] + a2[3]);
; }
; DI void at_pv(AtState& S, const f32x4 (&s1)[4], const f32x4 (&s2)[4], float alpha, float ps1, float ps2, const LAS unsigned char* buf, int hh, int fq, int tq, int tp) {
;     S.l1 = S.l1 * alpha + ps1; S.l2 = S.l2 * alpha + ps2;
; #pragma unroll
;     for (int dt = 0; dt < 4; ++dt) { S.O1[dt] = S.O1[dt] * alpha; S.O2[dt] = S.O2[dt] * alpha; }
;     bf16x8 p1[2], p2[2];
; #pragma unroll
;     for (int s = 0; s < 2; ++s) { p1[s] = packp(s1[2 * s], s1[2 * s + 1]); p2[s] = packp(s2[2 * s], s2[2 * s + 1]); }
; #pragma unroll
;     for (int dh = 0; dh < 2; ++dh) {
;         bf16x8 vt[2][2];
; #pragma unroll
;         for (int d2 = 0; d2 < 2; ++d2)
; #pragma unroll
;             for (int s = 0; s < 2; ++s) { const int dt = 2 * dh + d2; const LAS unsigned char* vr = buf + AT_V + (32 * s + 4 * fq + tq) * 288 + (hh * 64 + 16 * dt + 4 * tp) * 2; vt[d2][s] = cat44(tr4(vr), tr4(vr + 16 * 288)); }
;         __builtin_amdgcn_s_setprio(1);
; #pragma unroll
;         for (int s = 0; s < 2; ++s)
; #pragma unroll
;             for (int d2 = 0; d2 < 2; ++d2) { const int dt = 2 * dh + d2; S.O1[dt] = MFMA16(vt[d2][s], p1[s], S.O1[dt]); S.O2[dt] = MFMA16(vt[d2][s], p2[s], S.O2[dt]); }
;         __builtin_amdgcn_s_setprio(0);
;         __builtin_amdgcn_sched_barrier(0);
;     }
; template <int VAR>
; DI void attn_tile(AtState& S, const LAS unsigned char* buf, const bf16x8 q1, const bf16x8 q2, int kt, bool diag, int qpos0, int qpos_l, float slope2, float adv, float decay, int hh, int fr, int fq) {
;     ...
;             const float bump = fmaxf(lm, 0.f);
;             const float alpha = decay * fast_exp2(-bump); S.ref += bump;
; #pragma unroll
;             for (int k4 = 0; k4 < 4; ++k4) { s1[k4] = s1[k4] - bump; s2[k4] = s2[k4] - bump; S.cinit[k4] = S.cinit[k4] - bump; }
;             at_exp(s1, s2, ps1, ps2);
;             at_pv(S, s1, s2, alpha, ps1, ps2, buf, hh, fq, tq, tp);
	v_max3_f32 v84, v255, v85, 0
	v_sub_f32_e32 v86, v47, v84
	v_sub_f32_e32 v87, v46, v84
	v_sub_f32_e32 v88, v45, v84
	v_sub_f32_e32 v89, v44, v84
	v_sub_f32_e32 v90, v51, v84
	v_sub_f32_e32 v91, v50, v84
	v_sub_f32_e32 v92, v49, v84
	v_sub_f32_e32 v93, v48, v84
	v_sub_f32_e32 v94, v55, v84
	v_sub_f32_e32 v95, v54, v84
	v_sub_f32_e32 v101, v53, v84
	v_sub_f32_e32 v102, v52, v84
	v_sub_f32_e32 v103, v59, v84
	v_sub_f32_e32 v151, v58, v84
	v_sub_f32_e32 v156, v57, v84
	v_sub_f32_e32 v157, v56, v84
	v_exp_f32_e32 v216, v89
	v_exp_f32_e32 v220, v93
	v_exp_f32_e32 v217, v88
	v_exp_f32_e32 v221, v92
	v_exp_f32_e32 v218, v87
	v_exp_f32_e32 v222, v91
	v_exp_f32_e32 v219, v86
	v_exp_f32_e32 v223, v90
	v_sub_f32_e32 v237, v63, v84
	v_sub_f32_e32 v236, v62, v84
	v_sub_f32_e32 v233, v61, v84
	v_sub_f32_e32 v232, v60, v84
	v_sub_f32_e32 v239, v67, v84
	v_sub_f32_e32 v238, v66, v84
	v_sub_f32_e32 v235, v65, v84
	v_sub_f32_e32 v234, v64, v84
	v_exp_f32_e32 v224, v102
	v_exp_f32_e32 v226, v157
	v_exp_f32_e32 v225, v101
	v_exp_f32_e32 v227, v156
	v_exp_f32_e32 v228, v95
	v_exp_f32_e32 v230, v151
	v_exp_f32_e32 v229, v94
	v_exp_f32_e32 v231, v103
	v_sub_f32_e32 v71, v71, v84
	v_sub_f32_e32 v70, v70, v84
	v_sub_f32_e32 v69, v69, v84
	v_sub_f32_e32 v68, v68, v84
	v_sub_f32_e32 v75, v75, v84
	v_sub_f32_e32 v74, v74, v84
	v_sub_f32_e32 v73, v73, v84
	v_sub_f32_e32 v72, v72, v84
	v_exp_f32_e32 v232, v232
	v_exp_f32_e32 v234, v234
	v_exp_f32_e32 v233, v233
	v_exp_f32_e32 v235, v235
	v_exp_f32_e32 v236, v236
	v_exp_f32_e32 v238, v238
	v_exp_f32_e32 v237, v237
	v_exp_f32_e32 v239, v239
	v_exp_f32_e32 v240, v68
	v_exp_f32_e32 v242, v72
	v_exp_f32_e32 v241, v69
	v_exp_f32_e32 v243, v73
	v_exp_f32_e32 v244, v70
	v_exp_f32_e32 v246, v74
	v_exp_f32_e32 v245, v71
	v_exp_f32_e32 v247, v75
	v_pk_add_f32 v[62:63], v[228:229], v[218:219]
	v_pk_add_f32 v[60:61], v[224:225], v[216:217]
	v_pk_add_f32 v[66:67], v[230:231], v[222:223]
	v_pk_add_f32 v[64:65], v[226:227], v[220:221]
	v_pk_add_f32 v[60:61], v[232:233], v[60:61]
	v_pk_add_f32 v[62:63], v[236:237], v[62:63]
	v_pk_add_f32 v[64:65], v[234:235], v[64:65]
	v_pk_add_f32 v[66:67], v[238:239], v[66:67]
	v_pk_add_f32 v[62:63], v[244:245], v[62:63]
	v_pk_add_f32 v[60:61], v[240:241], v[60:61]
	v_pk_add_f32 v[66:67], v[246:247], v[66:67]
	v_pk_add_f32 v[64:65], v[242:243], v[64:65]
	v_cvt_pk_bf16_f32 v216, v216, v217
	v_cvt_pk_bf16_f32 v217, v218, v219
	v_cvt_pk_bf16_f32 v218, v224, v225
	v_cvt_pk_bf16_f32 v219, v228, v229
	v_cvt_pk_bf16_f32 v220, v220, v221
	v_cvt_pk_bf16_f32 v221, v222, v223
	v_cvt_pk_bf16_f32 v222, v226, v227
	v_cvt_pk_bf16_f32 v223, v230, v231
	v_cvt_pk_bf16_f32 v224, v232, v233
	v_cvt_pk_bf16_f32 v225, v236, v237
	v_cvt_pk_bf16_f32 v226, v240, v241
	v_cvt_pk_bf16_f32 v227, v244, v245
	v_cvt_pk_bf16_f32 v228, v234, v235
	v_cvt_pk_bf16_f32 v229, v238, v239
	v_cvt_pk_bf16_f32 v230, v242, v243
	v_cvt_pk_bf16_f32 v231, v246, v247
	ds_read_b64_tr_b16 v[232:233], v208 offset:53248
	ds_read_b64_tr_b16 v[236:237], v208 offset:53280
	ds_read_b64_tr_b16 v[234:235], v208 offset:57856
	ds_read_b64_tr_b16 v[240:241], v208 offset:62464
	ds_read_b64_tr_b16 v[242:243], v209 offset:4608
	ds_read_b64_tr_b16 v[238:239], v208 offset:57888
	ds_read_b64_tr_b16 v[244:245], v208 offset:62496
	ds_read_b64_tr_b16 v[246:247], v210 offset:4608
	v_exp_f32_e64 v85, -v84
	v_mov_b32_e32 v68, v64
	v_mov_b32_e32 v69, v60
	v_mov_b32_e32 v60, v65
	v_mov_b32_e32 v64, v66
	v_mov_b32_e32 v65, v62
	v_mov_b32_e32 v62, v67
	v_pk_add_f32 v[60:61], v[68:69], v[60:61]
	v_pk_add_f32 v[62:63], v[64:65], v[62:63]
	v_mul_f32_e32 v100, v150, v85
	v_pk_add_f32 v[60:61], v[60:61], v[62:63]
	v_add_f32_e32 v214, v215, v84
	v_sub_f32_e32 v47, v79, v84
	v_sub_f32_e32 v46, v78, v84
	v_sub_f32_e32 v45, v77, v84
	v_sub_f32_e32 v44, v76, v84
	v_sub_f32_e32 v51, v99, v84
	v_sub_f32_e32 v50, v98, v84
	v_sub_f32_e32 v49, v97, v84
	v_sub_f32_e32 v48, v96, v84
	v_sub_f32_e32 v55, v107, v84
	v_sub_f32_e32 v54, v106, v84
	v_sub_f32_e32 v53, v105, v84
	v_sub_f32_e32 v52, v104, v84
	v_sub_f32_e32 v59, v83, v84
	v_sub_f32_e32 v58, v82, v84
	v_sub_f32_e32 v57, v81, v84
	v_sub_f32_e32 v56, v80, v84
	v_pk_fma_f32 v[156:157], v[158:159], v[100:101], v[60:61] op_sel_hi:[1,0,1]
	v_pk_mul_f32 v[62:63], v[122:123], v[100:101] op_sel_hi:[1,0]
	v_pk_mul_f32 v[60:61], v[120:121], v[100:101] op_sel_hi:[1,0]
	v_pk_mul_f32 v[66:67], v[118:119], v[100:101] op_sel_hi:[1,0]
	v_pk_mul_f32 v[64:65], v[116:117], v[100:101] op_sel_hi:[1,0]
	v_pk_mul_f32 v[70:71], v[114:115], v[100:101] op_sel_hi:[1,0]
	v_pk_mul_f32 v[68:69], v[112:113], v[100:101] op_sel_hi:[1,0]
	v_pk_mul_f32 v[74:75], v[110:111], v[100:101] op_sel_hi:[1,0]
	v_pk_mul_f32 v[72:73], v[108:109], v[100:101] op_sel_hi:[1,0]
	v_pk_mul_f32 v[86:87], v[138:139], v[100:101] op_sel_hi:[1,0]
	v_pk_mul_f32 v[84:85], v[136:137], v[100:101] op_sel_hi:[1,0]
	v_pk_mul_f32 v[90:91], v[134:135], v[100:101] op_sel_hi:[1,0]
	v_pk_mul_f32 v[88:89], v[132:133], v[100:101] op_sel_hi:[1,0]
	v_pk_mul_f32 v[94:95], v[130:131], v[100:101] op_sel_hi:[1,0]
	v_pk_mul_f32 v[92:93], v[128:129], v[100:101] op_sel_hi:[1,0]
	v_pk_mul_f32 v[102:103], v[126:127], v[100:101] op_sel_hi:[1,0]
	v_pk_mul_f32 v[100:101], v[124:125], v[100:101] op_sel_hi:[1,0]
	s_setprio 1
	s_waitcnt lgkmcnt(5)
	v_mfma_f32_16x16x32_bf16 v[60:63], v[232:235], v[216:219], v[60:63]
	v_mfma_f32_16x16x32_bf16 v[232:235], v[232:235], v[220:223], v[64:67]
	s_waitcnt lgkmcnt(2)
	v_mfma_f32_16x16x32_bf16 v[68:71], v[236:239], v[216:219], v[68:71]
	v_mfma_f32_16x16x32_bf16 v[236:239], v[236:239], v[220:223], v[72:75]
	v_mfma_f32_16x16x32_bf16 v[64:67], v[240:243], v[224:227], v[60:63]
	v_mfma_f32_16x16x32_bf16 v[72:75], v[240:243], v[228:231], v[232:235]
	s_waitcnt lgkmcnt(0)
	v_mfma_f32_16x16x32_bf16 v[60:63], v[244:247], v[224:227], v[68:71]
	v_mfma_f32_16x16x32_bf16 v[68:71], v[244:247], v[228:231], v[236:239]
	s_setprio 0
	ds_read_b64_tr_b16 v[232:233], v208 offset:53312
	s_nop 0
	ds_read_b64_tr_b16 v[236:237], v208 offset:53344
	ds_read_b64_tr_b16 v[234:235], v208 offset:57920
	ds_read_b64_tr_b16 v[238:239], v208 offset:57952
	ds_read_b64_tr_b16 v[240:241], v208 offset:62528
	ds_read_b64_tr_b16 v[242:243], v211 offset:4608
	ds_read_b64_tr_b16 v[246:247], v212 offset:4608
	ds_read_b64_tr_b16 v[244:245], v208 offset:62560
	s_setprio 1
	s_waitcnt lgkmcnt(5)
	v_mfma_f32_16x16x32_bf16 v[84:87], v[232:235], v[216:219], v[84:87]
	v_mfma_f32_16x16x32_bf16 v[232:235], v[232:235], v[220:223], v[88:91]
	s_waitcnt lgkmcnt(4)
	v_mfma_f32_16x16x32_bf16 v[92:95], v[236:239], v[216:219], v[92:95]
	v_mfma_f32_16x16x32_bf16 v[216:219], v[236:239], v[220:223], v[100:103]
	s_waitcnt lgkmcnt(2)
	v_mfma_f32_16x16x32_bf16 v[88:91], v[240:243], v[224:227], v[84:87]
	v_mfma_f32_16x16x32_bf16 v[100:103], v[240:243], v[228:231], v[232:235]
	s_waitcnt lgkmcnt(0)
	v_mfma_f32_16x16x32_bf16 v[84:87], v[244:247], v[224:227], v[92:95]
	v_mfma_f32_16x16x32_bf16 v[92:95], v[244:247], v[228:231], v[216:219]
	s_setprio 0
	s_cbranch_execnz .LBB0_1390

; #define LAS __attribute__((address_space(3)))
; #define MFMA16(a, b, c) __builtin_amdgcn_mfma_f32_16x16x32_bf16((a), (b), (c), 0, 0, 0)
; DI void at_qk(f32x4 (&s1)[4], f32x4 (&s2)[4], const LAS unsigned char* buf, const bf16x8 q1, const bf16x8 q2, const f32x4 (&ci)[4], int hh, int fr, int fq) {
; #pragma unroll
;     for (int k4 = 0; k4 < 4; ++k4) { const LAS unsigned char* kr = buf + AT_K + (16 * k4 + fr) * 272 + hh * 128 + fq * 16;
;         s1[k4] = MFMA16(ld8l(kr), q1, ci[k4]); s2[k4] = MFMA16(ld8l(kr + 64), q2, ci[k4]); }
; }
; template <int VAR>
; DI void attn_tile(AtState& S, const LAS unsigned char* buf, const bf16x8 q1, const bf16x8 q2, int kt, bool diag, int qpos0, int qpos_l, float slope2, float adv, float decay, int hh, int fr, int fq) {
;     ...
;         { f32x4 z[4];
; #pragma unroll
;           for (int k4 = 0; k4 < 4; ++k4) z[k4] = (f32x4){0.f, 0.f, 0.f, 0.f};
;           at_qk(s1, s2, buf, q1, q2, z, hh, fr, fq); }
;         int ql = qpos_l - 4 * fq; asm volatile("" : "+v"(ql));
;         const float dk = slope2 * (float)(qpos0 - kt * 64);
;         float mx = -1e30f;
; #pragma unroll
;         for (int k4 = 0; k4 < 4; ++k4)
; #pragma unroll
;             for (int j = 0; j < 4; ++j) { const float g = slope2 * (float)(16 * k4 + j - ql); const float bias = diag ? -fabsf(g) : g - dk;
;                 s1[k4][j] += bias; s2[k4][j] += bias; mx = fmaxf(mx, fmaxf(s1[k4][j], s2[k4][j])); }
;         mx = fmaxf(mx, __shfl_xor(mx, 16)); mx = fmaxf(mx, __shfl_xor(mx, 32));
.LBB0_1391:
	s_andn2_b64 vcc, exec, s[14:15]
	s_cbranch_vccnz .LBB0_1393
	ds_read_b128 v[44:47], v213 offset:35840
	ds_read_b128 v[48:51], v213 offset:35904
	v_mov_b32_e32 v86, v206
	ds_read_b128 v[52:55], v213 offset:40192
	ds_read_b128 v[56:59], v213 offset:40256
	ds_read_b128 v[60:63], v213 offset:44544
	ds_read_b128 v[64:67], v213 offset:44608
	ds_read_b128 v[68:71], v213 offset:48896
	ds_read_b128 v[72:75], v213 offset:48960
	s_waitcnt lgkmcnt(7)
	v_mfma_f32_16x16x32_bf16 v[44:47], v[44:47], v[4:7], 0
	v_sub_u32_e32 v84, 0, v86
	v_sub_u32_e32 v85, 1, v86
	v_cvt_f32_i32_e32 v85, v85
	v_cvt_f32_i32_e32 v84, v84
	s_waitcnt lgkmcnt(6)
	v_mfma_f32_16x16x32_bf16 v[48:51], v[48:51], v[8:11], 0
	v_mul_f32_e64 v84, v148, v84
	v_mul_f32_e64 v85, v149, v85
	v_and_b32_e32 v85, 0x7fffffff, v85
	v_and_b32_e32 v84, 0x7fffffff, v84
	s_nop 3
	v_pk_add_f32 v[48:49], v[48:49], v[84:85] neg_lo:[0,1] neg_hi:[0,1]
	v_pk_add_f32 v[44:45], v[44:45], v[84:85] neg_lo:[0,1] neg_hi:[0,1]
	v_sub_u32_e32 v84, 2, v86
	v_sub_u32_e32 v85, 3, v86
	v_cvt_f32_i32_e32 v85, v85
	v_cvt_f32_i32_e32 v84, v84
	s_waitcnt lgkmcnt(5)
	v_mfma_f32_16x16x32_bf16 v[52:55], v[52:55], v[4:7], 0
	v_max_f32_e32 v87, v44, v48
	v_max_f32_e32 v88, v45, v49
	v_pk_mul_f32 v[84:85], v[148:149], v[84:85]
	s_waitcnt lgkmcnt(4)
	v_mfma_f32_16x16x32_bf16 v[56:59], v[56:59], v[8:11], 0
	v_and_b32_e32 v85, 0x7fffffff, v85
	v_and_b32_e32 v84, 0x7fffffff, v84
	v_pk_add_f32 v[50:51], v[50:51], v[84:85] neg_lo:[0,1] neg_hi:[0,1]
	v_pk_add_f32 v[46:47], v[46:47], v[84:85] neg_lo:[0,1] neg_hi:[0,1]
	v_sub_u32_e32 v84, 16, v86
	v_sub_u32_e32 v85, 17, v86
	v_cvt_f32_i32_e32 v85, v85
	v_cvt_f32_i32_e32 v84, v84
	s_waitcnt lgkmcnt(3)
	v_mfma_f32_16x16x32_bf16 v[60:63], v[60:63], v[4:7], 0
	v_max3_f32 v87, v87, s60, v88
	v_max_f32_e32 v88, v46, v50
	v_pk_mul_f32 v[84:85], v[148:149], v[84:85]
	s_waitcnt lgkmcnt(2)
	v_mfma_f32_16x16x32_bf16 v[64:67], v[64:67], v[8:11], 0
	v_and_b32_e32 v85, 0x7fffffff, v85
	v_and_b32_e32 v84, 0x7fffffff, v84
	v_pk_add_f32 v[56:57], v[56:57], v[84:85] neg_lo:[0,1] neg_hi:[0,1]
	v_pk_add_f32 v[52:53], v[52:53], v[84:85] neg_lo:[0,1] neg_hi:[0,1]
	v_sub_u32_e32 v84, 18, v86
	v_sub_u32_e32 v85, 19, v86
	v_cvt_f32_i32_e32 v85, v85
	v_cvt_f32_i32_e32 v84, v84
	s_waitcnt lgkmcnt(1)
	v_mfma_f32_16x16x32_bf16 v[68:71], v[68:71], v[4:7], 0
	v_max_f32_e32 v89, v47, v51
	v_max3_f32 v87, v87, v88, v89
	v_pk_mul_f32 v[84:85], v[148:149], v[84:85]
	s_waitcnt lgkmcnt(0)
	v_mfma_f32_16x16x32_bf16 v[72:75], v[72:75], v[8:11], 0
	v_and_b32_e32 v85, 0x7fffffff, v85
	v_and_b32_e32 v84, 0x7fffffff, v84
	v_pk_add_f32 v[58:59], v[58:59], v[84:85] neg_lo:[0,1] neg_hi:[0,1]
	v_pk_add_f32 v[54:55], v[54:55], v[84:85] neg_lo:[0,1] neg_hi:[0,1]
	v_sub_u32_e32 v84, 32, v86
	v_sub_u32_e32 v85, 33, v86
	v_cvt_f32_i32_e32 v85, v85
	v_cvt_f32_i32_e32 v84, v84
	v_max_f32_e32 v88, v52, v56
	v_max_f32_e32 v89, v53, v57
	v_max3_f32 v87, v87, v88, v89
	v_pk_mul_f32 v[84:85], v[148:149], v[84:85]
	v_max_f32_e32 v88, v54, v58
	v_and_b32_e32 v85, 0x7fffffff, v85
	v_and_b32_e32 v84, 0x7fffffff, v84
	v_pk_add_f32 v[64:65], v[64:65], v[84:85] neg_lo:[0,1] neg_hi:[0,1]
	v_pk_add_f32 v[60:61], v[60:61], v[84:85] neg_lo:[0,1] neg_hi:[0,1]
	v_sub_u32_e32 v84, 34, v86
	v_sub_u32_e32 v85, 35, v86
	v_cvt_f32_i32_e32 v85, v85
	v_cvt_f32_i32_e32 v84, v84
	v_max_f32_e32 v89, v55, v59
	v_max3_f32 v87, v87, v88, v89
	v_max_f32_e32 v88, v60, v64
	v_pk_mul_f32 v[84:85], v[148:149], v[84:85]
	v_max_f32_e32 v89, v61, v65
	v_and_b32_e32 v85, 0x7fffffff, v85
	v_and_b32_e32 v84, 0x7fffffff, v84
	v_pk_add_f32 v[66:67], v[66:67], v[84:85] neg_lo:[0,1] neg_hi:[0,1]
	v_pk_add_f32 v[62:63], v[62:63], v[84:85] neg_lo:[0,1] neg_hi:[0,1]
	v_sub_u32_e32 v84, 48, v86
	v_sub_u32_e32 v85, 49, v86
	v_cvt_f32_i32_e32 v85, v85
	v_cvt_f32_i32_e32 v84, v84
	v_max3_f32 v87, v87, v88, v89
	v_max_f32_e32 v88, v62, v66
	v_max_f32_e32 v89, v63, v67
	v_pk_mul_f32 v[84:85], v[148:149], v[84:85]
	v_max3_f32 v87, v87, v88, v89
	v_and_b32_e32 v85, 0x7fffffff, v85
	v_and_b32_e32 v84, 0x7fffffff, v84
	v_pk_add_f32 v[72:73], v[72:73], v[84:85] neg_lo:[0,1] neg_hi:[0,1]
	v_pk_add_f32 v[68:69], v[68:69], v[84:85] neg_lo:[0,1] neg_hi:[0,1]
	v_sub_u32_e32 v84, 50, v86
	v_sub_u32_e32 v85, 51, v86
	v_cvt_f32_i32_e32 v85, v85
	v_cvt_f32_i32_e32 v84, v84
	v_max_f32_e32 v86, v68, v72
	v_max_f32_e32 v88, v69, v73
	v_max3_f32 v86, v87, v86, v88
	v_pk_mul_f32 v[84:85], v[148:149], v[84:85]
	s_nop 0
	v_and_b32_e32 v85, 0x7fffffff, v85
	v_and_b32_e32 v84, 0x7fffffff, v84
	v_pk_add_f32 v[74:75], v[74:75], v[84:85] neg_lo:[0,1] neg_hi:[0,1]
	v_pk_add_f32 v[70:71], v[70:71], v[84:85] neg_lo:[0,1] neg_hi:[0,1]
	s_nop 0
	v_max_f32_e32 v84, v70, v74
	v_max_f32_e32 v85, v71, v75
	v_max3_f32 v84, v86, v84, v85
	v_and_b32_e32 v86, 64, v198
	v_mov_b32_e32 v85, v84
	v_mov_b32_e32 v255, v84
	s_nop 1
	v_permlane16_swap_b32_e32 v85, v255
	s_waitcnt lgkmcnt(0)
	v_max_f32_e32 v84, v85, v255
	v_mov_b32_e32 v85, v84
	v_mov_b32_e32 v255, v84
	s_nop 1
	v_permlane32_swap_b32_e32 v85, v255
	s_waitcnt lgkmcnt(0)
; #define LAS __attribute__((address_space(3)))
; DI float fast_exp2(float x) { return __builtin_amdgcn_exp2f(x); }
; DI void at_exp(f32x4 (&s1)[4], f32x4 (&s2)[4], float& ps1, float& ps2) {
;     f32x4 a1 = (f32x4){0.f, 0.f, 0.f, 0.f}, a2 = a1;
; #pragma unroll
;     for (int k4 = 0; k4 < 4; ++k4) {
; #pragma unroll
;         for (int j = 0; j < 4; ++j) { s1[k4][j] = fast_exp2(s1[k4][j]); s2[k4][j] = fast_exp2(s2[k4][j]); }
;         a1 = a1 + s1[k4]; a2 = a2 + s2[k4]; }
;     ps1 = (a1[0] + a1[1]) + (a1[2] + a1[3]); ps2 = (a2[0] + a2[1]) + (a2[2] + a2[3]);
; }
; DI void at_pv(AtState& S, const f32x4 (&s1)[4], const f32x4 (&s2)[4], float alpha, float ps1, float ps2, const LAS unsigned char* buf, int hh, int fq, int tq, int tp) {
;     S.l1 = S.l1 * alpha + ps1; S.l2 = S.l2 * alpha + ps2;
; #pragma unroll
;     for (int dt = 0; dt < 4; ++dt) { S.O1[dt] = S.O1[dt] * alpha; S.O2[dt] = S.O2[dt] * alpha; }
;     bf16x8 p1[2], p2[2];
; #pragma unroll
;     for (int s = 0; s < 2; ++s) { p1[s] = packp(s1[2 * s], s1[2 * s + 1]); p2[s] = packp(s2[2 * s], s2[2 * s + 1]); }
; #pragma unroll
;     for (int dh = 0; dh < 2; ++dh) {
;         bf16x8 vt[2][2];
; #pragma unroll
;         for (int d2 = 0; d2 < 2; ++d2)
; #pragma unroll
;             for (int s = 0; s < 2; ++s) { const int dt = 2 * dh + d2; const LAS unsigned char* vr = buf + AT_V + (32 * s + 4 * fq + tq) * 288 + (hh * 64 + 16 * dt + 4 * tp) * 2; vt[d2][s] = cat44(tr4(vr), tr4(vr + 16 * 288)); }
;         __builtin_amdgcn_s_setprio(1);
; #pragma unroll
;         for (int s = 0; s < 2; ++s)
; #pragma unroll
; template <int VAR>
; DI void attn_tile(AtState& S, const LAS unsigned char* buf, const bf16x8 q1, const bf16x8 q2, int kt, bool diag, int qpos0, int qpos_l, float slope2, float adv, float decay, int hh, int fr, int fq) {
;     ...
;         const float nref = fmaxf(S.ref, mx);
;         const float alpha = fast_exp2(S.ref - nref); S.ref = nref;
; #pragma unroll
;         for (int k4 = 0; k4 < 4; ++k4) { s1[k4] = s1[k4] - nref; s2[k4] = s2[k4] - nref; }
;         if (kt == 0) { const float c0 = -slope2 * (float)qpos0 - S.ref;
; #pragma unroll
;             for (int k4 = 0; k4 < 4; ++k4)
; #pragma unroll
;                 for (int j = 0; j < 4; ++j) S.cinit[k4][j] = slope2 * (float)(16 * k4 + j - ql) + c0; }
;         at_exp(s1, s2, ps1, ps2);
;         at_pv(S, s1, s2, alpha, ps1, ps2, buf, hh, fq, tq, tp);
	v_max3_f32 v214, v3, v255, v85
	v_sub_f32_e32 v47, v47, v214
	v_sub_f32_e32 v46, v46, v214
	v_sub_f32_e32 v45, v45, v214
	v_sub_f32_e32 v44, v44, v214
	v_sub_f32_e32 v51, v51, v214
	v_sub_f32_e32 v50, v50, v214
	v_sub_f32_e32 v49, v49, v214
	v_sub_f32_e32 v48, v48, v214
	v_sub_f32_e32 v55, v55, v214
	v_sub_f32_e32 v54, v54, v214
	v_sub_f32_e32 v53, v53, v214
	v_sub_f32_e32 v52, v52, v214
	v_sub_f32_e32 v59, v59, v214
	v_sub_f32_e32 v58, v58, v214
	v_sub_f32_e32 v57, v57, v214
	v_sub_f32_e32 v56, v56, v214
	v_sub_f32_e32 v84, v63, v214
	v_sub_f32_e32 v85, v62, v214
	v_sub_f32_e32 v87, v67, v214
	v_sub_f32_e32 v88, v66, v214
	v_sub_f32_e32 v89, v65, v214
	v_sub_f32_e32 v90, v64, v214
	v_sub_f32_e32 v93, v69, v214
	v_sub_f32_e32 v94, v68, v214
	v_exp_f32_e32 v62, v44
	v_exp_f32_e32 v64, v48
	v_exp_f32_e32 v63, v45
	v_exp_f32_e32 v65, v49
	v_exp_f32_e32 v66, v46
	v_exp_f32_e32 v67, v47
	v_exp_f32_e32 v68, v50
	v_exp_f32_e32 v69, v51
	v_sub_f32_e32 v61, v61, v214
	v_sub_f32_e32 v86, v60, v214
	v_sub_f32_e32 v91, v71, v214
	v_sub_f32_e32 v92, v70, v214
	v_sub_f32_e32 v95, v75, v214
	v_sub_f32_e32 v100, v74, v214
	v_sub_f32_e32 v101, v73, v214
	v_sub_f32_e32 v102, v72, v214
	v_exp_f32_e32 v70, v52
	v_exp_f32_e32 v72, v56
	v_exp_f32_e32 v71, v53
	v_exp_f32_e32 v74, v54
	v_exp_f32_e32 v75, v55
	v_exp_f32_e32 v162, v58
	v_exp_f32_e32 v163, v59
	v_exp_f32_e32 v73, v57
	v_exp_f32_e32 v164, v86
	v_exp_f32_e32 v166, v90
	v_exp_f32_e32 v165, v61
	v_exp_f32_e32 v167, v89
	v_exp_f32_e32 v168, v85
	v_exp_f32_e32 v169, v84
	v_exp_f32_e32 v170, v88
	v_exp_f32_e32 v171, v87
	v_exp_f32_e32 v172, v94
	v_exp_f32_e32 v174, v102
	v_exp_f32_e32 v173, v93
	v_exp_f32_e32 v176, v92
	v_exp_f32_e32 v177, v91
	v_exp_f32_e32 v178, v100
	v_exp_f32_e32 v179, v95
	v_exp_f32_e32 v175, v101
	v_pk_add_f32 v[46:47], v[74:75], v[66:67]
	v_pk_add_f32 v[44:45], v[70:71], v[62:63]
	v_pk_add_f32 v[50:51], v[162:163], v[68:69]
	v_pk_add_f32 v[48:49], v[72:73], v[64:65]
	v_sub_f32_e32 v3, v3, v214
	v_pk_add_f32 v[44:45], v[164:165], v[44:45]
	v_pk_add_f32 v[46:47], v[168:169], v[46:47]
	v_pk_add_f32 v[48:49], v[166:167], v[48:49]
	v_pk_add_f32 v[50:51], v[170:171], v[50:51]
	v_exp_f32_e32 v60, v3
	v_pk_add_f32 v[46:47], v[176:177], v[46:47]
	v_pk_add_f32 v[44:45], v[172:173], v[44:45]
	v_pk_add_f32 v[50:51], v[178:179], v[50:51]
	v_pk_add_f32 v[48:49], v[174:175], v[48:49]
	v_mov_b32_e32 v53, v44
	v_mov_b32_e32 v52, v48
	v_mov_b32_e32 v44, v49
	v_mov_b32_e32 v48, v50
	v_mov_b32_e32 v49, v46
	v_mov_b32_e32 v46, v51
	v_pk_add_f32 v[44:45], v[52:53], v[44:45]
	v_pk_add_f32 v[46:47], v[48:49], v[46:47]
	v_pk_mul_f32 v[50:51], v[118:119], v[60:61] op_sel_hi:[1,0]
	v_pk_add_f32 v[44:45], v[44:45], v[46:47]
	v_pk_mul_f32 v[46:47], v[122:123], v[60:61] op_sel_hi:[1,0]
	v_pk_fma_f32 v[156:157], v[158:159], v[60:61], v[44:45] op_sel_hi:[1,0,1]
	v_pk_mul_f32 v[44:45], v[120:121], v[60:61] op_sel_hi:[1,0]
	v_pk_mul_f32 v[48:49], v[116:117], v[60:61] op_sel_hi:[1,0]
	v_pk_mul_f32 v[54:55], v[114:115], v[60:61] op_sel_hi:[1,0]
	v_pk_mul_f32 v[52:53], v[112:113], v[60:61] op_sel_hi:[1,0]
	v_pk_mul_f32 v[58:59], v[110:111], v[60:61] op_sel_hi:[1,0]
	v_pk_mul_f32 v[56:57], v[108:109], v[60:61] op_sel_hi:[1,0]
	v_pk_mul_f32 v[86:87], v[138:139], v[60:61] op_sel_hi:[1,0]
	v_pk_mul_f32 v[84:85], v[136:137], v[60:61] op_sel_hi:[1,0]
	v_pk_mul_f32 v[90:91], v[134:135], v[60:61] op_sel_hi:[1,0]
	v_pk_mul_f32 v[88:89], v[132:133], v[60:61] op_sel_hi:[1,0]
	v_pk_mul_f32 v[94:95], v[130:131], v[60:61] op_sel_hi:[1,0]
	v_pk_mul_f32 v[92:93], v[128:129], v[60:61] op_sel_hi:[1,0]
	v_pk_mul_f32 v[102:103], v[126:127], v[60:61] op_sel_hi:[1,0]
	v_pk_mul_f32 v[100:101], v[124:125], v[60:61] op_sel_hi:[1,0]
	v_cvt_pk_bf16_f32 v108, v62, v63
	v_cvt_pk_bf16_f32 v109, v66, v67
	v_cvt_pk_bf16_f32 v110, v70, v71
	v_cvt_pk_bf16_f32 v112, v64, v65
	v_cvt_pk_bf16_f32 v113, v68, v69
	ds_read_b64_tr_b16 v[60:61], v208 offset:53248
	ds_read_b64_tr_b16 v[64:65], v208 offset:53280
	ds_read_b64_tr_b16 v[62:63], v208 offset:57856
	ds_read_b64_tr_b16 v[66:67], v208 offset:57888
	ds_read_b64_tr_b16 v[68:69], v208 offset:62464
	ds_read_b64_tr_b16 v[70:71], v209 offset:4608
	ds_read_b64_tr_b16 v[122:123], v210 offset:4608
	ds_read_b64_tr_b16 v[120:121], v208 offset:62496
	v_cvt_pk_bf16_f32 v111, v74, v75
	v_cvt_pk_bf16_f32 v114, v72, v73
	v_cvt_pk_bf16_f32 v115, v162, v163
	v_cvt_pk_bf16_f32 v116, v164, v165
	v_cvt_pk_bf16_f32 v117, v168, v169
	v_cvt_pk_bf16_f32 v118, v172, v173
	v_cvt_pk_bf16_f32 v119, v176, v177
	v_cvt_pk_bf16_f32 v124, v166, v167
	v_cvt_pk_bf16_f32 v125, v170, v171
	v_cvt_pk_bf16_f32 v126, v174, v175
	v_cvt_pk_bf16_f32 v127, v178, v179
	s_setprio 1
	s_waitcnt lgkmcnt(5)
	v_mfma_f32_16x16x32_bf16 v[44:47], v[60:63], v[108:111], v[44:47]
	v_mfma_f32_16x16x32_bf16 v[48:51], v[60:63], v[112:115], v[48:51]
	s_waitcnt lgkmcnt(4)
	v_mfma_f32_16x16x32_bf16 v[52:55], v[64:67], v[108:111], v[52:55]
	v_mfma_f32_16x16x32_bf16 v[56:59], v[64:67], v[112:115], v[56:59]
	s_waitcnt lgkmcnt(2)
	v_mfma_f32_16x16x32_bf16 v[64:67], v[68:71], v[116:119], v[44:47]
	v_mfma_f32_16x16x32_bf16 v[72:75], v[68:71], v[124:127], v[48:51]
	s_waitcnt lgkmcnt(0)
	v_mfma_f32_16x16x32_bf16 v[60:63], v[120:123], v[116:119], v[52:55]
	v_mfma_f32_16x16x32_bf16 v[68:71], v[120:123], v[124:127], v[56:59]
	s_setprio 0
	ds_read_b64_tr_b16 v[44:45], v208 offset:53312
	ds_read_b64_tr_b16 v[48:49], v208 offset:53344
	ds_read_b64_tr_b16 v[46:47], v208 offset:57920
	ds_read_b64_tr_b16 v[50:51], v208 offset:57952
	ds_read_b64_tr_b16 v[52:53], v208 offset:62528
	ds_read_b64_tr_b16 v[54:55], v211 offset:4608
	ds_read_b64_tr_b16 v[58:59], v212 offset:4608
	ds_read_b64_tr_b16 v[56:57], v208 offset:62560
	s_setprio 1
	s_waitcnt lgkmcnt(5)
	v_mfma_f32_16x16x32_bf16 v[84:87], v[44:47], v[108:111], v[84:87]
	v_mfma_f32_16x16x32_bf16 v[44:47], v[44:47], v[112:115], v[88:91]
	s_waitcnt lgkmcnt(4)
	v_mfma_f32_16x16x32_bf16 v[92:95], v[48:51], v[108:111], v[92:95]
	v_mfma_f32_16x16x32_bf16 v[48:51], v[48:51], v[112:115], v[100:103]
	s_waitcnt lgkmcnt(2)
	v_mfma_f32_16x16x32_bf16 v[88:91], v[52:55], v[116:119], v[84:87]
	v_mfma_f32_16x16x32_bf16 v[100:103], v[52:55], v[124:127], v[44:47]
	s_waitcnt lgkmcnt(0)
	v_mfma_f32_16x16x32_bf16 v[84:87], v[56:59], v[116:119], v[92:95]
	v_mfma_f32_16x16x32_bf16 v[92:95], v[56:59], v[124:127], v[48:51]
	s_setprio 0
	v_mov_b64_e32 v[52:53], v[104:105]
	s_nop 0
	v_mov_b64_e32 v[48:49], v[96:97]
	v_mov_b64_e32 v[44:45], v[76:77]
	v_mov_b64_e32 v[56:57], v[80:81]
	v_mov_b64_e32 v[54:55], v[106:107]
	v_mov_b64_e32 v[50:51], v[98:99]
	v_mov_b64_e32 v[46:47], v[78:79]
	v_mov_b64_e32 v[58:59], v[82:83]

; template <int VAR>
; DI void attn_segment(const Args& a, const Frame& F, int l, int qrow0, int qpos0, int hp, int ntile, int nf32, const float* ck, const float* cv, int prow0) {
;     ...
;     float l1 = S.l1, l2 = S.l2;
;     l1 += __shfl_xor(l1, 16); l1 += __shfl_xor(l1, 32); l2 += __shfl_xor(l2, 16); l2 += __shfl_xor(l2, 32);
;     const float lam = ((const float*)(sm + S_LAM))[0], lam_init = ((const float*)(sm + S_LAM))[1];
;     const float i1 = 1.f / l1, i2 = lam / l2;
;     float ss = 0.f;
; #pragma unroll
;     for (int dt = 0; dt < 4; ++dt)
; #pragma unroll
;         for (int j = 0; j < 4; ++j) { const float o = S.O1[dt][j] * i1 - S.O2[dt][j] * i2; S.O1[dt][j] = o; ss += o * o; }
;     ss += __shfl_xor(ss, 16); ss += __shfl_xor(ss, 32);
;     const float rs = (1.f - lam_init) / sqrtf(ss * (1.f / 64.f) + EPS);
.LBB0_1397:
	global_load_dword v3, v2, s[8:9]
	v_and_b32_e32 v5, 64, v198
	v_xor_b32_e32 v4, 16, v198
	v_add_u32_e32 v5, 64, v5
	v_cmp_lt_i32_e32 vcc, v4, v5
	v_xor_b32_e32 v6, 32, v198
	s_nop 0
	v_cndmask_b32_e32 v4, v198, v4, vcc
	s_waitcnt vmcnt(2)
	v_lshlrev_b32_e32 v36, 2, v4
	v_mov_b32_e32 v4, v157
	v_mov_b32_e32 v254, v157
	s_nop 1
	v_permlane16_swap_b32_e32 v4, v254
	s_nop 1
	v_mov_b32_dpp v4, v254 quad_perm:[0,1,2,3] row_mask:0x5 bank_mask:0xf
	v_cmp_lt_i32_e32 vcc, v6, v5
	s_waitcnt lgkmcnt(0)
	v_add_f32_e32 v4, v157, v4
	v_cndmask_b32_e32 v5, v198, v6, vcc
	v_lshlrev_b32_e32 v37, 2, v5
	v_mov_b32_e32 v6, v4
	v_mov_b32_e32 v255, v4
	s_nop 1
	v_permlane32_swap_b32_e32 v6, v255
	s_nop 1
	v_mov_b32_dpp v6, v255 quad_perm:[0,1,2,3] row_mask:0x3 bank_mask:0xf
	v_mov_b32_e32 v5, v156
	v_mov_b32_e32 v254, v156
	s_nop 1
	v_permlane16_swap_b32_e32 v5, v254
	s_nop 1
	v_mov_b32_dpp v5, v254 quad_perm:[0,1,2,3] row_mask:0x5 bank_mask:0xf
	s_waitcnt lgkmcnt(0)
	v_add_f32_e32 v4, v4, v6
	s_waitcnt lgkmcnt(0)
	v_add_f32_e32 v5, v156, v5
	v_div_scale_f32 v6, s[0:1], v4, v4, 1.0
	v_mov_b32_e32 v7, v5
	v_mov_b32_e32 v255, v5
	s_nop 1
	v_permlane32_swap_b32_e32 v7, v255
	s_nop 1
	v_mov_b32_dpp v7, v255 quad_perm:[0,1,2,3] row_mask:0x3 bank_mask:0xf
	v_rcp_f32_e32 v8, v6
	s_waitcnt lgkmcnt(0)
	v_add_f32_e32 v5, v5, v7
	v_fma_f32 v9, -v6, v8, 1.0
	v_div_scale_f32 v7, vcc, 1.0, v4, 1.0
	v_fmac_f32_e32 v8, v9, v8
	v_mul_f32_e32 v9, v7, v8
	v_fma_f32 v10, -v6, v9, v7
	v_fmac_f32_e32 v9, v10, v8
	v_fma_f32 v6, -v6, v9, v7
	v_div_fmas_f32 v6, v6, v8, v9
	v_div_fixup_f32 v4, v6, v4, 1.0
	s_waitcnt vmcnt(0)
	v_div_scale_f32 v7, s[0:1], v5, v5, v3
	v_rcp_f32_e32 v8, v7
	v_div_scale_f32 v6, vcc, v3, v5, v3
	v_fma_f32 v9, -v7, v8, 1.0
	v_fmac_f32_e32 v8, v9, v8
	v_mul_f32_e32 v9, v6, v8
	v_fma_f32 v10, -v7, v9, v6
	v_fmac_f32_e32 v9, v10, v8
	v_fma_f32 v6, -v7, v9, v6
	v_div_fmas_f32 v6, v6, v8, v9
	v_div_fixup_f32 v6, v6, v5, v3
	v_pk_mul_f32 v[8:9], v[72:73], v[6:7] op_sel_hi:[1,0]
	v_pk_mul_f32 v[10:11], v[74:75], v[6:7] op_sel_hi:[1,0]
	v_pk_mul_f32 v[12:13], v[68:69], v[6:7] op_sel_hi:[1,0]
	v_pk_mul_f32 v[20:21], v[70:71], v[6:7] op_sel_hi:[1,0]
	v_pk_fma_f32 v[18:19], v[64:65], v[4:5], v[8:9] op_sel_hi:[1,0,1] neg_lo:[0,0,1] neg_hi:[0,0,1]
	v_pk_mul_f32 v[22:23], v[100:101], v[6:7] op_sel_hi:[1,0]
	v_pk_fma_f32 v[16:17], v[66:67], v[4:5], v[10:11] op_sel_hi:[1,0,1] neg_lo:[0,0,1] neg_hi:[0,0,1]
	v_pk_fma_f32 v[14:15], v[60:61], v[4:5], v[12:13] op_sel_hi:[1,0,1] neg_lo:[0,0,1] neg_hi:[0,0,1]
	v_pk_fma_f32 v[12:13], v[62:63], v[4:5], v[20:21] op_sel_hi:[1,0,1] neg_lo:[0,0,1] neg_hi:[0,0,1]
	v_pk_mul_f32 v[20:21], v[18:19], v[18:19]
	v_pk_fma_f32 v[10:11], v[88:89], v[4:5], v[22:23] op_sel_hi:[1,0,1] neg_lo:[0,0,1] neg_hi:[0,0,1]
	v_pk_mul_f32 v[22:23], v[16:17], v[16:17]
	v_add_f32_e32 v3, v20, v21
	v_pk_mul_f32 v[24:25], v[102:103], v[6:7] op_sel_hi:[1,0]
	v_add_f32_e32 v3, v22, v3
	v_pk_fma_f32 v[8:9], v[90:91], v[4:5], v[24:25] op_sel_hi:[1,0,1] neg_lo:[0,0,1] neg_hi:[0,0,1]
	v_pk_mul_f32 v[24:25], v[14:15], v[14:15]
	v_add_f32_e32 v3, v23, v3
	v_pk_mul_f32 v[26:27], v[92:93], v[6:7] op_sel_hi:[1,0]
	v_add_f32_e32 v3, v24, v3
	v_pk_mul_f32 v[28:29], v[94:95], v[6:7] op_sel_hi:[1,0]
	v_pk_fma_f32 v[6:7], v[84:85], v[4:5], v[26:27] op_sel_hi:[1,0,1] neg_lo:[0,0,1] neg_hi:[0,0,1]
	v_pk_mul_f32 v[26:27], v[12:13], v[12:13]
	v_add_f32_e32 v3, v25, v3
	v_add_f32_e32 v3, v26, v3
	v_pk_fma_f32 v[4:5], v[86:87], v[4:5], v[28:29] op_sel_hi:[1,0,1] neg_lo:[0,0,1] neg_hi:[0,0,1]
	v_pk_mul_f32 v[28:29], v[10:11], v[10:11]
	v_add_f32_e32 v3, v27, v3
	v_add_f32_e32 v3, v28, v3
	v_pk_mul_f32 v[30:31], v[8:9], v[8:9]
	v_add_f32_e32 v3, v29, v3
	v_add_f32_e32 v3, v30, v3
	v_pk_mul_f32 v[32:33], v[6:7], v[6:7]
	v_add_f32_e32 v3, v31, v3
	v_add_f32_e32 v3, v32, v3
	v_pk_mul_f32 v[34:35], v[4:5], v[4:5]
	v_add_f32_e32 v3, v33, v3
	v_add_f32_e32 v3, v34, v3
	v_add_f32_e32 v3, v35, v3
	v_mov_b32_e32 v20, v3
	v_mov_b32_e32 v254, v3
	s_nop 1
	v_permlane16_swap_b32_e32 v20, v254
	s_nop 1
	v_mov_b32_dpp v20, v254 quad_perm:[0,1,2,3] row_mask:0x5 bank_mask:0xf
	s_waitcnt lgkmcnt(0)
	v_add_f32_e32 v3, v3, v20
	v_mov_b32_e32 v20, v3
	v_mov_b32_e32 v255, v3
	s_nop 1
	v_permlane32_swap_b32_e32 v20, v255
	s_nop 1
	v_mov_b32_dpp v20, v255 quad_perm:[0,1,2,3] row_mask:0x3 bank_mask:0xf
	s_branch .LBB0_1418

; #define LAS __attribute__((address_space(3)))
; DI float fast_exp2(float x) { return __builtin_amdgcn_exp2f(x); }
; #define MFMA16(a, b, c) __builtin_amdgcn_mfma_f32_16x16x32_bf16((a), (b), (c), 0, 0, 0)
; DI void at_qk(f32x4 (&s1)[4], f32x4 (&s2)[4], const LAS unsigned char* buf, const bf16x8 q1, const bf16x8 q2, const f32x4 (&ci)[4], int hh, int fr, int fq) {
; #pragma unroll
;     for (int k4 = 0; k4 < 4; ++k4) { const LAS unsigned char* kr = buf + AT_K + (16 * k4 + fr) * 272 + hh * 128 + fq * 16;
;         s1[k4] = MFMA16(ld8l(kr), q1, ci[k4]); s2[k4] = MFMA16(ld8l(kr + 64), q2, ci[k4]); }
; }
; DI void at_exp(f32x4 (&s1)[4], f32x4 (&s2)[4], float& ps1, float& ps2) {
;     f32x4 a1 = (f32x4){0.f, 0.f, 0.f, 0.f}, a2 = a1;
; #pragma unroll
;     for (int k4 = 0; k4 < 4; ++k4) {
; #pragma unroll
;         for (int j = 0; j < 4; ++j) { s1[k4][j] = fast_exp2(s1[k4][j]); s2[k4][j] = fast_exp2(s2[k4][j]); }
;         a1 = a1 + s1[k4]; a2 = a2 + s2[k4]; }
;     ps1 = (a1[0] + a1[1]) + (a1[2] + a1[3]); ps2 = (a2[0] + a2[1]) + (a2[2] + a2[3]);
; }
; template <int VAR>
; DI void attn_tile(AtState& S, const LAS unsigned char* buf, const bf16x8 q1, const bf16x8 q2, int kt, bool diag, int qpos0, int qpos_l, float slope2, float adv, float decay, int hh, int fr, int fq) {
;     ...
;         asm volatile("; attention: fast tile" ::: "memory");
;         at_qk(s1, s2, buf, q1, q2, S.cinit, hh, fr, fq);
;         S.ref += adv;
;         at_exp(s1, s2, ps1, ps2);
;         if (__any(!(ps1 + ps2 < 0x1p60f))) {
;             asm volatile("; attention: bump" ::: "memory");
;             at_qk(s1, s2, buf, q1, q2, S.cinit, hh, fr, fq);
;             float lm = -1e30f;
; #pragma unroll
;             for (int k4 = 0; k4 < 4; ++k4)
; #pragma unroll
;                 for (int j = 0; j < 4; ++j) lm = fmaxf(lm, fmaxf(s1[k4][j], s2[k4][j]));
;             lm = fmaxf(lm, __shfl_xor(lm, 16)); lm = fmaxf(lm, __shfl_xor(lm, 32));
.LBB0_1405:
	s_bitcmp1_b32 s40, 0
	s_cselect_b32 s26, 0x8c00, 0
	s_add_i32 s28, s41, s26
	s_sub_i32 s27, s40, 32
	v_add_u32_e32 v3, s28, v206
	s_cmp_gt_u32 s27, 0xffffffe0
	s_mov_b64 s[26:27], -1
	v_add_u32_e32 v3, v3, v207
	s_cbranch_scc0 .LBB0_1410
	ds_read_b128 v[62:65], v3
	ds_read_b128 v[66:69], v3 offset:64
	ds_read_b128 v[70:73], v3 offset:4352
	ds_read_b128 v[74:77], v3 offset:4416
	ds_read_b128 v[78:81], v3 offset:8704
	ds_read_b128 v[82:85], v3 offset:8768
	ds_read_b128 v[86:89], v3 offset:13056
	ds_read_b128 v[90:93], v3 offset:13120
	s_waitcnt lgkmcnt(7)
	v_mfma_f32_16x16x32_bf16 v[62:65], v[62:65], v[38:41], v[46:49]
	v_add_f32_e32 v213, v204, v212
	s_waitcnt lgkmcnt(6)
	v_mfma_f32_16x16x32_bf16 v[66:69], v[66:69], v[42:45], v[46:49]
	s_waitcnt lgkmcnt(5)
	v_mfma_f32_16x16x32_bf16 v[70:73], v[70:73], v[38:41], v[50:53]
	s_nop 2
	v_exp_f32_e32 v164, v62
	v_exp_f32_e32 v165, v63
	v_exp_f32_e32 v168, v64
	s_waitcnt lgkmcnt(4)
	v_mfma_f32_16x16x32_bf16 v[74:77], v[74:77], v[42:45], v[50:53]
	v_exp_f32_e32 v169, v65
	v_exp_f32_e32 v162, v66
	v_exp_f32_e32 v163, v67
	s_waitcnt lgkmcnt(3)
	v_mfma_f32_16x16x32_bf16 v[78:81], v[78:81], v[38:41], v[54:57]
	v_exp_f32_e32 v166, v68
	v_exp_f32_e32 v167, v69
	v_exp_f32_e32 v172, v70
	s_waitcnt lgkmcnt(2)
	v_mfma_f32_16x16x32_bf16 v[62:65], v[82:85], v[42:45], v[54:57]
	v_exp_f32_e32 v170, v74
	v_exp_f32_e32 v173, v71
	v_exp_f32_e32 v176, v72
	s_waitcnt lgkmcnt(1)
	v_mfma_f32_16x16x32_bf16 v[66:69], v[86:89], v[38:41], v[58:61]
	v_exp_f32_e32 v177, v73
	v_exp_f32_e32 v174, v76
	v_exp_f32_e32 v175, v77
	s_waitcnt lgkmcnt(0)
	v_mfma_f32_16x16x32_bf16 v[82:85], v[90:93], v[42:45], v[58:61]
	v_exp_f32_e32 v171, v75
	v_exp_f32_e32 v180, v78
	v_exp_f32_e32 v178, v62
	v_exp_f32_e32 v181, v79
	v_exp_f32_e32 v179, v63
	v_exp_f32_e32 v184, v80
	v_exp_f32_e32 v185, v81
	v_exp_f32_e32 v182, v64
	v_exp_f32_e32 v183, v65
	v_exp_f32_e32 v188, v66
	v_exp_f32_e32 v186, v82
	v_exp_f32_e32 v189, v67
	v_exp_f32_e32 v192, v68
	v_exp_f32_e32 v193, v69
	v_exp_f32_e32 v190, v84
	v_exp_f32_e32 v191, v85
	v_exp_f32_e32 v187, v83
	v_pk_add_f32 v[70:71], v[168:169], v[176:177]
	v_pk_add_f32 v[72:73], v[164:165], v[172:173]
	v_pk_add_f32 v[74:75], v[166:167], v[174:175]
	v_pk_add_f32 v[76:77], v[162:163], v[170:171]
	v_pk_add_f32 v[62:63], v[72:73], v[180:181]
	v_pk_add_f32 v[64:65], v[70:71], v[184:185]
	v_pk_add_f32 v[70:71], v[76:77], v[178:179]
	v_pk_add_f32 v[72:73], v[74:75], v[182:183]
	v_pk_add_f32 v[64:65], v[64:65], v[192:193]
	v_pk_add_f32 v[62:63], v[62:63], v[188:189]
	v_pk_add_f32 v[66:67], v[72:73], v[190:191]
	v_pk_add_f32 v[68:69], v[70:71], v[186:187]
	v_mov_b32_e32 v71, v62
	v_mov_b32_e32 v70, v68
	v_mov_b32_e32 v62, v69
	v_mov_b32_e32 v68, v66
	v_mov_b32_e32 v69, v64
	v_mov_b32_e32 v64, v67
	v_pk_add_f32 v[62:63], v[70:71], v[62:63]
	v_pk_add_f32 v[64:65], v[68:69], v[64:65]
	s_nop 0
	v_pk_add_f32 v[194:195], v[62:63], v[64:65]
	s_nop 0
	v_add_f32_e32 v62, v195, v194
	v_cmp_ngt_f32_e32 vcc, s65, v62
	s_cbranch_vccz .LBB0_1416
	ds_read_b128 v[62:65], v3
	ds_read_b128 v[66:69], v3 offset:64
	ds_read_b128 v[70:73], v3 offset:4352
	ds_read_b128 v[74:77], v3 offset:4416
	ds_read_b128 v[78:81], v3 offset:8704
	ds_read_b128 v[82:85], v3 offset:8768
	ds_read_b128 v[86:89], v3 offset:13056
	ds_read_b128 v[90:93], v3 offset:13120
	v_add3_u32 v246, s28, v208, v209
	s_waitcnt lgkmcnt(7)
	v_mfma_f32_16x16x32_bf16 v[62:65], v[62:65], v[38:41], v[46:49]
	s_waitcnt lgkmcnt(6)
	v_mfma_f32_16x16x32_bf16 v[66:69], v[66:69], v[42:45], v[46:49]
	s_waitcnt lgkmcnt(5)
	v_mfma_f32_16x16x32_bf16 v[70:73], v[70:73], v[38:41], v[50:53]
	s_waitcnt lgkmcnt(4)
	v_mfma_f32_16x16x32_bf16 v[74:77], v[74:77], v[42:45], v[50:53]
	s_waitcnt lgkmcnt(3)
	v_mfma_f32_16x16x32_bf16 v[78:81], v[78:81], v[38:41], v[54:57]
	s_waitcnt lgkmcnt(2)
	v_mfma_f32_16x16x32_bf16 v[82:85], v[82:85], v[42:45], v[54:57]
	s_waitcnt lgkmcnt(1)
	v_mfma_f32_16x16x32_bf16 v[86:89], v[86:89], v[38:41], v[58:61]
	s_waitcnt lgkmcnt(0)
	v_mfma_f32_16x16x32_bf16 v[90:93], v[90:93], v[42:45], v[58:61]
	v_max3_f32 v94, v62, v66, s60
	v_max3_f32 v94, v94, v63, v67
	v_max3_f32 v94, v94, v64, v68
	v_max3_f32 v94, v94, v65, v69
	v_max3_f32 v94, v94, v70, v74
	v_max3_f32 v94, v94, v71, v75
	v_max3_f32 v94, v94, v72, v76
	v_max3_f32 v94, v94, v73, v77
	v_max3_f32 v94, v94, v78, v82
	v_max3_f32 v94, v94, v79, v83
	v_max3_f32 v94, v94, v80, v84
	v_max3_f32 v94, v94, v81, v85
	v_max3_f32 v94, v94, v86, v90
	v_max3_f32 v94, v94, v87, v91
	v_max3_f32 v94, v94, v88, v92
	v_max3_f32 v94, v94, v89, v93
	v_and_b32_e32 v96, 64, v198
	v_mov_b32_e32 v95, v94
	v_mov_b32_e32 v255, v94
	s_nop 1
	v_permlane16_swap_b32_e32 v95, v255
	s_waitcnt lgkmcnt(0)
	v_max_f32_e32 v94, v95, v255
	v_mov_b32_e32 v95, v94
	v_mov_b32_e32 v255, v94
	s_nop 1
	v_permlane32_swap_b32_e32 v95, v255
	s_waitcnt lgkmcnt(0)
; #define LAS __attribute__((address_space(3)))
; DI void at_exp(f32x4 (&s1)[4], f32x4 (&s2)[4], float& ps1, float& ps2) {
;     f32x4 a1 = (f32x4){0.f, 0.f, 0.f, 0.f}, a2 = a1;
; #pragma unroll
;     for (int k4 = 0; k4 < 4; ++k4) {
; #pragma unroll
;         for (int j = 0; j < 4; ++j) { s1[k4][j] = fast_exp2(s1[k4][j]); s2[k4][j] = fast_exp2(s2[k4][j]); }
;         a1 = a1 + s1[k4]; a2 = a2 + s2[k4]; }
;     ps1 = (a1[0] + a1[1]) + (a1[2] + a1[3]); ps2 = (a2[0] + a2[1]) + (a2[2] + a2[3]);
; }
; DI void at_pv(AtState& S, const f32x4 (&s1)[4], const f32x4 (&s2)[4], float alpha, float ps1, float ps2, const LAS unsigned char* buf, int hh, int fq, int tq, int tp) {
;     S.l1 = S.l1 * alpha + ps1; S.l2 = S.l2 * alpha + ps2;
; #pragma unroll
;     for (int dt = 0; dt < 4; ++dt) { S.O1[dt] = S.O1[dt] * alpha; S.O2[dt] = S.O2[dt] * alpha; }
;     bf16x8 p1[2], p2[2];
; #pragma unroll
;     for (int s = 0; s < 2; ++s) { p1[s] = packp(s1[2 * s], s1[2 * s + 1]); p2[s] = packp(s2[2 * s], s2[2 * s + 1]); }
; #pragma unroll
;     for (int dh = 0; dh < 2; ++dh) {
;         bf16x8 vt[2][2];
; #pragma unroll
;         for (int d2 = 0; d2 < 2; ++d2)
; #pragma unroll
;             for (int s = 0; s < 2; ++s) { const int dt = 2 * dh + d2; const LAS unsigned char* vr = buf + AT_V + (32 * s + 4 * fq + tq) * 288 + (hh * 64 + 16 * dt + 4 * tp) * 2; vt[d2][s] = cat44(tr4(vr), tr4(vr + 16 * 288)); }
;         __builtin_amdgcn_s_setprio(1);
; #pragma unroll
;         for (int s = 0; s < 2; ++s)
; #pragma unroll
;             for (int d2 = 0; d2 < 2; ++d2) { const int dt = 2 * dh + d2; S.O1[dt] = MFMA16(vt[d2][s], p1[s], S.O1[dt]); S.O2[dt] = MFMA16(vt[d2][s], p2[s], S.O2[dt]); }
;         __builtin_amdgcn_s_setprio(0);
;         __builtin_amdgcn_sched_barrier(0);
;     }
; template <int VAR>
; DI void attn_tile(AtState& S, const LAS unsigned char* buf, const bf16x8 q1, const bf16x8 q2, int kt, bool diag, int qpos0, int qpos_l, float slope2, float adv, float decay, int hh, int fr, int fq) {
;     ...
;             const float bump = fmaxf(lm, 0.f);
;             const float alpha = decay * fast_exp2(-bump); S.ref += bump;
; #pragma unroll
;             for (int k4 = 0; k4 < 4; ++k4) { s1[k4] = s1[k4] - bump; s2[k4] = s2[k4] - bump; S.cinit[k4] = S.cinit[k4] - bump; }
;             at_exp(s1, s2, ps1, ps2);
;             at_pv(S, s1, s2, alpha, ps1, ps2, buf, hh, fq, tq, tp);
	v_max3_f32 v94, v255, v95, 0
	v_sub_f32_e32 v96, v65, v94
	v_sub_f32_e32 v97, v64, v94
	v_sub_f32_e32 v98, v63, v94
	v_sub_f32_e32 v99, v62, v94
	v_sub_f32_e32 v69, v69, v94
	v_sub_f32_e32 v68, v68, v94
	v_sub_f32_e32 v67, v67, v94
	v_sub_f32_e32 v66, v66, v94
	v_sub_f32_e32 v100, v73, v94
	v_sub_f32_e32 v101, v72, v94
	v_sub_f32_e32 v102, v71, v94
	v_sub_f32_e32 v103, v70, v94
	v_sub_f32_e32 v104, v77, v94
	v_sub_f32_e32 v105, v76, v94
	v_sub_f32_e32 v107, v75, v94
	v_sub_f32_e32 v108, v74, v94
	v_exp_f32_e32 v214, v99
	v_exp_f32_e32 v218, v66
	v_exp_f32_e32 v215, v98
	v_exp_f32_e32 v219, v67
	v_exp_f32_e32 v216, v97
	v_exp_f32_e32 v220, v68
	v_exp_f32_e32 v217, v96
	v_exp_f32_e32 v221, v69
	v_sub_f32_e32 v109, v81, v94
	v_sub_f32_e32 v158, v80, v94
	v_sub_f32_e32 v159, v79, v94
	v_sub_f32_e32 v230, v78, v94
	v_sub_f32_e32 v85, v85, v94
	v_sub_f32_e32 v84, v84, v94
	v_sub_f32_e32 v83, v83, v94
	v_sub_f32_e32 v82, v82, v94
	v_exp_f32_e32 v222, v103
	v_exp_f32_e32 v224, v108
	v_exp_f32_e32 v223, v102
	v_exp_f32_e32 v225, v107
	v_exp_f32_e32 v226, v101
	v_exp_f32_e32 v228, v105
	v_exp_f32_e32 v227, v100
	v_exp_f32_e32 v229, v104
	v_sub_f32_e32 v89, v89, v94
	v_sub_f32_e32 v88, v88, v94
	v_sub_f32_e32 v87, v87, v94
	v_sub_f32_e32 v86, v86, v94
	v_sub_f32_e32 v245, v93, v94
	v_sub_f32_e32 v243, v92, v94
	v_sub_f32_e32 v241, v91, v94
	v_sub_f32_e32 v239, v90, v94
	v_exp_f32_e32 v230, v230
	v_exp_f32_e32 v232, v82
	v_exp_f32_e32 v231, v159
	v_exp_f32_e32 v233, v83
	v_exp_f32_e32 v234, v158
	v_exp_f32_e32 v236, v84
	v_exp_f32_e32 v235, v109
	v_exp_f32_e32 v237, v85
	v_exp_f32_e32 v238, v86
	v_exp_f32_e32 v240, v239
	v_exp_f32_e32 v239, v87
	v_exp_f32_e32 v241, v241
	v_exp_f32_e32 v242, v88
	v_exp_f32_e32 v244, v243
	v_exp_f32_e32 v243, v89
	v_exp_f32_e32 v245, v245
	v_pk_add_f32 v[68:69], v[226:227], v[216:217]
	v_pk_add_f32 v[66:67], v[222:223], v[214:215]
	v_pk_add_f32 v[72:73], v[228:229], v[220:221]
	v_pk_add_f32 v[70:71], v[224:225], v[218:219]
	v_pk_add_f32 v[66:67], v[230:231], v[66:67]
	v_pk_add_f32 v[68:69], v[234:235], v[68:69]
	v_pk_add_f32 v[70:71], v[232:233], v[70:71]
	v_pk_add_f32 v[72:73], v[236:237], v[72:73]
	v_pk_add_f32 v[68:69], v[242:243], v[68:69]
	v_pk_add_f32 v[66:67], v[238:239], v[66:67]
	v_pk_add_f32 v[72:73], v[244:245], v[72:73]
	v_pk_add_f32 v[70:71], v[240:241], v[70:71]
	v_cvt_pk_bf16_f32 v214, v214, v215
	v_cvt_pk_bf16_f32 v215, v216, v217
	v_cvt_pk_bf16_f32 v216, v222, v223
	v_cvt_pk_bf16_f32 v217, v226, v227
	v_cvt_pk_bf16_f32 v218, v218, v219
	v_cvt_pk_bf16_f32 v219, v220, v221
	v_cvt_pk_bf16_f32 v220, v224, v225
	v_cvt_pk_bf16_f32 v221, v228, v229
	v_cvt_pk_bf16_f32 v222, v230, v231
	v_cvt_pk_bf16_f32 v223, v234, v235
	v_cvt_pk_bf16_f32 v224, v238, v239
	v_cvt_pk_bf16_f32 v225, v242, v243
	v_cvt_pk_bf16_f32 v226, v232, v233
	v_cvt_pk_bf16_f32 v227, v236, v237
	v_cvt_pk_bf16_f32 v228, v240, v241
	v_cvt_pk_bf16_f32 v229, v244, v245
	ds_read_b64_tr_b16 v[230:231], v246 offset:17408
	ds_read_b64_tr_b16 v[234:235], v246 offset:17440
	ds_read_b64_tr_b16 v[232:233], v246 offset:22016
	ds_read_b64_tr_b16 v[238:239], v246 offset:26624
	ds_read_b64_tr_b16 v[240:241], v246 offset:31232
	ds_read_b64_tr_b16 v[236:237], v246 offset:22048
	ds_read_b64_tr_b16 v[242:243], v246 offset:26656
	ds_read_b64_tr_b16 v[244:245], v246 offset:31264
	v_exp_f32_e64 v95, -v94
	v_mov_b32_e32 v82, v70
	v_mov_b32_e32 v83, v66
	v_mov_b32_e32 v66, v71
	v_mov_b32_e32 v70, v72
	v_mov_b32_e32 v71, v68
	v_mov_b32_e32 v68, v73
	v_pk_add_f32 v[66:67], v[82:83], v[66:67]
	v_pk_add_f32 v[68:69], v[70:71], v[68:69]
	v_mul_f32_e32 v106, v116, v95
	v_pk_add_f32 v[66:67], v[66:67], v[68:69]
	v_add_f32_e32 v117, v213, v94
	v_sub_f32_e32 v65, v49, v94
	v_sub_f32_e32 v64, v48, v94
	v_sub_f32_e32 v63, v47, v94
	v_sub_f32_e32 v62, v46, v94
	v_sub_f32_e32 v77, v53, v94
	v_sub_f32_e32 v76, v52, v94
	v_sub_f32_e32 v75, v51, v94
	v_sub_f32_e32 v74, v50, v94
	v_sub_f32_e32 v81, v57, v94
	v_sub_f32_e32 v80, v56, v94
	v_sub_f32_e32 v79, v55, v94
	v_sub_f32_e32 v78, v54, v94
	v_sub_f32_e32 v93, v61, v94
	v_sub_f32_e32 v92, v60, v94
	v_sub_f32_e32 v91, v59, v94
	v_sub_f32_e32 v90, v58, v94
	v_pk_fma_f32 v[158:159], v[156:157], v[106:107], v[66:67] op_sel_hi:[1,0,1]
	v_pk_mul_f32 v[68:69], v[154:155], v[106:107] op_sel_hi:[1,0]
	v_pk_mul_f32 v[66:67], v[152:153], v[106:107] op_sel_hi:[1,0]
	v_pk_mul_f32 v[72:73], v[150:151], v[106:107] op_sel_hi:[1,0]
	v_pk_mul_f32 v[70:71], v[148:149], v[106:107] op_sel_hi:[1,0]
	v_pk_mul_f32 v[84:85], v[146:147], v[106:107] op_sel_hi:[1,0]
	v_pk_mul_f32 v[82:83], v[144:145], v[106:107] op_sel_hi:[1,0]
	v_pk_mul_f32 v[88:89], v[138:139], v[106:107] op_sel_hi:[1,0]
	v_pk_mul_f32 v[86:87], v[136:137], v[106:107] op_sel_hi:[1,0]
	v_pk_mul_f32 v[96:97], v[134:135], v[106:107] op_sel_hi:[1,0]
	v_pk_mul_f32 v[94:95], v[132:133], v[106:107] op_sel_hi:[1,0]
	v_pk_mul_f32 v[100:101], v[130:131], v[106:107] op_sel_hi:[1,0]
	v_pk_mul_f32 v[98:99], v[128:129], v[106:107] op_sel_hi:[1,0]
	v_pk_mul_f32 v[104:105], v[126:127], v[106:107] op_sel_hi:[1,0]
	v_pk_mul_f32 v[102:103], v[124:125], v[106:107] op_sel_hi:[1,0]
	v_pk_mul_f32 v[108:109], v[4:5], v[106:107] op_sel_hi:[1,0]
	v_pk_mul_f32 v[106:107], v[122:123], v[106:107] op_sel_hi:[1,0]
	s_setprio 1
	s_waitcnt lgkmcnt(5)
	v_mfma_f32_16x16x32_bf16 v[66:69], v[230:233], v[214:217], v[66:69]
	v_mfma_f32_16x16x32_bf16 v[70:73], v[230:233], v[218:221], v[70:73]
	s_waitcnt lgkmcnt(2)
	v_mfma_f32_16x16x32_bf16 v[82:85], v[234:237], v[214:217], v[82:85]
	v_mfma_f32_16x16x32_bf16 v[230:233], v[234:237], v[218:221], v[86:89]
	v_mfma_f32_16x16x32_bf16 v[66:69], v[238:241], v[222:225], v[66:69]
	v_mfma_f32_16x16x32_bf16 v[86:89], v[238:241], v[226:229], v[70:73]
	s_waitcnt lgkmcnt(0)
	v_mfma_f32_16x16x32_bf16 v[70:73], v[242:245], v[222:225], v[82:85]
	v_mfma_f32_16x16x32_bf16 v[82:85], v[242:245], v[226:229], v[230:233]
	s_setprio 0
	s_nop 1
	ds_read_b64_tr_b16 v[230:231], v246 offset:17472
	ds_read_b64_tr_b16 v[234:235], v246 offset:17504
	ds_read_b64_tr_b16 v[232:233], v246 offset:22080
	ds_read_b64_tr_b16 v[236:237], v246 offset:22112
	ds_read_b64_tr_b16 v[238:239], v246 offset:26688
	ds_read_b64_tr_b16 v[240:241], v246 offset:31296
	ds_read_b64_tr_b16 v[244:245], v246 offset:31328
	ds_read_b64_tr_b16 v[242:243], v246 offset:26720
	s_setprio 1
	s_waitcnt lgkmcnt(5)
	v_mfma_f32_16x16x32_bf16 v[94:97], v[230:233], v[214:217], v[94:97]
	v_mfma_f32_16x16x32_bf16 v[98:101], v[230:233], v[218:221], v[98:101]
	s_waitcnt lgkmcnt(4)
	v_mfma_f32_16x16x32_bf16 v[102:105], v[234:237], v[214:217], v[102:105]
	v_mfma_f32_16x16x32_bf16 v[214:217], v[234:237], v[218:221], v[106:109]
	s_waitcnt lgkmcnt(2)
	v_mfma_f32_16x16x32_bf16 v[94:97], v[238:241], v[222:225], v[94:97]
	v_mfma_f32_16x16x32_bf16 v[106:109], v[238:241], v[226:229], v[98:101]
	s_waitcnt lgkmcnt(0)
	v_mfma_f32_16x16x32_bf16 v[98:101], v[242:245], v[222:225], v[102:105]
	v_mfma_f32_16x16x32_bf16 v[102:105], v[242:245], v[226:229], v[214:217]
	s_setprio 0
	s_cbranch_execnz .LBB0_1409

; #define LAS __attribute__((address_space(3)))
; DI float fast_exp2(float x) { return __builtin_amdgcn_exp2f(x); }
; DI void at_exp(f32x4 (&s1)[4], f32x4 (&s2)[4], float& ps1, float& ps2) {
;     f32x4 a1 = (f32x4){0.f, 0.f, 0.f, 0.f}, a2 = a1;
; #pragma unroll
;     for (int k4 = 0; k4 < 4; ++k4) {
; #pragma unroll
;         for (int j = 0; j < 4; ++j) { s1[k4][j] = fast_exp2(s1[k4][j]); s2[k4][j] = fast_exp2(s2[k4][j]); }
;         a1 = a1 + s1[k4]; a2 = a2 + s2[k4]; }
;     ps1 = (a1[0] + a1[1]) + (a1[2] + a1[3]); ps2 = (a2[0] + a2[1]) + (a2[2] + a2[3]);
; }
; DI void at_pv(AtState& S, const f32x4 (&s1)[4], const f32x4 (&s2)[4], float alpha, float ps1, float ps2, const LAS unsigned char* buf, int hh, int fq, int tq, int tp) {
;     S.l1 = S.l1 * alpha + ps1; S.l2 = S.l2 * alpha + ps2;
; #pragma unroll
;     for (int dt = 0; dt < 4; ++dt) { S.O1[dt] = S.O1[dt] * alpha; S.O2[dt] = S.O2[dt] * alpha; }
;     bf16x8 p1[2], p2[2];
; #pragma unroll
;     for (int s = 0; s < 2; ++s) { p1[s] = packp(s1[2 * s], s1[2 * s + 1]); p2[s] = packp(s2[2 * s], s2[2 * s + 1]); }
; #pragma unroll
;     for (int dh = 0; dh < 2; ++dh) {
;         bf16x8 vt[2][2];
; #pragma unroll
;         for (int d2 = 0; d2 < 2; ++d2)
; #pragma unroll
;             for (int s = 0; s < 2; ++s) { const int dt = 2 * dh + d2; const LAS unsigned char* vr = buf + AT_V + (32 * s + 4 * fq + tq) * 288 + (hh * 64 + 16 * dt + 4 * tp) * 2; vt[d2][s] = cat44(tr4(vr), tr4(vr + 16 * 288)); }
;         __builtin_amdgcn_s_setprio(1);
; #pragma unroll
;         for (int s = 0; s < 2; ++s)
; #pragma unroll
; template <int VAR>
; DI void attn_tile(AtState& S, const LAS unsigned char* buf, const bf16x8 q1, const bf16x8 q2, int kt, bool diag, int qpos0, int qpos_l, float slope2, float adv, float decay, int hh, int fr, int fq) {
;     ...
;         const float nref = fmaxf(S.ref, mx);
;         const float alpha = fast_exp2(S.ref - nref); S.ref = nref;
; #pragma unroll
;         for (int k4 = 0; k4 < 4; ++k4) { s1[k4] = s1[k4] - nref; s2[k4] = s2[k4] - nref; }
;         if (kt == 0) { const float c0 = -slope2 * (float)qpos0 - S.ref;
; #pragma unroll
;             for (int k4 = 0; k4 < 4; ++k4)
; #pragma unroll
;                 for (int j = 0; j < 4; ++j) S.cinit[k4][j] = slope2 * (float)(16 * k4 + j - ql) + c0; }
;         at_exp(s1, s2, ps1, ps2);
;         at_pv(S, s1, s2, alpha, ps1, ps2, buf, hh, fq, tq, tp);
.LBB0_1413:
	v_sub_f32_e32 v63, v94, v117
	v_sub_f32_e32 v69, v92, v117
	v_sub_f32_e32 v70, v90, v117
	v_sub_f32_e32 v3, v3, v117
	v_sub_f32_e32 v71, v93, v117
	v_sub_f32_e32 v72, v91, v117
	v_sub_f32_e32 v73, v89, v117
	v_sub_f32_e32 v78, v88, v117
	v_sub_f32_e32 v79, v102, v117
	v_sub_f32_e32 v80, v100, v117
	v_sub_f32_e32 v81, v98, v117
	v_sub_f32_e32 v83, v96, v117
	v_sub_f32_e32 v90, v101, v117
	v_sub_f32_e32 v91, v99, v117
	v_sub_f32_e32 v92, v97, v117
	v_sub_f32_e32 v93, v95, v117
	v_sub_f32_e32 v99, v109, v117
	v_sub_f32_e32 v100, v108, v117
	v_exp_f32_e32 v84, v3
	v_exp_f32_e32 v86, v78
	v_exp_f32_e32 v85, v70
	v_exp_f32_e32 v87, v73
	v_exp_f32_e32 v88, v69
	v_exp_f32_e32 v89, v63
	v_exp_f32_e32 v108, v72
	v_exp_f32_e32 v109, v71
	v_sub_f32_e32 v94, v106, v117
	v_sub_f32_e32 v95, v105, v117
	v_sub_f32_e32 v96, v104, v117
	v_sub_f32_e32 v97, v103, v117
	v_sub_f32_e32 v77, v77, v117
	v_sub_f32_e32 v76, v76, v117
	v_sub_f32_e32 v75, v75, v117
	v_sub_f32_e32 v74, v74, v117
	v_sub_f32_e32 v101, v107, v117
	v_exp_f32_e32 v104, v83
	v_exp_f32_e32 v162, v93
	v_exp_f32_e32 v105, v81
	v_exp_f32_e32 v106, v80
	v_exp_f32_e32 v107, v79
	v_exp_f32_e32 v164, v91
	v_exp_f32_e32 v165, v90
	v_exp_f32_e32 v163, v92
	v_sub_f32_e32 v98, v68, v117
	v_sub_f32_e32 v102, v65, v117
	v_sub_f32_e32 v103, v64, v117
	v_sub_f32_e32 v158, v67, v117
	v_sub_f32_e32 v159, v66, v117
	v_exp_f32_e32 v166, v97
	v_exp_f32_e32 v168, v74
	v_exp_f32_e32 v167, v96
	v_exp_f32_e32 v169, v75
	v_exp_f32_e32 v170, v95
	v_exp_f32_e32 v171, v94
	v_exp_f32_e32 v172, v76
	v_exp_f32_e32 v173, v77
	v_sub_f32_e32 v62, v212, v117
	v_exp_f32_e32 v174, v101
	v_exp_f32_e32 v176, v159
	v_exp_f32_e32 v175, v100
	v_exp_f32_e32 v178, v99
	v_exp_f32_e32 v179, v98
	v_exp_f32_e32 v180, v103
	v_exp_f32_e32 v181, v102
	v_exp_f32_e32 v177, v158
	v_exp_f32_e32 v82, v62
	v_pk_add_f32 v[64:65], v[106:107], v[88:89]
	v_pk_add_f32 v[62:63], v[104:105], v[84:85]
	v_pk_add_f32 v[68:69], v[164:165], v[108:109]
	v_pk_add_f32 v[66:67], v[162:163], v[86:87]
	v_pk_add_f32 v[62:63], v[166:167], v[62:63]
	v_pk_add_f32 v[64:65], v[170:171], v[64:65]
	v_pk_add_f32 v[66:67], v[168:169], v[66:67]
	v_pk_add_f32 v[68:69], v[172:173], v[68:69]
	v_pk_add_f32 v[64:65], v[178:179], v[64:65]
	v_pk_add_f32 v[62:63], v[174:175], v[62:63]
	v_pk_add_f32 v[68:69], v[180:181], v[68:69]
	v_pk_add_f32 v[66:67], v[176:177], v[66:67]
	v_mov_b32_e32 v71, v62
	v_mov_b32_e32 v70, v66
	v_mov_b32_e32 v62, v67
	v_mov_b32_e32 v66, v68
	v_mov_b32_e32 v67, v64
	v_mov_b32_e32 v64, v69
	v_pk_add_f32 v[62:63], v[70:71], v[62:63]
	v_pk_add_f32 v[64:65], v[66:67], v[64:65]
	v_add3_u32 v3, s28, v208, v209
	v_pk_add_f32 v[62:63], v[62:63], v[64:65]
	v_pk_mul_f32 v[64:65], v[154:155], v[82:83] op_sel_hi:[1,0]
	v_pk_fma_f32 v[158:159], v[156:157], v[82:83], v[62:63] op_sel_hi:[1,0,1]
	v_pk_mul_f32 v[62:63], v[152:153], v[82:83] op_sel_hi:[1,0]
	v_pk_mul_f32 v[68:69], v[150:151], v[82:83] op_sel_hi:[1,0]
	v_pk_mul_f32 v[66:67], v[148:149], v[82:83] op_sel_hi:[1,0]
	v_pk_mul_f32 v[72:73], v[146:147], v[82:83] op_sel_hi:[1,0]
	v_pk_mul_f32 v[70:71], v[144:145], v[82:83] op_sel_hi:[1,0]
	v_pk_mul_f32 v[76:77], v[138:139], v[82:83] op_sel_hi:[1,0]
	v_pk_mul_f32 v[74:75], v[136:137], v[82:83] op_sel_hi:[1,0]
	v_pk_mul_f32 v[80:81], v[134:135], v[82:83] op_sel_hi:[1,0]
	v_pk_mul_f32 v[78:79], v[132:133], v[82:83] op_sel_hi:[1,0]
	v_pk_mul_f32 v[92:93], v[130:131], v[82:83] op_sel_hi:[1,0]
	v_pk_mul_f32 v[90:91], v[128:129], v[82:83] op_sel_hi:[1,0]
	v_pk_mul_f32 v[96:97], v[126:127], v[82:83] op_sel_hi:[1,0]
	v_pk_mul_f32 v[94:95], v[124:125], v[82:83] op_sel_hi:[1,0]
	v_pk_mul_f32 v[100:101], v[4:5], v[82:83] op_sel_hi:[1,0]
	v_pk_mul_f32 v[98:99], v[122:123], v[82:83] op_sel_hi:[1,0]
	v_cvt_pk_bf16_f32 v102, v84, v85
	v_cvt_pk_bf16_f32 v103, v88, v89
	v_cvt_pk_bf16_f32 v104, v104, v105
	v_cvt_pk_bf16_f32 v105, v106, v107
	v_cvt_pk_bf16_f32 v106, v86, v87
	ds_read_b64_tr_b16 v[82:83], v3 offset:17408
	ds_read_b64_tr_b16 v[86:87], v3 offset:17440
	ds_read_b64_tr_b16 v[84:85], v3 offset:22016
	ds_read_b64_tr_b16 v[88:89], v3 offset:22048
	ds_read_b64_tr_b16 v[126:127], v3 offset:26624
	ds_read_b64_tr_b16 v[128:129], v3 offset:31232
	ds_read_b64_tr_b16 v[132:133], v3 offset:31264
	ds_read_b64_tr_b16 v[130:131], v3 offset:26656
	v_cvt_pk_bf16_f32 v107, v108, v109
	v_cvt_pk_bf16_f32 v108, v162, v163
	v_cvt_pk_bf16_f32 v109, v164, v165
	v_cvt_pk_bf16_f32 v122, v166, v167
	v_cvt_pk_bf16_f32 v123, v170, v171
	v_cvt_pk_bf16_f32 v124, v174, v175
	v_cvt_pk_bf16_f32 v125, v178, v179
	v_cvt_pk_bf16_f32 v134, v168, v169
	v_cvt_pk_bf16_f32 v135, v172, v173
	v_cvt_pk_bf16_f32 v136, v176, v177
	v_cvt_pk_bf16_f32 v137, v180, v181
	s_setprio 1
	s_waitcnt lgkmcnt(5)
	v_mfma_f32_16x16x32_bf16 v[62:65], v[82:85], v[102:105], v[62:65]
	v_mfma_f32_16x16x32_bf16 v[82:85], v[82:85], v[106:109], v[66:69]
	s_waitcnt lgkmcnt(4)
	v_mfma_f32_16x16x32_bf16 v[70:73], v[86:89], v[102:105], v[70:73]
	v_mfma_f32_16x16x32_bf16 v[74:77], v[86:89], v[106:109], v[74:77]
	s_waitcnt lgkmcnt(2)
	v_mfma_f32_16x16x32_bf16 v[66:69], v[126:129], v[122:125], v[62:65]
	v_mfma_f32_16x16x32_bf16 v[86:89], v[126:129], v[134:137], v[82:85]
	s_waitcnt lgkmcnt(0)
	v_mfma_f32_16x16x32_bf16 v[70:73], v[130:133], v[122:125], v[70:73]
	v_mfma_f32_16x16x32_bf16 v[82:85], v[130:133], v[134:137], v[74:77]
	s_setprio 0
	ds_read_b64_tr_b16 v[62:63], v3 offset:17472
	s_nop 0
	ds_read_b64_tr_b16 v[74:75], v3 offset:17504
	ds_read_b64_tr_b16 v[64:65], v3 offset:22080
	ds_read_b64_tr_b16 v[76:77], v3 offset:22112
	ds_read_b64_tr_b16 v[126:127], v3 offset:26688
	ds_read_b64_tr_b16 v[128:129], v3 offset:31296
	ds_read_b64_tr_b16 v[132:133], v3 offset:31328
	ds_read_b64_tr_b16 v[130:131], v3 offset:26720
	s_setprio 1
	s_waitcnt lgkmcnt(5)
	v_mfma_f32_16x16x32_bf16 v[78:81], v[62:65], v[102:105], v[78:81]
	v_mfma_f32_16x16x32_bf16 v[62:65], v[62:65], v[106:109], v[90:93]
	s_waitcnt lgkmcnt(4)
	v_mfma_f32_16x16x32_bf16 v[90:93], v[74:77], v[102:105], v[94:97]
	v_mfma_f32_16x16x32_bf16 v[74:77], v[74:77], v[106:109], v[98:101]
	s_waitcnt lgkmcnt(2)
	v_mfma_f32_16x16x32_bf16 v[94:97], v[126:129], v[122:125], v[78:81]
	v_mfma_f32_16x16x32_bf16 v[106:109], v[126:129], v[134:137], v[62:65]
	s_waitcnt lgkmcnt(0)
	v_mfma_f32_16x16x32_bf16 v[98:101], v[130:133], v[122:125], v[90:93]
	v_mfma_f32_16x16x32_bf16 v[102:105], v[130:133], v[134:137], v[74:77]
	s_setprio 0
	v_mov_b64_e32 v[64:65], v[48:49]
	s_nop 0
	v_mov_b64_e32 v[76:77], v[52:53]
	v_mov_b64_e32 v[80:81], v[56:57]
	v_mov_b64_e32 v[92:93], v[60:61]
	v_mov_b64_e32 v[62:63], v[46:47]
	v_mov_b64_e32 v[74:75], v[50:51]
	v_mov_b64_e32 v[78:79], v[54:55]
	v_mov_b64_e32 v[90:91], v[58:59]

; template <int VAR>
; DI void attn_segment(const Args& a, const Frame& F, int l, int qrow0, int qpos0, int hp, int ntile, int nf32, const float* ck, const float* cv, int prow0) {
;     ...
;     float l1 = S.l1, l2 = S.l2;
;     l1 += __shfl_xor(l1, 16); l1 += __shfl_xor(l1, 32); l2 += __shfl_xor(l2, 16); l2 += __shfl_xor(l2, 32);
;     const float lam = ((const float*)(sm + S_LAM))[0], lam_init = ((const float*)(sm + S_LAM))[1];
;     const float i1 = 1.f / l1, i2 = lam / l2;
;     float ss = 0.f;
; #pragma unroll
;     for (int dt = 0; dt < 4; ++dt)
; #pragma unroll
;         for (int j = 0; j < 4; ++j) { const float o = S.O1[dt][j] * i1 - S.O2[dt][j] * i2; S.O1[dt][j] = o; ss += o * o; }
;     ss += __shfl_xor(ss, 16); ss += __shfl_xor(ss, 32);
;     const float rs = (1.f - lam_init) / sqrtf(ss * (1.f / 64.f) + EPS);
.LBB0_1417:
	global_load_dword v3, v2, s[8:9]
	v_and_b32_e32 v5, 64, v198
	v_xor_b32_e32 v4, 16, v198
	v_add_u32_e32 v5, 64, v5
	v_cmp_lt_i32_e32 vcc, v4, v5
	s_waitcnt vmcnt(8)
	v_xor_b32_e32 v6, 32, v198
	v_cndmask_b32_e32 v4, v198, v4, vcc
	s_waitcnt vmcnt(1)
	v_lshlrev_b32_e32 v36, 2, v4
	v_mov_b32_e32 v4, v159
	v_mov_b32_e32 v254, v159
	s_nop 1
	v_permlane16_swap_b32_e32 v4, v254
	s_nop 1
	v_mov_b32_dpp v4, v254 quad_perm:[0,1,2,3] row_mask:0x5 bank_mask:0xf
	v_cmp_lt_i32_e32 vcc, v6, v5
	s_waitcnt lgkmcnt(0)
	v_add_f32_e32 v4, v159, v4
	v_cndmask_b32_e32 v5, v198, v6, vcc
	v_lshlrev_b32_e32 v37, 2, v5
	v_mov_b32_e32 v6, v4
	v_mov_b32_e32 v255, v4
	s_nop 1
	v_permlane32_swap_b32_e32 v6, v255
	s_nop 1
	v_mov_b32_dpp v6, v255 quad_perm:[0,1,2,3] row_mask:0x3 bank_mask:0xf
	v_mov_b32_e32 v5, v158
	v_mov_b32_e32 v254, v158
	s_nop 1
	v_permlane16_swap_b32_e32 v5, v254
	s_nop 1
	v_mov_b32_dpp v5, v254 quad_perm:[0,1,2,3] row_mask:0x5 bank_mask:0xf
	s_waitcnt lgkmcnt(0)
	v_add_f32_e32 v4, v4, v6
	s_waitcnt lgkmcnt(0)
	v_add_f32_e32 v5, v158, v5
	v_div_scale_f32 v6, s[0:1], v4, v4, 1.0
	v_mov_b32_e32 v7, v5
	v_mov_b32_e32 v255, v5
	s_nop 1
	v_permlane32_swap_b32_e32 v7, v255
	s_nop 1
	v_mov_b32_dpp v7, v255 quad_perm:[0,1,2,3] row_mask:0x3 bank_mask:0xf
	v_rcp_f32_e32 v8, v6
	s_waitcnt lgkmcnt(0)
	v_add_f32_e32 v5, v5, v7
	v_fma_f32 v9, -v6, v8, 1.0
	v_div_scale_f32 v7, vcc, 1.0, v4, 1.0
	v_fmac_f32_e32 v8, v9, v8
	v_mul_f32_e32 v9, v7, v8
	v_fma_f32 v10, -v6, v9, v7
	v_fmac_f32_e32 v9, v10, v8
	v_fma_f32 v6, -v6, v9, v7
	v_div_fmas_f32 v6, v6, v8, v9
	v_div_fixup_f32 v4, v6, v4, 1.0
	s_waitcnt vmcnt(0)
	v_div_scale_f32 v7, s[0:1], v5, v5, v3
	v_rcp_f32_e32 v8, v7
	v_div_scale_f32 v6, vcc, v3, v5, v3
	v_fma_f32 v9, -v7, v8, 1.0
	v_fmac_f32_e32 v8, v9, v8
	v_mul_f32_e32 v9, v6, v8
	v_fma_f32 v10, -v7, v9, v6
	v_fmac_f32_e32 v9, v10, v8
	v_fma_f32 v6, -v7, v9, v6
	v_div_fmas_f32 v6, v6, v8, v9
	v_div_fixup_f32 v6, v6, v5, v3
	v_pk_mul_f32 v[8:9], v[86:87], v[6:7] op_sel_hi:[1,0]
	v_pk_mul_f32 v[10:11], v[88:89], v[6:7] op_sel_hi:[1,0]
	v_pk_mul_f32 v[12:13], v[82:83], v[6:7] op_sel_hi:[1,0]
	v_pk_mul_f32 v[20:21], v[84:85], v[6:7] op_sel_hi:[1,0]
	v_pk_fma_f32 v[18:19], v[66:67], v[4:5], v[8:9] op_sel_hi:[1,0,1] neg_lo:[0,0,1] neg_hi:[0,0,1]
	v_pk_mul_f32 v[22:23], v[106:107], v[6:7] op_sel_hi:[1,0]
	v_pk_fma_f32 v[16:17], v[68:69], v[4:5], v[10:11] op_sel_hi:[1,0,1] neg_lo:[0,0,1] neg_hi:[0,0,1]
	v_pk_fma_f32 v[14:15], v[70:71], v[4:5], v[12:13] op_sel_hi:[1,0,1] neg_lo:[0,0,1] neg_hi:[0,0,1]
	v_pk_fma_f32 v[12:13], v[72:73], v[4:5], v[20:21] op_sel_hi:[1,0,1] neg_lo:[0,0,1] neg_hi:[0,0,1]
	v_pk_mul_f32 v[20:21], v[18:19], v[18:19]
	v_pk_fma_f32 v[10:11], v[94:95], v[4:5], v[22:23] op_sel_hi:[1,0,1] neg_lo:[0,0,1] neg_hi:[0,0,1]
	v_pk_mul_f32 v[22:23], v[16:17], v[16:17]
	v_add_f32_e32 v3, v20, v21
	v_pk_mul_f32 v[24:25], v[108:109], v[6:7] op_sel_hi:[1,0]
	v_add_f32_e32 v3, v22, v3
	v_pk_fma_f32 v[8:9], v[96:97], v[4:5], v[24:25] op_sel_hi:[1,0,1] neg_lo:[0,0,1] neg_hi:[0,0,1]
	v_pk_mul_f32 v[24:25], v[14:15], v[14:15]
	v_add_f32_e32 v3, v23, v3
	v_pk_mul_f32 v[26:27], v[102:103], v[6:7] op_sel_hi:[1,0]
	v_add_f32_e32 v3, v24, v3
	v_pk_mul_f32 v[28:29], v[104:105], v[6:7] op_sel_hi:[1,0]
	v_pk_fma_f32 v[6:7], v[98:99], v[4:5], v[26:27] op_sel_hi:[1,0,1] neg_lo:[0,0,1] neg_hi:[0,0,1]
	v_pk_mul_f32 v[26:27], v[12:13], v[12:13]
	v_add_f32_e32 v3, v25, v3
	v_add_f32_e32 v3, v26, v3
	v_pk_fma_f32 v[4:5], v[100:101], v[4:5], v[28:29] op_sel_hi:[1,0,1] neg_lo:[0,0,1] neg_hi:[0,0,1]
	v_pk_mul_f32 v[28:29], v[10:11], v[10:11]
	v_add_f32_e32 v3, v27, v3
	v_add_f32_e32 v3, v28, v3
	v_pk_mul_f32 v[30:31], v[8:9], v[8:9]
	v_add_f32_e32 v3, v29, v3
	v_add_f32_e32 v3, v30, v3
	v_pk_mul_f32 v[32:33], v[6:7], v[6:7]
	v_add_f32_e32 v3, v31, v3
	v_add_f32_e32 v3, v32, v3
	v_pk_mul_f32 v[34:35], v[4:5], v[4:5]
	v_add_f32_e32 v3, v33, v3
	v_add_f32_e32 v3, v34, v3
	v_add_f32_e32 v3, v35, v3
	v_mov_b32_e32 v20, v3
	v_mov_b32_e32 v254, v3
	s_nop 1
	v_permlane16_swap_b32_e32 v20, v254
	s_nop 1
	v_mov_b32_dpp v20, v254 quad_perm:[0,1,2,3] row_mask:0x5 bank_mask:0xf
	s_waitcnt lgkmcnt(0)
	v_add_f32_e32 v3, v3, v20
	v_mov_b32_e32 v20, v3
	v_mov_b32_e32 v255, v3
	s_nop 1
	v_permlane32_swap_b32_e32 v20, v255
	s_nop 1
	v_mov_b32_dpp v20, v255 quad_perm:[0,1,2,3] row_mask:0x3 bank_mask:0xf

; template <int N> DI void wave_sum_n(float (&v)[N]) {
; #pragma unroll
;     for (int o = 1; o < 64; o <<= 1) {
;         float t[N];
; #pragma unroll
;         for (int i = 0; i < N; ++i) t[i] = __shfl_xor(v[i], o);
; #pragma unroll
;         for (int i = 0; i < N; ++i) v[i] += t[i]; }
; }
; template <int MODE>
; DI void norm_phase(const Args& a, const Frame& F, int nslab, float sscale, float* RSTD, const float* SSP) {
;     ...
;         float ss[RB];
; #pragma unroll
;         for (int r = 0; r < RB; ++r) { ss[r] = 0.f;
; #pragma unroll
;             for (int j = 0; j < 4; ++j) ss[r] += (v[r][j][0] * v[r][j][0] + v[r][j][1] * v[r][j][1]) + (v[r][j][2] * v[r][j][2] + v[r][j][3] * v[r][j][3]); }
;         wave_sum_n<RB>(ss);
; #pragma unroll
;         for (int r = 0; r < RB; ++r) if (ok[r]) { const int row = rows[r];
;             const float rstd = 1.f / sqrtf(ss[r] * (1.f / DM) + EPS);
.LBB0_1861:
	v_mul_f32_e32 v60, v19, v19
	s_waitcnt lgkmcnt(0)
	v_mul_f32_e32 v61, v17, v17
	v_fmac_f32_e32 v60, v18, v18
	v_fmac_f32_e32 v61, v16, v16
	v_add_f32_e32 v60, v60, v61
	v_mul_f32_e32 v61, v23, v23
	v_mul_f32_e32 v62, v21, v21
	v_fmac_f32_e32 v61, v22, v22
	v_fmac_f32_e32 v62, v20, v20
	v_add_f32_e32 v61, v61, v62
	v_add_f32_e32 v60, v61, v60
	v_mul_f32_e32 v61, v27, v27
	v_mul_f32_e32 v62, v25, v25
	v_fmac_f32_e32 v61, v26, v26
	v_fmac_f32_e32 v62, v24, v24
	v_add_f32_e32 v61, v61, v62
	v_add_f32_e32 v60, v61, v60
	v_mul_f32_e32 v61, v15, v15
	v_mul_f32_e32 v62, v13, v13
	v_fmac_f32_e32 v61, v14, v14
	v_fmac_f32_e32 v62, v12, v12
	v_add_f32_e32 v61, v61, v62
	v_add_f32_e32 v60, v61, v60
	v_mul_f32_e32 v61, v51, v51
	v_mul_f32_e32 v62, v49, v49
	v_fmac_f32_e32 v61, v50, v50
	v_fmac_f32_e32 v62, v48, v48
	v_add_f32_e32 v61, v61, v62
	v_mul_f32_e32 v62, v47, v47
	v_mul_f32_e32 v63, v45, v45
	v_fmac_f32_e32 v62, v46, v46
	v_fmac_f32_e32 v63, v44, v44
	v_add_f32_e32 v62, v62, v63
	v_add_f32_e32 v61, v62, v61
	v_mul_f32_e32 v62, v43, v43
	v_mul_f32_e32 v63, v41, v41
	v_fmac_f32_e32 v62, v42, v42
	v_fmac_f32_e32 v63, v40, v40
	v_add_f32_e32 v62, v62, v63
	v_add_f32_e32 v61, v61, v62
	v_mul_f32_e32 v62, v39, v39
	v_mul_f32_e32 v63, v37, v37
	v_fmac_f32_e32 v62, v38, v38
	v_fmac_f32_e32 v63, v36, v36
	v_add_f32_e32 v62, v62, v63
	v_add_f32_e32 v61, v61, v62
	v_mul_f32_e32 v62, v59, v59
	v_mul_f32_e32 v63, v57, v57
	v_fmac_f32_e32 v62, v58, v58
	v_fmac_f32_e32 v63, v56, v56
	v_add_f32_e32 v62, v62, v63
	v_mul_f32_e32 v63, v55, v55
	v_mul_f32_e32 v64, v53, v53
	v_fmac_f32_e32 v63, v54, v54
	v_fmac_f32_e32 v64, v52, v52
	v_add_f32_e32 v63, v63, v64
	v_add_f32_e32 v62, v62, v63
	v_mul_f32_e32 v63, v35, v35
	v_mul_f32_e32 v64, v33, v33
	v_fmac_f32_e32 v63, v34, v34
	v_fmac_f32_e32 v64, v32, v32
	v_add_f32_e32 v63, v63, v64
	v_add_f32_e32 v62, v62, v63
	v_mul_f32_e32 v63, v31, v31
	v_mul_f32_e32 v64, v29, v29
	v_fmac_f32_e32 v63, v30, v30
	v_fmac_f32_e32 v64, v28, v28
	v_add_f32_e32 v63, v63, v64
	v_add_f32_e32 v62, v62, v63
	v_mov_b32_dpp v63, v60 quad_perm:[1,0,3,2] row_mask:0xf bank_mask:0xf
	v_mov_b32_dpp v64, v61 quad_perm:[1,0,3,2] row_mask:0xf bank_mask:0xf
	v_mov_b32_dpp v65, v62 quad_perm:[1,0,3,2] row_mask:0xf bank_mask:0xf
	s_waitcnt lgkmcnt(0)
	v_add_f32_e32 v60, v60, v63
	s_waitcnt lgkmcnt(0)
	v_add_f32_e32 v61, v61, v64
	s_waitcnt lgkmcnt(0)
	v_add_f32_e32 v62, v62, v65
	v_mov_b32_dpp v63, v60 quad_perm:[2,3,0,1] row_mask:0xf bank_mask:0xf
	v_mov_b32_dpp v64, v61 quad_perm:[2,3,0,1] row_mask:0xf bank_mask:0xf
	v_mov_b32_dpp v65, v62 quad_perm:[2,3,0,1] row_mask:0xf bank_mask:0xf
	s_waitcnt lgkmcnt(0)
	v_add_f32_e32 v60, v60, v63
	s_waitcnt lgkmcnt(0)
	v_add_f32_e32 v61, v61, v64
	s_waitcnt lgkmcnt(0)
	v_add_f32_e32 v62, v62, v65
	v_mov_b32_dpp v63, v60 row_half_mirror row_mask:0xf bank_mask:0xf
	v_mov_b32_dpp v64, v61 row_half_mirror row_mask:0xf bank_mask:0xf
	v_mov_b32_dpp v65, v62 row_half_mirror row_mask:0xf bank_mask:0xf
	s_waitcnt lgkmcnt(0)
	v_add_f32_e32 v60, v60, v63
	s_waitcnt lgkmcnt(0)
	v_add_f32_e32 v61, v61, v64
	s_waitcnt lgkmcnt(0)
	v_add_f32_e32 v62, v62, v65
	v_mov_b32_dpp v63, v60 row_ror:8 row_mask:0xf bank_mask:0xf
	v_mov_b32_dpp v64, v61 row_ror:8 row_mask:0xf bank_mask:0xf
	v_mov_b32_dpp v65, v62 row_ror:8 row_mask:0xf bank_mask:0xf
	s_waitcnt lgkmcnt(0)
	v_add_f32_e32 v60, v60, v63
	s_waitcnt lgkmcnt(0)
	v_add_f32_e32 v61, v61, v64
	s_waitcnt lgkmcnt(0)
	v_add_f32_e32 v63, v62, v65
	v_mov_b32_e32 v62, v60
	v_mov_b32_e32 v254, v60
	s_nop 1
	v_permlane16_swap_b32_e32 v62, v254
	s_nop 1
	v_mov_b32_dpp v62, v254 quad_perm:[0,1,2,3] row_mask:0x5 bank_mask:0xf
	v_mov_b32_e32 v65, v61
	v_mov_b32_e32 v255, v61
	s_nop 1
	v_permlane16_swap_b32_e32 v65, v255
	s_nop 1
	v_mov_b32_dpp v65, v255 quad_perm:[0,1,2,3] row_mask:0x5 bank_mask:0xf
	v_mov_b32_e32 v66, v63
	v_mov_b32_e32 v254, v63
	s_nop 1
	v_permlane16_swap_b32_e32 v66, v254
	s_nop 1
	v_mov_b32_dpp v66, v254 quad_perm:[0,1,2,3] row_mask:0x5 bank_mask:0xf
	s_waitcnt lgkmcnt(0)
	v_add_f32_e32 v64, v60, v62
	s_waitcnt lgkmcnt(0)
	v_add_f32_e32 v62, v61, v65
	s_waitcnt lgkmcnt(0)
	v_add_f32_e32 v60, v63, v66
	v_mov_b32_e32 v65, v64
	v_mov_b32_e32 v255, v64
	s_nop 1
	v_permlane32_swap_b32_e32 v65, v255
	s_nop 1
	v_mov_b32_dpp v65, v255 quad_perm:[0,1,2,3] row_mask:0x3 bank_mask:0xf
	v_mov_b32_e32 v63, v62
	v_mov_b32_e32 v254, v62
	s_nop 1
	v_permlane32_swap_b32_e32 v63, v254
	s_nop 1
	v_mov_b32_dpp v63, v254 quad_perm:[0,1,2,3] row_mask:0x3 bank_mask:0xf
	v_mov_b32_e32 v61, v60
	v_mov_b32_e32 v255, v60
	s_nop 1
	v_permlane32_swap_b32_e32 v61, v255
	s_nop 1
	v_mov_b32_dpp v61, v255 quad_perm:[0,1,2,3] row_mask:0x3 bank_mask:0xf
	s_and_saveexec_b64 s[16:17], s[2:3]
	s_cbranch_execz .LBB0_1863
	s_waitcnt lgkmcnt(0)
	v_add_f32_e32 v64, v64, v65
	v_fmamk_f32 v64, v64, 0x3a800000, v1
	v_mul_f32_e32 v65, 0x4f800000, v64
	v_cmp_gt_f32_e32 vcc, s67, v64
	s_nop 1
	v_cndmask_b32_e32 v64, v64, v65, vcc
	v_sqrt_f32_e32 v65, v64
	s_nop 0
	v_add_u32_e32 v66, -1, v65
	v_fma_f32 v68, -v66, v65, v64
	v_add_u32_e32 v67, 1, v65
	v_cmp_ge_f32_e64 s[4:5], 0, v68
	s_nop 1
	v_cndmask_b32_e64 v66, v65, v66, s[4:5]
	v_fma_f32 v65, -v67, v65, v64
	v_cmp_lt_f32_e64 s[4:5], 0, v65
	s_nop 1
	v_cndmask_b32_e64 v65, v66, v67, s[4:5]
	v_mul_f32_e32 v66, 0x37800000, v65
	v_cndmask_b32_e32 v65, v65, v66, vcc
	v_cmp_class_f32_e32 vcc, v64, v196
	s_nop 1
	v_cndmask_b32_e32 v64, v65, v64, vcc
	v_div_scale_f32 v65, s[4:5], v64, v64, 1.0
	v_rcp_f32_e32 v66, v65
	s_nop 0
	v_fma_f32 v67, -v65, v66, 1.0
	v_fmac_f32_e32 v66, v67, v66
	v_div_scale_f32 v67, vcc, 1.0, v64, 1.0
	v_mul_f32_e32 v68, v67, v66
	v_fma_f32 v69, -v65, v68, v67
	v_fmac_f32_e32 v68, v69, v66
	v_fma_f32 v65, -v65, v68, v67
	v_div_fmas_f32 v65, v65, v66, v68
	v_div_fixup_f32 v64, v65, v64, 1.0
	global_store_dword v2, v64, s[6:7]
; DI unsigned pk2(float lo, float hi) { const f32x2 v = {lo, hi}; return __builtin_bit_cast(unsigned, __builtin_convertvector(v, hwbf16x2)); }
; template <int MODE>
; DI void norm_phase(const Args& a, const Frame& F, int nslab, float sscale, float* RSTD, const float* SSP) {
;     ...
;         for (int r = 0; r < RB; ++r) if (ok[r]) { const int row = rows[r];
;             const float rstd = 1.f / sqrtf(ss[r] * (1.f / DM) + EPS);
;             if (MODE == 2) {
;                 float* o = (row < NP) ? a.out + O_YP + (size_t)row * DM : a.out + O_YS + (size_t)(row - NP) * DM;
; #pragma unroll
;                 for (int j = 0; j < 4; ++j) { const f32x4 g = ((const f32x4*)a.in[I_FINAL])[F.lane + 64 * j]; ((f32x4*)o)[F.lane + 64 * j] = v[r][j] * rstd * g; }
;             } else {
;                 if (F.lane == 0) RSTD[row] = rstd;
; #pragma unroll
;                 for (int j = 0; j < 4; ++j) { u32x2 w; w.x = pk2(v[r][j][0], v[r][j][1]); w.y = pk2(v[r][j][2], v[r][j][3]); ((u32x2*)(X + (size_t)row * DM))[F.lane + 64 * j] = w; }
.LBB0_1863:
	s_or_b64 exec, exec, s[16:17]
	v_cvt_pk_bf16_f32 v18, v18, v19
	v_cvt_pk_bf16_f32 v19, v16, v17
	v_cvt_pk_bf16_f32 v16, v22, v23
	v_cvt_pk_bf16_f32 v17, v20, v21
	global_store_dwordx2 v[6:7], v[16:17], off offset:512
	v_cvt_pk_bf16_f32 v16, v26, v27
	v_cvt_pk_bf16_f32 v17, v24, v25
	v_cvt_pk_bf16_f32 v14, v14, v15
	v_cvt_pk_bf16_f32 v15, v12, v13
	s_andn2_b64 vcc, exec, s[14:15]
	global_store_dwordx2 v[6:7], v[18:19], off
	global_store_dwordx2 v[6:7], v[16:17], off offset:1024
	global_store_dwordx2 v[6:7], v[14:15], off offset:1536
	s_cbranch_vccnz .LBB0_1867
	s_and_saveexec_b64 s[14:15], s[2:3]
	s_cbranch_execz .LBB0_1866
	s_waitcnt lgkmcnt(0)
	v_add_f32_e32 v12, v62, v63
	v_fmamk_f32 v12, v12, 0x3a800000, v1
	v_mul_f32_e32 v13, 0x4f800000, v12
	v_cmp_gt_f32_e32 vcc, s67, v12
	s_nop 1
	v_cndmask_b32_e32 v12, v12, v13, vcc
	v_sqrt_f32_e32 v13, v12
	s_nop 0
	v_add_u32_e32 v14, -1, v13
	v_fma_f32 v16, -v14, v13, v12
	v_add_u32_e32 v15, 1, v13
	v_cmp_ge_f32_e64 s[4:5], 0, v16
	s_nop 1
	v_cndmask_b32_e64 v14, v13, v14, s[4:5]
	v_fma_f32 v13, -v15, v13, v12
	v_cmp_lt_f32_e64 s[4:5], 0, v13
	s_nop 1
	v_cndmask_b32_e64 v13, v14, v15, s[4:5]
	v_mul_f32_e32 v14, 0x37800000, v13
	v_cndmask_b32_e32 v13, v13, v14, vcc
	v_cmp_class_f32_e32 vcc, v12, v196
	s_nop 1
	v_cndmask_b32_e32 v12, v13, v12, vcc
	v_div_scale_f32 v13, s[4:5], v12, v12, 1.0
	v_rcp_f32_e32 v14, v13
	s_lshl_b64 s[4:5], s[12:13], 2
	s_add_u32 s4, s19, s4
	s_addc_u32 s5, s20, s5
	v_fma_f32 v15, -v13, v14, 1.0
	v_fmac_f32_e32 v14, v15, v14
	v_div_scale_f32 v15, vcc, 1.0, v12, 1.0
	v_mul_f32_e32 v16, v15, v14
	v_fma_f32 v17, -v13, v16, v15
	v_fmac_f32_e32 v16, v17, v14
	v_fma_f32 v13, -v13, v16, v15
	v_div_fmas_f32 v13, v13, v14, v16
	v_div_fixup_f32 v12, v13, v12, 1.0
	global_store_dword v2, v12, s[4:5]

; #define MFMA16(a, b, c) __builtin_amdgcn_mfma_f32_16x16x32_bf16((a), (b), (c), 0, 0, 0)
; DI void xattn_unit(const Args& a, const Frame& F, int l, int unit) {
;     ...
;     for (int rr = 0; rr < 4; ++rr) {
;         const int rg = F.wave + rr * NWAVES; if (rg >= nrg) break;
;         const int row = row0 + 16 * rg + fr;
;         bf16x8 qn[4];
;         { const int rgn = rg + NWAVES; const int rown = row0 + 16 * (rgn < nrg ? rgn : rg) + fr;
; #pragma unroll
;           for (int ks = 0; ks < 4; ++ks) qn[ks] = ld8g(Q + (size_t)rown * XW + h * 128 + 32 * ks + 8 * fq); }
;         f32x4 sc[16];
; #pragma unroll
;         for (int k4 = 0; k4 < 4; ++k4) {
; #pragma unroll
;             for (int i = 0; i < 4; ++i) sc[4 * k4 + i] = (f32x4){0.f, 0.f, 0.f, 0.f};
; #pragma unroll
;             for (int ks = 0; ks < 4; ++ks)
; #pragma unroll
;                 for (int i = 0; i < 4; ++i) { const int kb = 4 * k4 + i; sc[kb] = MFMA16(ld8l(F.lds + XA_K + (16 * kb + fr) * 272 + (32 * ks + 8 * fq) * 2), qc[ks], sc[kb]); }
;         }
.LBB0_2040:
	s_cmp_ge_i32 s9, s8
	s_mov_b64 s[0:1], -1
	s_cbranch_scc1 .LBB0_2039
	s_add_i32 s7, s9, 8
	s_cmp_lt_i32 s7, s8
	s_cselect_b32 s0, s7, s9
	v_lshl_add_u32 v4, s0, 4, v94
	v_ashrrev_i32_e32 v5, 31, v4
	v_lshlrev_b64 v[4:5], 10, v[4:5]
	v_lshl_add_u64 v[16:17], v[84:85], 0, v[4:5]
	global_load_dwordx4 v[4:7], v[16:17], off
	global_load_dwordx4 v[8:11], v[16:17], off offset:64
	global_load_dwordx4 v[12:15], v[16:17], off offset:128
	s_nop 0
	global_load_dwordx4 v[16:19], v[16:17], off offset:192
	ds_read_b128 v[36:39], v88
	ds_read_b128 v[52:55], v88 offset:64
	ds_read_b128 v[40:43], v88 offset:4352
	ds_read_b128 v[44:47], v88 offset:8704
	ds_read_b128 v[48:51], v88 offset:13056
	s_mov_b32 s9, s7
	s_waitcnt lgkmcnt(4)
	v_mfma_f32_16x16x32_bf16 v[36:39], v[36:39], v[32:35], 0
	ds_read_b128 v[100:103], v88 offset:34880
	ds_read_b128 v[108:111], v88 offset:60928
	ds_read_b128 v[112:115], v88 offset:65280
	s_waitcnt lgkmcnt(6)
	v_mfma_f32_16x16x32_bf16 v[36:39], v[52:55], v[28:31], v[36:39]
	ds_read_b128 v[52:55], v88 offset:4416
	s_waitcnt lgkmcnt(6)
	v_mfma_f32_16x16x32_bf16 v[40:43], v[40:43], v[32:35], 0
	s_waitcnt lgkmcnt(0)
	v_mfma_f32_16x16x32_bf16 v[40:43], v[52:55], v[28:31], v[40:43]
	ds_read_b128 v[52:55], v88 offset:8768
	v_mfma_f32_16x16x32_bf16 v[44:47], v[44:47], v[32:35], 0
	s_waitcnt lgkmcnt(0)
	v_mfma_f32_16x16x32_bf16 v[44:47], v[52:55], v[28:31], v[44:47]
	ds_read_b128 v[52:55], v88 offset:13120
	v_mfma_f32_16x16x32_bf16 v[48:51], v[48:51], v[32:35], 0
	s_waitcnt lgkmcnt(0)
	v_mfma_f32_16x16x32_bf16 v[48:51], v[52:55], v[28:31], v[48:51]
	ds_read_b128 v[52:55], v88 offset:128
	s_waitcnt lgkmcnt(0)
	v_mfma_f32_16x16x32_bf16 v[36:39], v[52:55], v[24:27], v[36:39]
	ds_read_b128 v[52:55], v88 offset:4480
	s_waitcnt lgkmcnt(0)
	v_mfma_f32_16x16x32_bf16 v[40:43], v[52:55], v[24:27], v[40:43]
	ds_read_b128 v[52:55], v88 offset:8832
	s_waitcnt lgkmcnt(0)
	v_mfma_f32_16x16x32_bf16 v[44:47], v[52:55], v[24:27], v[44:47]
	ds_read_b128 v[52:55], v88 offset:13184
	s_waitcnt lgkmcnt(0)
	v_mfma_f32_16x16x32_bf16 v[48:51], v[52:55], v[24:27], v[48:51]
	ds_read_b128 v[52:55], v88 offset:192
	s_waitcnt lgkmcnt(0)
	v_mfma_f32_16x16x32_bf16 v[76:79], v[52:55], v[20:23], v[36:39]
	s_nop 2
	ds_read_b128 v[36:39], v88 offset:4544
	ds_read_b128 v[52:55], v88 offset:17472
	s_waitcnt lgkmcnt(1)
	v_mfma_f32_16x16x32_bf16 v[80:83], v[36:39], v[20:23], v[40:43]
	ds_read_b128 v[36:39], v88 offset:8896
	s_nop 1
	ds_read_b128 v[40:43], v88 offset:21760
	s_waitcnt lgkmcnt(1)
	v_mfma_f32_16x16x32_bf16 v[68:71], v[36:39], v[20:23], v[44:47]
	ds_read_b128 v[36:39], v88 offset:13248
	s_nop 1
	ds_read_b128 v[44:47], v88 offset:26112
	s_waitcnt lgkmcnt(1)
	v_mfma_f32_16x16x32_bf16 v[72:75], v[36:39], v[20:23], v[48:51]
	ds_read_b128 v[36:39], v88 offset:17408
	s_nop 1
	ds_read_b128 v[48:51], v88 offset:30464
	s_waitcnt lgkmcnt(1)
	v_mfma_f32_16x16x32_bf16 v[36:39], v[36:39], v[32:35], 0
	v_mfma_f32_16x16x32_bf16 v[36:39], v[52:55], v[28:31], v[36:39]
	ds_read_b128 v[52:55], v88 offset:21824
	v_mfma_f32_16x16x32_bf16 v[40:43], v[40:43], v[32:35], 0
	s_waitcnt lgkmcnt(0)
	v_mfma_f32_16x16x32_bf16 v[40:43], v[52:55], v[28:31], v[40:43]
	ds_read_b128 v[52:55], v88 offset:26176
	v_mfma_f32_16x16x32_bf16 v[44:47], v[44:47], v[32:35], 0
	s_waitcnt lgkmcnt(0)
	v_mfma_f32_16x16x32_bf16 v[44:47], v[52:55], v[28:31], v[44:47]
	ds_read_b128 v[52:55], v88 offset:30528
	v_mfma_f32_16x16x32_bf16 v[48:51], v[48:51], v[32:35], 0
	s_waitcnt lgkmcnt(0)
	v_mfma_f32_16x16x32_bf16 v[48:51], v[52:55], v[28:31], v[48:51]
	ds_read_b128 v[52:55], v88 offset:17536
	s_waitcnt lgkmcnt(0)
	v_mfma_f32_16x16x32_bf16 v[36:39], v[52:55], v[24:27], v[36:39]
	ds_read_b128 v[52:55], v88 offset:21888
	s_waitcnt lgkmcnt(0)
	v_mfma_f32_16x16x32_bf16 v[40:43], v[52:55], v[24:27], v[40:43]
	ds_read_b128 v[52:55], v88 offset:26240
	s_waitcnt lgkmcnt(0)
	v_mfma_f32_16x16x32_bf16 v[44:47], v[52:55], v[24:27], v[44:47]
	ds_read_b128 v[52:55], v88 offset:30592
	s_waitcnt lgkmcnt(0)
	v_mfma_f32_16x16x32_bf16 v[48:51], v[52:55], v[24:27], v[48:51]
	ds_read_b128 v[52:55], v88 offset:17600
	s_waitcnt lgkmcnt(0)
	v_mfma_f32_16x16x32_bf16 v[60:63], v[52:55], v[20:23], v[36:39]
	s_nop 2
	ds_read_b128 v[36:39], v88 offset:21952
	s_waitcnt lgkmcnt(0)
	v_mfma_f32_16x16x32_bf16 v[64:67], v[36:39], v[20:23], v[40:43]
	ds_read_b128 v[36:39], v88 offset:26304
	s_nop 1
	ds_read_b128 v[40:43], v88 offset:39168
	s_waitcnt lgkmcnt(1)
	v_mfma_f32_16x16x32_bf16 v[52:55], v[36:39], v[20:23], v[44:47]
	ds_read_b128 v[36:39], v88 offset:30656
	s_nop 1
	ds_read_b128 v[44:47], v88 offset:43520
	s_waitcnt lgkmcnt(1)
	v_mfma_f32_16x16x32_bf16 v[56:59], v[36:39], v[20:23], v[48:51]
	ds_read_b128 v[36:39], v88 offset:34816
	s_nop 1
	ds_read_b128 v[48:51], v88 offset:47872
	s_waitcnt lgkmcnt(1)
	v_mfma_f32_16x16x32_bf16 v[36:39], v[36:39], v[32:35], 0
	v_mfma_f32_16x16x32_bf16 v[36:39], v[100:103], v[28:31], v[36:39]
	ds_read_b128 v[100:103], v88 offset:39232
	v_mfma_f32_16x16x32_bf16 v[40:43], v[40:43], v[32:35], 0
	s_waitcnt lgkmcnt(0)
	v_mfma_f32_16x16x32_bf16 v[40:43], v[100:103], v[28:31], v[40:43]
	ds_read_b128 v[100:103], v88 offset:43584
	v_mfma_f32_16x16x32_bf16 v[44:47], v[44:47], v[32:35], 0
	s_waitcnt lgkmcnt(0)
	v_mfma_f32_16x16x32_bf16 v[44:47], v[100:103], v[28:31], v[44:47]
	ds_read_b128 v[100:103], v88 offset:47936
	v_mfma_f32_16x16x32_bf16 v[48:51], v[48:51], v[32:35], 0
	s_waitcnt lgkmcnt(0)
	v_mfma_f32_16x16x32_bf16 v[48:51], v[100:103], v[28:31], v[48:51]
	ds_read_b128 v[100:103], v88 offset:34944
	s_waitcnt lgkmcnt(0)
	v_mfma_f32_16x16x32_bf16 v[36:39], v[100:103], v[24:27], v[36:39]
	ds_read_b128 v[100:103], v88 offset:39296
	s_waitcnt lgkmcnt(0)
; #define MFMA16(a, b, c) __builtin_amdgcn_mfma_f32_16x16x32_bf16((a), (b), (c), 0, 0, 0)
; DI float max3f(float a, float b, float c) { float r; asm("v_max3_f32 %0, %1, %2, %3" : "=v"(r) : "v"(a), "v"(b), "v"(c)); return r; }
; DI void xattn_unit(const Args& a, const Frame& F, int l, int unit) {
;     ...
;         f32x4 sc[16];
; #pragma unroll
;         for (int k4 = 0; k4 < 4; ++k4) {
; #pragma unroll
;             for (int i = 0; i < 4; ++i) sc[4 * k4 + i] = (f32x4){0.f, 0.f, 0.f, 0.f};
; #pragma unroll
;             for (int ks = 0; ks < 4; ++ks)
; #pragma unroll
;                 for (int i = 0; i < 4; ++i) { const int kb = 4 * k4 + i; sc[kb] = MFMA16(ld8l(F.lds + XA_K + (16 * kb + fr) * 272 + (32 * ks + 8 * fq) * 2), qc[ks], sc[kb]); }
;         }
;         float mx = max3f(sc[0][0], sc[0][1], sc[0][2]); mx = max3f(mx, sc[0][3], sc[0][3]);
; #pragma unroll
;         for (int kb = 1; kb < 16; ++kb) { mx = max3f(mx, sc[kb][0], sc[kb][1]); mx = max3f(mx, sc[kb][2], sc[kb][3]); }
;         mx = fmaxf(mx, __shfl_xor(mx, 16)); mx = fmaxf(mx, __shfl_xor(mx, 32));
	v_mfma_f32_16x16x32_bf16 v[40:43], v[100:103], v[24:27], v[40:43]
	ds_read_b128 v[100:103], v88 offset:43648
	s_waitcnt lgkmcnt(0)
	v_mfma_f32_16x16x32_bf16 v[100:103], v[100:103], v[24:27], v[44:47]
	s_nop 2
	ds_read_b128 v[44:47], v88 offset:48000
	s_waitcnt lgkmcnt(0)
	v_mfma_f32_16x16x32_bf16 v[104:107], v[44:47], v[24:27], v[48:51]
	ds_read_b128 v[44:47], v88 offset:35008
	s_waitcnt lgkmcnt(0)
	v_mfma_f32_16x16x32_bf16 v[44:47], v[44:47], v[20:23], v[36:39]
	s_nop 2
	ds_read_b128 v[36:39], v88 offset:39360
	s_waitcnt lgkmcnt(0)
	v_mfma_f32_16x16x32_bf16 v[48:51], v[36:39], v[20:23], v[40:43]
	ds_read_b128 v[36:39], v88 offset:43712
	s_nop 1
	ds_read_b128 v[40:43], v88 offset:48064
	s_waitcnt lgkmcnt(1)
	v_mfma_f32_16x16x32_bf16 v[36:39], v[36:39], v[20:23], v[100:103]
	s_nop 2
	ds_read_b128 v[100:103], v88 offset:52224
	s_waitcnt lgkmcnt(1)
	v_mfma_f32_16x16x32_bf16 v[40:43], v[40:43], v[20:23], v[104:107]
	s_nop 2
	ds_read_b128 v[104:107], v88 offset:56576
	s_waitcnt lgkmcnt(1)
	v_mfma_f32_16x16x32_bf16 v[100:103], v[100:103], v[32:35], 0
	s_waitcnt lgkmcnt(0)
	v_mfma_f32_16x16x32_bf16 v[104:107], v[104:107], v[32:35], 0
	v_mfma_f32_16x16x32_bf16 v[108:111], v[108:111], v[32:35], 0
	v_mfma_f32_16x16x32_bf16 v[32:35], v[112:115], v[32:35], 0
	ds_read_b128 v[112:115], v88 offset:52288
	s_waitcnt lgkmcnt(0)
	v_mfma_f32_16x16x32_bf16 v[100:103], v[112:115], v[28:31], v[100:103]
	ds_read_b128 v[112:115], v88 offset:56640
	s_waitcnt lgkmcnt(0)
	v_mfma_f32_16x16x32_bf16 v[104:107], v[112:115], v[28:31], v[104:107]
	ds_read_b128 v[112:115], v88 offset:60992
	s_waitcnt lgkmcnt(0)
	v_mfma_f32_16x16x32_bf16 v[108:111], v[112:115], v[28:31], v[108:111]
	ds_read_b128 v[112:115], v88 offset:65344
	s_waitcnt lgkmcnt(0)
	v_mfma_f32_16x16x32_bf16 v[28:31], v[112:115], v[28:31], v[32:35]
	s_nop 2
	ds_read_b128 v[32:35], v88 offset:52352
	s_waitcnt lgkmcnt(0)
	v_mfma_f32_16x16x32_bf16 v[32:35], v[32:35], v[24:27], v[100:103]
	s_nop 2
	ds_read_b128 v[100:103], v88 offset:56704
	s_waitcnt lgkmcnt(0)
	v_mfma_f32_16x16x32_bf16 v[100:103], v[100:103], v[24:27], v[104:107]
	s_nop 2
	ds_read_b128 v[104:107], v88 offset:61056
	s_waitcnt lgkmcnt(0)
	v_mfma_f32_16x16x32_bf16 v[104:107], v[104:107], v[24:27], v[108:111]
	s_nop 2
	ds_read_b128 v[108:111], v88 offset:65408
	s_waitcnt lgkmcnt(0)
	v_mfma_f32_16x16x32_bf16 v[108:111], v[108:111], v[24:27], v[28:31]
	ds_read_b128 v[24:27], v88 offset:52416
	s_waitcnt lgkmcnt(0)
	v_mfma_f32_16x16x32_bf16 v[28:31], v[24:27], v[20:23], v[32:35]
	ds_read_b128 v[24:27], v88 offset:56768
	s_waitcnt lgkmcnt(0)
	v_mfma_f32_16x16x32_bf16 v[32:35], v[24:27], v[20:23], v[100:103]
	ds_read_b128 v[24:27], v88 offset:61120
	s_nop 1
	ds_read_b128 v[100:103], v88 offset:65472
	s_waitcnt lgkmcnt(1)
	v_mfma_f32_16x16x32_bf16 v[24:27], v[24:27], v[20:23], v[104:107]
	s_waitcnt lgkmcnt(0)
	v_mfma_f32_16x16x32_bf16 v[20:23], v[100:103], v[20:23], v[108:111]
	v_max3_f32 v100, v76, v77, v78
	v_and_b32_e32 v102, 64, v198
	v_max3_f32 v100, v100, v79, v79
	v_add_u32_e32 v102, 64, v102
	v_max3_f32 v100, v100, v80, v81
	s_nop 0
	v_max3_f32 v100, v100, v82, v83
	s_nop 0
	v_max3_f32 v100, v100, v68, v69
	s_nop 0
	v_max3_f32 v100, v100, v70, v71
	s_nop 0
	v_max3_f32 v100, v100, v72, v73
	s_nop 0
	v_max3_f32 v100, v100, v74, v75
	s_nop 0
	v_max3_f32 v100, v100, v60, v61
	s_nop 0
	v_max3_f32 v100, v100, v62, v63
	s_nop 0
	v_max3_f32 v100, v100, v64, v65
	s_nop 0
	v_max3_f32 v100, v100, v66, v67
	s_nop 0
	v_max3_f32 v100, v100, v52, v53
	s_nop 0
	v_max3_f32 v100, v100, v54, v55
	s_nop 0
	v_max3_f32 v100, v100, v56, v57
	s_nop 0
	v_max3_f32 v100, v100, v58, v59
	s_nop 0
	v_max3_f32 v100, v100, v44, v45
	s_nop 0
	v_max3_f32 v100, v100, v46, v47
	s_nop 0
	v_max3_f32 v100, v100, v48, v49
	s_nop 0
	v_max3_f32 v100, v100, v50, v51
	s_nop 0
	v_max3_f32 v100, v100, v36, v37
	s_nop 0
	v_max3_f32 v100, v100, v38, v39
	s_nop 0
	v_max3_f32 v100, v100, v40, v41
	s_nop 0
	v_max3_f32 v100, v100, v42, v43
	s_nop 0
	v_max3_f32 v100, v100, v28, v29
	s_nop 0
	v_max3_f32 v100, v100, v30, v31
	s_nop 0
	v_max3_f32 v100, v100, v32, v33
	s_nop 0
	v_max3_f32 v100, v100, v34, v35
	s_nop 0
	v_max3_f32 v100, v100, v24, v25
	s_nop 0
	v_max3_f32 v100, v100, v26, v27
	s_nop 0
	v_max3_f32 v100, v100, v20, v21
	s_nop 0
	v_max3_f32 v101, v100, v22, v23
	v_xor_b32_e32 v100, 16, v198
	v_cmp_lt_i32_e32 vcc, v100, v102
	s_nop 1
	v_cndmask_b32_e32 v100, v198, v100, vcc
	v_lshlrev_b32_e32 v100, 2, v100
	v_mov_b32_e32 v103, v101
	v_mov_b32_e32 v254, v101
	s_nop 1
	v_permlane16_swap_b32_e32 v103, v254
	s_nop 1
	v_mov_b32_dpp v103, v254 quad_perm:[0,1,2,3] row_mask:0x5 bank_mask:0xf
	v_max_f32_e32 v101, v101, v101
	s_waitcnt lgkmcnt(0)
	v_max_f32_e32 v103, v103, v103
	v_max_f32_e32 v103, v101, v103
	v_xor_b32_e32 v101, 32, v198
	v_cmp_lt_i32_e32 vcc, v101, v102
	s_nop 1
	v_cndmask_b32_e32 v101, v198, v101, vcc
	v_lshlrev_b32_e32 v101, 2, v101
	v_mov_b32_e32 v102, v103
	v_mov_b32_e32 v255, v103
	s_nop 1
	v_permlane32_swap_b32_e32 v102, v255
	s_nop 1
	v_mov_b32_dpp v102, v255 quad_perm:[0,1,2,3] row_mask:0x3 bank_mask:0xf
	s_waitcnt lgkmcnt(0)
; #define LAS __attribute__((address_space(3)))
; DI float fast_exp2(float x) { return __builtin_amdgcn_exp2f(x); }
; #define MFMA16(a, b, c) __builtin_amdgcn_mfma_f32_16x16x32_bf16((a), (b), (c), 0, 0, 0)
; DI u32x2 tr4(const LAS unsigned char* p) { return __builtin_bit_cast(u32x2, __builtin_amdgcn_ds_read_tr16_b64_v4i16((LAS v4i16_t*)p)); }
; DI bf16x8 packp(f32x4 a, f32x4 b) { return __builtin_bit_cast(bf16x8, pack8(a, b)); }
; DI void xattn_unit(const Args& a, const Frame& F, int l, int unit) {
;     ...
;         for (int s8 = 0; s8 < 8; ++s8) {
;             f32x4 e0 = sc[2 * s8] - mx, e1 = sc[2 * s8 + 1] - mx;
; #pragma unroll
;             for (int j = 0; j < 4; ++j) { e0[j] = fast_exp2(e0[j]); e1[j] = fast_exp2(e1[j]); }
;             acc4 = acc4 + e0; acc4 = acc4 + e1;
;             pf[s8] = packp(e0, e1);
; #pragma unroll
;             for (int dt = 0; dt < 8; ++dt) { const LAS unsigned char* vr = F.lds + XA_V + (32 * s8 + 4 * fq + (fr >> 2)) * 288 + (16 * dt + 4 * (fr & 3)) * 2;
;                 O[dt] = MFMA16(cat44(tr4(vr), tr4(vr + 16 * 288)), pf[s8], O[dt]); }
	v_max_f32_e32 v102, v102, v102
	v_max_f32_e32 v102, v103, v102
	v_sub_f32_e32 v83, v83, v102
	v_sub_f32_e32 v82, v82, v102
	v_sub_f32_e32 v81, v81, v102
	v_sub_f32_e32 v80, v80, v102
	v_exp_f32_e32 v132, v80
	v_exp_f32_e32 v133, v81
	v_exp_f32_e32 v134, v82
	v_exp_f32_e32 v135, v83
	ds_read_b64_tr_b16 v[80:81], v89
	ds_read_b64_tr_b16 v[104:105], v89 offset:32
	ds_read_b64_tr_b16 v[82:83], v89 offset:4608
	ds_read_b64_tr_b16 v[106:107], v89 offset:4640
	v_sub_f32_e32 v79, v79, v102
	v_sub_f32_e32 v78, v78, v102
	v_sub_f32_e32 v77, v77, v102
	v_sub_f32_e32 v76, v76, v102
	v_exp_f32_e32 v76, v76
	v_exp_f32_e32 v77, v77
	v_exp_f32_e32 v78, v78
	v_exp_f32_e32 v79, v79
	ds_read_b64_tr_b16 v[108:109], v89 offset:64
	ds_read_b64_tr_b16 v[110:111], v89 offset:4672
	ds_read_b64_tr_b16 v[112:113], v89 offset:96
	ds_read_b64_tr_b16 v[114:115], v89 offset:4704
	ds_read_b64_tr_b16 v[116:117], v89 offset:128
	ds_read_b64_tr_b16 v[118:119], v89 offset:4736
	ds_read_b64_tr_b16 v[120:121], v89 offset:160
	ds_read_b64_tr_b16 v[122:123], v89 offset:4768
	ds_read_b64_tr_b16 v[124:125], v89 offset:192
	ds_read_b64_tr_b16 v[126:127], v89 offset:4800
	ds_read_b64_tr_b16 v[128:129], v89 offset:224
	ds_read_b64_tr_b16 v[130:131], v89 offset:4832
	v_pk_add_f32 v[136:137], v[76:77], 0 op_sel_hi:[1,0]
	v_pk_add_f32 v[138:139], v[78:79], 0 op_sel_hi:[1,0]
	v_cvt_pk_bf16_f32 v76, v76, v77
	v_cvt_pk_bf16_f32 v77, v78, v79
	v_cvt_pk_bf16_f32 v78, v132, v133
	v_cvt_pk_bf16_f32 v79, v134, v135
	v_sub_f32_e32 v71, v71, v102
	v_sub_f32_e32 v70, v70, v102
	v_sub_f32_e32 v69, v69, v102
	v_sub_f32_e32 v68, v68, v102
	v_sub_f32_e32 v75, v75, v102
	v_sub_f32_e32 v74, v74, v102
	v_sub_f32_e32 v73, v73, v102
	v_sub_f32_e32 v72, v72, v102
	s_waitcnt lgkmcnt(13)
	v_mfma_f32_16x16x32_bf16 v[80:83], v[80:83], v[76:79], 0
	v_exp_f32_e32 v68, v68
	v_exp_f32_e32 v69, v69
	v_exp_f32_e32 v70, v70
	s_waitcnt lgkmcnt(12)
	v_mfma_f32_16x16x32_bf16 v[104:107], v[104:107], v[76:79], 0
	v_exp_f32_e32 v71, v71
	v_sub_f32_e32 v63, v63, v102
	v_sub_f32_e32 v62, v62, v102
	s_waitcnt lgkmcnt(10)
	v_mfma_f32_16x16x32_bf16 v[108:111], v[108:111], v[76:79], 0
	v_sub_f32_e32 v61, v61, v102
	v_sub_f32_e32 v60, v60, v102
	v_sub_f32_e32 v67, v67, v102
	s_waitcnt lgkmcnt(8)
	v_mfma_f32_16x16x32_bf16 v[112:115], v[112:115], v[76:79], 0
	v_sub_f32_e32 v66, v66, v102
	v_sub_f32_e32 v65, v65, v102
	v_sub_f32_e32 v64, v64, v102
	s_waitcnt lgkmcnt(6)
	v_mfma_f32_16x16x32_bf16 v[116:119], v[116:119], v[76:79], 0
	v_exp_f32_e32 v60, v60
	v_exp_f32_e32 v61, v61
	v_exp_f32_e32 v62, v62
	s_waitcnt lgkmcnt(4)
	v_mfma_f32_16x16x32_bf16 v[120:123], v[120:123], v[76:79], 0
	v_exp_f32_e32 v63, v63
	v_sub_f32_e32 v55, v55, v102
	v_sub_f32_e32 v54, v54, v102
	s_waitcnt lgkmcnt(2)
	v_mfma_f32_16x16x32_bf16 v[124:127], v[124:127], v[76:79], 0
	v_sub_f32_e32 v53, v53, v102
	v_sub_f32_e32 v52, v52, v102
	v_sub_f32_e32 v59, v59, v102
	s_waitcnt lgkmcnt(0)
	v_mfma_f32_16x16x32_bf16 v[76:79], v[128:131], v[76:79], 0
	v_add_f32_e64 v128, v134, v138
	v_add_f32_e64 v129, v135, v139
	v_pk_add_f32 v[130:131], v[132:133], v[136:137]
	v_exp_f32_e32 v132, v72
	v_exp_f32_e32 v133, v73
	v_exp_f32_e32 v134, v74
	v_exp_f32_e32 v135, v75
	ds_read_b64_tr_b16 v[72:73], v89 offset:9216
	ds_read_b64_tr_b16 v[74:75], v89 offset:13824
	v_pk_add_f32 v[130:131], v[68:69], v[130:131]
	v_pk_add_f32 v[128:129], v[70:71], v[128:129]
	v_cvt_pk_bf16_f32 v68, v68, v69
	v_cvt_pk_bf16_f32 v69, v70, v71
	v_cvt_pk_bf16_f32 v70, v132, v133
	v_cvt_pk_bf16_f32 v71, v134, v135
	v_sub_f32_e32 v58, v58, v102
	v_sub_f32_e32 v57, v57, v102
	s_waitcnt lgkmcnt(0)
	v_mfma_f32_16x16x32_bf16 v[72:75], v[72:75], v[68:71], v[80:83]
	s_nop 2
	ds_read_b64_tr_b16 v[80:81], v89 offset:9248
	ds_read_b64_tr_b16 v[82:83], v89 offset:13856
	v_sub_f32_e32 v56, v56, v102
	v_exp_f32_e32 v52, v52
	s_waitcnt lgkmcnt(0)
	v_mfma_f32_16x16x32_bf16 v[80:83], v[80:83], v[68:71], v[104:107]
	s_nop 2
	ds_read_b64_tr_b16 v[104:105], v89 offset:9280
	ds_read_b64_tr_b16 v[106:107], v89 offset:13888
	v_exp_f32_e32 v53, v53
	v_exp_f32_e32 v54, v54
	s_waitcnt lgkmcnt(0)
	v_mfma_f32_16x16x32_bf16 v[104:107], v[104:107], v[68:71], v[108:111]
	s_nop 2
	ds_read_b64_tr_b16 v[108:109], v89 offset:9312
	ds_read_b64_tr_b16 v[110:111], v89 offset:13920
	v_exp_f32_e32 v55, v55
	v_sub_f32_e32 v47, v47, v102
	s_waitcnt lgkmcnt(0)
	v_mfma_f32_16x16x32_bf16 v[108:111], v[108:111], v[68:71], v[112:115]
	s_nop 2
	ds_read_b64_tr_b16 v[112:113], v89 offset:9344
	ds_read_b64_tr_b16 v[114:115], v89 offset:13952
	v_sub_f32_e32 v46, v46, v102
	v_sub_f32_e32 v45, v45, v102
	s_waitcnt lgkmcnt(0)
	v_mfma_f32_16x16x32_bf16 v[112:115], v[112:115], v[68:71], v[116:119]
	s_nop 2
	ds_read_b64_tr_b16 v[116:117], v89 offset:9376
	ds_read_b64_tr_b16 v[118:119], v89 offset:13984
	v_sub_f32_e32 v44, v44, v102
	v_sub_f32_e32 v51, v51, v102
	s_waitcnt lgkmcnt(0)
	v_mfma_f32_16x16x32_bf16 v[116:119], v[116:119], v[68:71], v[120:123]
	s_nop 2
	ds_read_b64_tr_b16 v[120:121], v89 offset:9408
	ds_read_b64_tr_b16 v[122:123], v89 offset:14016
	v_sub_f32_e32 v50, v50, v102
	v_sub_f32_e32 v49, v49, v102
	s_waitcnt lgkmcnt(0)
	v_mfma_f32_16x16x32_bf16 v[120:123], v[120:123], v[68:71], v[124:127]
	s_nop 2
	ds_read_b64_tr_b16 v[124:125], v89 offset:9440
	ds_read_b64_tr_b16 v[126:127], v89 offset:14048
	v_sub_f32_e32 v48, v48, v102
	v_exp_f32_e32 v44, v44
	s_waitcnt lgkmcnt(0)
; #define LAS __attribute__((address_space(3)))
; DI float fast_exp2(float x) { return __builtin_amdgcn_exp2f(x); }
; #define MFMA16(a, b, c) __builtin_amdgcn_mfma_f32_16x16x32_bf16((a), (b), (c), 0, 0, 0)
; DI u32x2 tr4(const LAS unsigned char* p) { return __builtin_bit_cast(u32x2, __builtin_amdgcn_ds_read_tr16_b64_v4i16((LAS v4i16_t*)p)); }
; DI bf16x8 packp(f32x4 a, f32x4 b) { return __builtin_bit_cast(bf16x8, pack8(a, b)); }
; DI void xattn_unit(const Args& a, const Frame& F, int l, int unit) {
;     ...
;         for (int s8 = 0; s8 < 8; ++s8) {
;             f32x4 e0 = sc[2 * s8] - mx, e1 = sc[2 * s8 + 1] - mx;
; #pragma unroll
;             for (int j = 0; j < 4; ++j) { e0[j] = fast_exp2(e0[j]); e1[j] = fast_exp2(e1[j]); }
;             acc4 = acc4 + e0; acc4 = acc4 + e1;
;             pf[s8] = packp(e0, e1);
; #pragma unroll
;             for (int dt = 0; dt < 8; ++dt) { const LAS unsigned char* vr = F.lds + XA_V + (32 * s8 + 4 * fq + (fr >> 2)) * 288 + (16 * dt + 4 * (fr & 3)) * 2;
;                 O[dt] = MFMA16(cat44(tr4(vr), tr4(vr + 16 * 288)), pf[s8], O[dt]); }
	v_mfma_f32_16x16x32_bf16 v[68:71], v[124:127], v[68:71], v[76:79]
	v_exp_f32_e32 v124, v64
	v_exp_f32_e32 v125, v65
	v_exp_f32_e32 v126, v66
	v_exp_f32_e32 v127, v67
	ds_read_b64_tr_b16 v[64:65], v89 offset:18432
	ds_read_b64_tr_b16 v[66:67], v89 offset:23040
	v_pk_add_f32 v[76:77], v[134:135], v[128:129]
	v_pk_add_f32 v[78:79], v[132:133], v[130:131]
	v_pk_add_f32 v[130:131], v[62:63], v[76:77]
	v_pk_add_f32 v[128:129], v[60:61], v[78:79]
	v_cvt_pk_bf16_f32 v60, v60, v61
	v_cvt_pk_bf16_f32 v61, v62, v63
	v_cvt_pk_bf16_f32 v62, v124, v125
	v_cvt_pk_bf16_f32 v63, v126, v127
	v_exp_f32_e32 v45, v45
	v_exp_f32_e32 v46, v46
	s_waitcnt lgkmcnt(0)
	v_mfma_f32_16x16x32_bf16 v[64:67], v[64:67], v[60:63], v[72:75]
	s_nop 2
	ds_read_b64_tr_b16 v[72:73], v89 offset:18464
	ds_read_b64_tr_b16 v[74:75], v89 offset:23072
	ds_read_b64_tr_b16 v[76:77], v89 offset:18496
	ds_read_b64_tr_b16 v[78:79], v89 offset:23104
	v_exp_f32_e32 v47, v47
	s_waitcnt lgkmcnt(2)
	v_mfma_f32_16x16x32_bf16 v[72:75], v[72:75], v[60:63], v[80:83]
	s_nop 2
	ds_read_b64_tr_b16 v[80:81], v89 offset:18528
	ds_read_b64_tr_b16 v[82:83], v89 offset:23136
	v_sub_f32_e32 v39, v39, v102
	v_sub_f32_e32 v38, v38, v102
	s_waitcnt lgkmcnt(2)
	v_mfma_f32_16x16x32_bf16 v[76:79], v[76:79], v[60:63], v[104:107]
	s_nop 2
	ds_read_b64_tr_b16 v[104:105], v89 offset:18560
	ds_read_b64_tr_b16 v[106:107], v89 offset:23168
	v_sub_f32_e32 v37, v37, v102
	v_sub_f32_e32 v36, v36, v102
	s_waitcnt lgkmcnt(2)
	v_mfma_f32_16x16x32_bf16 v[80:83], v[80:83], v[60:63], v[108:111]
	s_nop 2
	ds_read_b64_tr_b16 v[108:109], v89 offset:18592
	ds_read_b64_tr_b16 v[110:111], v89 offset:23200
	v_exp_f32_e32 v36, v36
	v_exp_f32_e32 v37, v37
	s_waitcnt lgkmcnt(2)
	v_mfma_f32_16x16x32_bf16 v[104:107], v[104:107], v[60:63], v[112:115]
	s_nop 2
	ds_read_b64_tr_b16 v[112:113], v89 offset:18624
	ds_read_b64_tr_b16 v[114:115], v89 offset:23232
	v_exp_f32_e32 v38, v38
	v_exp_f32_e32 v39, v39
	s_waitcnt lgkmcnt(2)
	v_mfma_f32_16x16x32_bf16 v[108:111], v[108:111], v[60:63], v[116:119]
	s_nop 2
	ds_read_b64_tr_b16 v[116:117], v89 offset:18656
	ds_read_b64_tr_b16 v[118:119], v89 offset:23264
	v_sub_f32_e32 v43, v43, v102
	v_sub_f32_e32 v42, v42, v102
	s_waitcnt lgkmcnt(2)
	v_mfma_f32_16x16x32_bf16 v[112:115], v[112:115], v[60:63], v[120:123]
	v_sub_f32_e32 v41, v41, v102
	v_sub_f32_e32 v40, v40, v102
	v_sub_f32_e32 v31, v31, v102
	s_waitcnt lgkmcnt(0)
	v_mfma_f32_16x16x32_bf16 v[60:63], v[116:119], v[60:63], v[68:71]
	v_exp_f32_e32 v116, v56
	v_exp_f32_e32 v117, v57
	v_exp_f32_e32 v118, v58
	v_exp_f32_e32 v119, v59
	ds_read_b64_tr_b16 v[56:57], v89 offset:27648
	ds_read_b64_tr_b16 v[58:59], v89 offset:32256
	v_pk_add_f32 v[68:69], v[126:127], v[130:131]
	v_pk_add_f32 v[70:71], v[124:125], v[128:129]
	v_pk_add_f32 v[122:123], v[54:55], v[68:69]
	v_pk_add_f32 v[120:121], v[52:53], v[70:71]
	v_cvt_pk_bf16_f32 v52, v52, v53
	v_cvt_pk_bf16_f32 v53, v54, v55
	v_cvt_pk_bf16_f32 v54, v116, v117
	v_cvt_pk_bf16_f32 v55, v118, v119
	v_sub_f32_e32 v30, v30, v102
	v_sub_f32_e32 v29, v29, v102
	s_waitcnt lgkmcnt(0)
	v_mfma_f32_16x16x32_bf16 v[56:59], v[56:59], v[52:55], v[64:67]
	s_nop 2
	ds_read_b64_tr_b16 v[64:65], v89 offset:27680
	ds_read_b64_tr_b16 v[66:67], v89 offset:32288
	ds_read_b64_tr_b16 v[68:69], v89 offset:27712
	ds_read_b64_tr_b16 v[70:71], v89 offset:32320
	v_sub_f32_e32 v28, v28, v102
	s_waitcnt lgkmcnt(2)
	v_mfma_f32_16x16x32_bf16 v[64:67], v[64:67], v[52:55], v[72:75]
	s_nop 2
	ds_read_b64_tr_b16 v[72:73], v89 offset:27744
	ds_read_b64_tr_b16 v[74:75], v89 offset:32352
	v_exp_f32_e32 v28, v28
	v_exp_f32_e32 v29, v29
	s_waitcnt lgkmcnt(2)
	v_mfma_f32_16x16x32_bf16 v[68:71], v[68:71], v[52:55], v[76:79]
	s_nop 2
	ds_read_b64_tr_b16 v[76:77], v89 offset:27776
	ds_read_b64_tr_b16 v[78:79], v89 offset:32384
	v_exp_f32_e32 v30, v30
	v_exp_f32_e32 v31, v31
	s_waitcnt lgkmcnt(2)
	v_mfma_f32_16x16x32_bf16 v[72:75], v[72:75], v[52:55], v[80:83]
	s_nop 2
	ds_read_b64_tr_b16 v[80:81], v89 offset:27808
	ds_read_b64_tr_b16 v[82:83], v89 offset:32416
	v_sub_f32_e32 v35, v35, v102
	v_sub_f32_e32 v34, v34, v102
	s_waitcnt lgkmcnt(2)
	v_mfma_f32_16x16x32_bf16 v[76:79], v[76:79], v[52:55], v[104:107]
	s_nop 2
	ds_read_b64_tr_b16 v[104:105], v89 offset:27840
	ds_read_b64_tr_b16 v[106:107], v89 offset:32448
	v_sub_f32_e32 v33, v33, v102
	v_sub_f32_e32 v32, v32, v102
	s_waitcnt lgkmcnt(2)
	v_mfma_f32_16x16x32_bf16 v[80:83], v[80:83], v[52:55], v[108:111]
	s_nop 2
	ds_read_b64_tr_b16 v[108:109], v89 offset:27872
	ds_read_b64_tr_b16 v[110:111], v89 offset:32480
	v_sub_f32_e32 v27, v27, v102
	v_sub_f32_e32 v26, v26, v102
	s_waitcnt lgkmcnt(2)
	v_mfma_f32_16x16x32_bf16 v[104:107], v[104:107], v[52:55], v[112:115]
	v_sub_f32_e32 v25, v25, v102
	v_sub_f32_e32 v24, v24, v102
	s_waitcnt lgkmcnt(0)
	v_mfma_f32_16x16x32_bf16 v[52:55], v[108:111], v[52:55], v[60:63]
	s_nop 2
	v_add_f32_e64 v60, v118, v122
	v_add_f32_e64 v61, v119, v123
	v_pk_add_f32 v[62:63], v[116:117], v[120:121]
	v_exp_f32_e32 v116, v48
	v_exp_f32_e32 v117, v49
	v_exp_f32_e32 v118, v50
	v_exp_f32_e32 v119, v51
	ds_read_b64_tr_b16 v[48:49], v89 offset:36864
	ds_read_b64_tr_b16 v[50:51], v89 offset:41472
	v_pk_add_f32 v[120:121], v[44:45], v[62:63]
	v_pk_add_f32 v[122:123], v[46:47], v[60:61]
	v_cvt_pk_bf16_f32 v44, v44, v45
	v_cvt_pk_bf16_f32 v45, v46, v47
	v_cvt_pk_bf16_f32 v46, v116, v117
	v_cvt_pk_bf16_f32 v47, v118, v119
	s_waitcnt lgkmcnt(0)
	s_nop 0
	v_mfma_f32_16x16x32_bf16 v[48:51], v[48:51], v[44:47], v[56:59]
	s_nop 2
	ds_read_b64_tr_b16 v[56:57], v89 offset:36896
	ds_read_b64_tr_b16 v[58:59], v89 offset:41504
	s_waitcnt lgkmcnt(0)
; #define LAS __attribute__((address_space(3)))
; DI float fast_exp2(float x) { return __builtin_amdgcn_exp2f(x); }
; #define MFMA16(a, b, c) __builtin_amdgcn_mfma_f32_16x16x32_bf16((a), (b), (c), 0, 0, 0)
; DI u32x2 tr4(const LAS unsigned char* p) { return __builtin_bit_cast(u32x2, __builtin_amdgcn_ds_read_tr16_b64_v4i16((LAS v4i16_t*)p)); }
; DI bf16x8 packp(f32x4 a, f32x4 b) { return __builtin_bit_cast(bf16x8, pack8(a, b)); }
; DI void xattn_unit(const Args& a, const Frame& F, int l, int unit) {
;     ...
;         for (int s8 = 0; s8 < 8; ++s8) {
;             f32x4 e0 = sc[2 * s8] - mx, e1 = sc[2 * s8 + 1] - mx;
; #pragma unroll
;             for (int j = 0; j < 4; ++j) { e0[j] = fast_exp2(e0[j]); e1[j] = fast_exp2(e1[j]); }
;             acc4 = acc4 + e0; acc4 = acc4 + e1;
;             pf[s8] = packp(e0, e1);
; #pragma unroll
;             for (int dt = 0; dt < 8; ++dt) { const LAS unsigned char* vr = F.lds + XA_V + (32 * s8 + 4 * fq + (fr >> 2)) * 288 + (16 * dt + 4 * (fr & 3)) * 2;
;                 O[dt] = MFMA16(cat44(tr4(vr), tr4(vr + 16 * 288)), pf[s8], O[dt]); }
	v_mfma_f32_16x16x32_bf16 v[108:111], v[56:59], v[44:47], v[64:67]
	ds_read_b64_tr_b16 v[56:57], v89 offset:36928
	ds_read_b64_tr_b16 v[58:59], v89 offset:41536
	s_waitcnt lgkmcnt(0)
	v_mfma_f32_16x16x32_bf16 v[112:115], v[56:59], v[44:47], v[68:71]
	ds_read_b64_tr_b16 v[56:57], v89 offset:36960
	ds_read_b64_tr_b16 v[58:59], v89 offset:41568
	s_waitcnt lgkmcnt(0)
	v_mfma_f32_16x16x32_bf16 v[72:75], v[56:59], v[44:47], v[72:75]
	ds_read_b64_tr_b16 v[56:57], v89 offset:36992
	ds_read_b64_tr_b16 v[58:59], v89 offset:41600
	ds_read_b64_tr_b16 v[60:61], v89 offset:37024
	ds_read_b64_tr_b16 v[62:63], v89 offset:41632
	ds_read_b64_tr_b16 v[64:65], v89 offset:37056
	ds_read_b64_tr_b16 v[66:67], v89 offset:41664
	ds_read_b64_tr_b16 v[68:69], v89 offset:37088
	ds_read_b64_tr_b16 v[70:71], v89 offset:41696
	s_waitcnt lgkmcnt(6)
	v_mfma_f32_16x16x32_bf16 v[56:59], v[56:59], v[44:47], v[76:79]
	s_nop 2
	v_cvt_pk_bf16_f32 v76, v36, v37
	s_waitcnt lgkmcnt(4)
	v_mfma_f32_16x16x32_bf16 v[60:63], v[60:63], v[44:47], v[80:83]
	v_cvt_pk_bf16_f32 v77, v38, v39
	s_waitcnt lgkmcnt(2)
	v_mfma_f32_16x16x32_bf16 v[64:67], v[64:67], v[44:47], v[104:107]
	s_waitcnt lgkmcnt(0)
	v_mfma_f32_16x16x32_bf16 v[44:47], v[68:71], v[44:47], v[52:55]
	v_exp_f32_e32 v68, v40
	v_exp_f32_e32 v69, v41
	v_exp_f32_e32 v70, v42
	v_pk_add_f32 v[52:53], v[118:119], v[122:123]
	v_pk_add_f32 v[54:55], v[116:117], v[120:121]
	v_exp_f32_e32 v71, v43
	v_pk_add_f32 v[80:81], v[36:37], v[54:55]
	v_pk_add_f32 v[82:83], v[38:39], v[52:53]
	ds_read_b64_tr_b16 v[36:37], v89 offset:46080
	ds_read_b64_tr_b16 v[38:39], v89 offset:50688
	v_cvt_pk_bf16_f32 v78, v68, v69
	v_cvt_pk_bf16_f32 v79, v70, v71
	ds_read_b64_tr_b16 v[40:41], v89 offset:46112
	ds_read_b64_tr_b16 v[42:43], v89 offset:50720
	s_waitcnt lgkmcnt(2)
	v_mfma_f32_16x16x32_bf16 v[36:39], v[36:39], v[76:79], v[48:51]
	s_nop 2
	ds_read_b64_tr_b16 v[48:49], v89 offset:46144
	ds_read_b64_tr_b16 v[50:51], v89 offset:50752
	ds_read_b64_tr_b16 v[52:53], v89 offset:46176
	ds_read_b64_tr_b16 v[54:55], v89 offset:50784
	v_pk_add_f32 v[70:71], v[70:71], v[82:83]
	s_waitcnt lgkmcnt(0)
	v_mfma_f32_16x16x32_bf16 v[52:55], v[52:55], v[76:79], v[72:75]
	s_nop 2
	ds_read_b64_tr_b16 v[72:73], v89 offset:46208
	ds_read_b64_tr_b16 v[74:75], v89 offset:50816
	s_waitcnt lgkmcnt(0)
	v_mfma_f32_16x16x32_bf16 v[56:59], v[72:75], v[76:79], v[56:59]
	ds_read_b64_tr_b16 v[72:73], v89 offset:46240
	ds_read_b64_tr_b16 v[74:75], v89 offset:50848
	s_waitcnt lgkmcnt(0)
	v_mfma_f32_16x16x32_bf16 v[60:63], v[72:75], v[76:79], v[60:63]
	ds_read_b64_tr_b16 v[72:73], v89 offset:46272
	ds_read_b64_tr_b16 v[74:75], v89 offset:50880
	s_waitcnt lgkmcnt(0)
	v_mfma_f32_16x16x32_bf16 v[64:67], v[72:75], v[76:79], v[64:67]
	ds_read_b64_tr_b16 v[72:73], v89 offset:46304
	ds_read_b64_tr_b16 v[74:75], v89 offset:50912
	s_waitcnt lgkmcnt(0)
	v_mfma_f32_16x16x32_bf16 v[44:47], v[72:75], v[76:79], v[44:47]
	v_add_f32_e64 v72, v68, v80
	v_add_f32_e64 v73, v69, v81
	v_exp_f32_e32 v68, v32
	v_exp_f32_e32 v69, v33
	v_mfma_f32_16x16x32_bf16 v[40:43], v[40:43], v[76:79], v[108:111]
	v_exp_f32_e32 v74, v34
	v_exp_f32_e32 v75, v35
	v_mfma_f32_16x16x32_bf16 v[48:51], v[48:51], v[76:79], v[112:115]
	v_add_f32_e64 v76, v28, v72
	v_add_f32_e64 v77, v29, v73
	v_pk_add_f32 v[78:79], v[30:31], v[70:71]
	v_cvt_pk_bf16_f32 v70, v28, v29
	v_cvt_pk_bf16_f32 v71, v30, v31
	ds_read_b64_tr_b16 v[28:29], v89 offset:55296
	ds_read_b64_tr_b16 v[30:31], v89 offset:59904
	v_cvt_pk_bf16_f32 v72, v68, v69
	v_cvt_pk_bf16_f32 v73, v74, v75
	s_waitcnt lgkmcnt(0)
	s_nop 0
	v_mfma_f32_16x16x32_bf16 v[32:35], v[28:31], v[70:73], v[36:39]
	ds_read_b64_tr_b16 v[28:29], v89 offset:55328
	ds_read_b64_tr_b16 v[30:31], v89 offset:59936
	s_waitcnt lgkmcnt(0)
	v_mfma_f32_16x16x32_bf16 v[36:39], v[28:31], v[70:73], v[40:43]
	ds_read_b64_tr_b16 v[28:29], v89 offset:55360
	ds_read_b64_tr_b16 v[30:31], v89 offset:59968
	s_waitcnt lgkmcnt(0)
	v_mfma_f32_16x16x32_bf16 v[40:43], v[28:31], v[70:73], v[48:51]
	ds_read_b64_tr_b16 v[28:29], v89 offset:55392
	ds_read_b64_tr_b16 v[30:31], v89 offset:60000
	s_waitcnt lgkmcnt(0)
	v_mfma_f32_16x16x32_bf16 v[48:51], v[28:31], v[70:73], v[52:55]
	ds_read_b64_tr_b16 v[28:29], v89 offset:55424
	ds_read_b64_tr_b16 v[30:31], v89 offset:60032
	s_waitcnt lgkmcnt(0)
	v_mfma_f32_16x16x32_bf16 v[52:55], v[28:31], v[70:73], v[56:59]
	ds_read_b64_tr_b16 v[28:29], v89 offset:55456
	ds_read_b64_tr_b16 v[30:31], v89 offset:60064
	s_nop 0
	ds_read_b64_tr_b16 v[56:57], v89 offset:55488
	ds_read_b64_tr_b16 v[58:59], v89 offset:60096
	s_waitcnt lgkmcnt(2)
	v_mfma_f32_16x16x32_bf16 v[28:31], v[28:31], v[70:73], v[60:63]
	s_nop 2
	ds_read_b64_tr_b16 v[60:61], v89 offset:55520
	ds_read_b64_tr_b16 v[62:63], v89 offset:60128
	s_waitcnt lgkmcnt(2)
	v_mfma_f32_16x16x32_bf16 v[56:59], v[56:59], v[70:73], v[64:67]
	s_nop 2
	v_sub_f32_e32 v67, v23, v102
	v_sub_f32_e32 v23, v22, v102
	v_sub_f32_e32 v22, v21, v102
	v_sub_f32_e32 v21, v20, v102
	v_exp_f32_e32 v20, v24
	v_exp_f32_e32 v64, v21
	v_exp_f32_e32 v21, v25
	v_exp_f32_e32 v65, v22
	v_exp_f32_e32 v22, v26
	v_exp_f32_e32 v66, v23
	v_exp_f32_e32 v23, v27
	v_exp_f32_e32 v67, v67
	ds_read_b64_tr_b16 v[24:25], v89 offset:64512
	ds_read_b64_tr_b16 v[26:27], v90
	s_waitcnt lgkmcnt(2)
; #define LAS __attribute__((address_space(3)))
; DI unsigned pk2(float lo, float hi) { const f32x2 v = {lo, hi}; return __builtin_bit_cast(unsigned, __builtin_convertvector(v, hwbf16x2)); }
; DI float fast_exp2(float x) { return __builtin_amdgcn_exp2f(x); }
; #define MFMA16(a, b, c) __builtin_amdgcn_mfma_f32_16x16x32_bf16((a), (b), (c), 0, 0, 0)
; DI u32x2 tr4(const LAS unsigned char* p) { return __builtin_bit_cast(u32x2, __builtin_amdgcn_ds_read_tr16_b64_v4i16((LAS v4i16_t*)p)); }
; DI bf16x8 packp(f32x4 a, f32x4 b) { return __builtin_bit_cast(bf16x8, pack8(a, b)); }
; DI void xattn_unit(const Args& a, const Frame& F, int l, int unit) {
;     ...
;         for (int s8 = 0; s8 < 8; ++s8) {
;             f32x4 e0 = sc[2 * s8] - mx, e1 = sc[2 * s8 + 1] - mx;
; #pragma unroll
;             for (int j = 0; j < 4; ++j) { e0[j] = fast_exp2(e0[j]); e1[j] = fast_exp2(e1[j]); }
;             acc4 = acc4 + e0; acc4 = acc4 + e1;
;             pf[s8] = packp(e0, e1);
; #pragma unroll
;             for (int dt = 0; dt < 8; ++dt) { const LAS unsigned char* vr = F.lds + XA_V + (32 * s8 + 4 * fq + (fr >> 2)) * 288 + (16 * dt + 4 * (fr & 3)) * 2;
;                 O[dt] = MFMA16(cat44(tr4(vr), tr4(vr + 16 * 288)), pf[s8], O[dt]); }
;         }
;         float ls = (acc4[0] + acc4[1]) + (acc4[2] + acc4[3]);
;         ls += __shfl_xor(ls, 16); ls += __shfl_xor(ls, 32);
;         const float inv = 1.f / ls;
;         bf16* op = OX + (size_t)row * XW + h * 128 + 4 * fq;
; #pragma unroll
;         for (int dt = 0; dt < 8; ++dt) { const f32x4 o = O[dt] * inv; u32x2 w; w.x = pk2(o[0], o[1]); w.y = pk2(o[2], o[3]); *(u32x2*)(op + 16 * dt) = w; }
; #pragma unroll
;         for (int ks = 0; ks < 4; ++ks) qc[ks] = qn[ks];
	v_mfma_f32_16x16x32_bf16 v[44:47], v[60:63], v[70:73], v[44:47]
	v_add_f32_e64 v60, v74, v78
	v_add_f32_e64 v61, v75, v79
	v_pk_add_f32 v[62:63], v[68:69], v[76:77]
	v_pk_add_f32 v[60:61], v[22:23], v[60:61]
	v_pk_add_f32 v[62:63], v[20:21], v[62:63]
	v_cvt_pk_bf16_f32 v20, v20, v21
	v_cvt_pk_bf16_f32 v21, v22, v23
	v_cvt_pk_bf16_f32 v22, v64, v65
	v_cvt_pk_bf16_f32 v23, v66, v67
	s_waitcnt lgkmcnt(0)
	s_nop 0
	v_mfma_f32_16x16x32_bf16 v[24:27], v[24:27], v[20:23], v[32:35]
	s_nop 2
	ds_read_b64_tr_b16 v[32:33], v89 offset:64544
	ds_read_b64_tr_b16 v[34:35], v91
	s_waitcnt lgkmcnt(0)
	v_mfma_f32_16x16x32_bf16 v[32:35], v[32:35], v[20:23], v[36:39]
	s_nop 2
	ds_read_b64_tr_b16 v[36:37], v89 offset:64576
	ds_read_b64_tr_b16 v[38:39], v92
	s_waitcnt lgkmcnt(0)
	v_mfma_f32_16x16x32_bf16 v[36:39], v[36:39], v[20:23], v[40:43]
	s_nop 2
	ds_read_b64_tr_b16 v[40:41], v89 offset:64608
	ds_read_b64_tr_b16 v[42:43], v93
	s_waitcnt lgkmcnt(0)
	v_mfma_f32_16x16x32_bf16 v[40:43], v[40:43], v[20:23], v[48:51]
	s_nop 2
	ds_read_b64_tr_b16 v[48:49], v89 offset:64640
	ds_read_b64_tr_b16 v[50:51], v95
	s_waitcnt lgkmcnt(0)
	v_mfma_f32_16x16x32_bf16 v[48:51], v[48:51], v[20:23], v[52:55]
	s_nop 2
	ds_read_b64_tr_b16 v[52:53], v89 offset:64672
	ds_read_b64_tr_b16 v[54:55], v96
	s_waitcnt lgkmcnt(0)
	v_mfma_f32_16x16x32_bf16 v[28:31], v[52:55], v[20:23], v[28:31]
	ds_read_b64_tr_b16 v[52:53], v89 offset:64704
	ds_read_b64_tr_b16 v[54:55], v97
	s_waitcnt lgkmcnt(0)
	v_mfma_f32_16x16x32_bf16 v[52:55], v[52:55], v[20:23], v[56:59]
	s_nop 2
	ds_read_b64_tr_b16 v[56:57], v89 offset:64736
	ds_read_b64_tr_b16 v[58:59], v98
	s_waitcnt lgkmcnt(0)
	v_mfma_f32_16x16x32_bf16 v[20:23], v[56:59], v[20:23], v[44:47]
	v_add_u32_e32 v56, s6, v99
	s_nop 1
	v_pk_add_f32 v[44:45], v[66:67], v[60:61]
	v_pk_add_f32 v[46:47], v[64:65], v[62:63]
	s_addk_i32 s6, 0x80
	v_pk_mov_b32 v[58:59], v[46:47], v[44:45] op_sel:[1,0]
	v_mov_b32_e32 v47, v45
	v_pk_add_f32 v[44:45], v[58:59], v[46:47]
	s_cmpk_eq_i32 s6, 0x200
	v_add_f32_e32 v44, v44, v45
	v_mov_b32_e32 v45, v44
	v_mov_b32_e32 v254, v44
	s_nop 1
	v_permlane16_swap_b32_e32 v45, v254
	s_nop 1
	v_mov_b32_dpp v45, v254 quad_perm:[0,1,2,3] row_mask:0x5 bank_mask:0xf
	s_waitcnt lgkmcnt(0)
	v_add_f32_e32 v44, v44, v45
	v_mov_b32_e32 v45, v44
	v_mov_b32_e32 v255, v44
	s_nop 1
	v_permlane32_swap_b32_e32 v45, v255
	s_nop 1
	v_mov_b32_dpp v45, v255 quad_perm:[0,1,2,3] row_mask:0x3 bank_mask:0xf
	s_waitcnt lgkmcnt(0)
	v_add_f32_e32 v44, v44, v45
	v_div_scale_f32 v45, s[0:1], v44, v44, 1.0
	v_rcp_f32_e32 v46, v45
	s_cselect_b64 s[0:1], -1, 0
	v_fma_f32 v47, -v45, v46, 1.0
	v_fmac_f32_e32 v46, v47, v46
	v_div_scale_f32 v47, vcc, 1.0, v44, 1.0
	v_mul_f32_e32 v57, v47, v46
	v_fma_f32 v58, -v45, v57, v47
	v_fmac_f32_e32 v57, v58, v46
	v_fma_f32 v45, -v45, v57, v47
	v_div_fmas_f32 v45, v45, v46, v57
	v_div_fixup_f32 v44, v45, v44, 1.0
	v_ashrrev_i32_e32 v57, 31, v56
	v_lshlrev_b64 v[46:47], 10, v[56:57]
	v_pk_mul_f32 v[26:27], v[26:27], v[44:45] op_sel_hi:[1,0]
	v_pk_mul_f32 v[24:25], v[24:25], v[44:45] op_sel_hi:[1,0]
	v_lshl_add_u64 v[46:47], v[86:87], 0, v[46:47]
	v_cvt_pk_bf16_f32 v24, v24, v25
	v_cvt_pk_bf16_f32 v25, v26, v27
	global_store_dwordx2 v[46:47], v[24:25], off
	v_pk_mul_f32 v[24:25], v[34:35], v[44:45] op_sel_hi:[1,0]
	v_pk_mul_f32 v[26:27], v[32:33], v[44:45] op_sel_hi:[1,0]
	v_pk_mul_f32 v[22:23], v[22:23], v[44:45] op_sel_hi:[1,0]
	v_cvt_pk_bf16_f32 v26, v26, v27
	v_cvt_pk_bf16_f32 v27, v24, v25
	global_store_dwordx2 v[46:47], v[26:27], off offset:32
	v_pk_mul_f32 v[24:25], v[38:39], v[44:45] op_sel_hi:[1,0]
	v_pk_mul_f32 v[26:27], v[36:37], v[44:45] op_sel_hi:[1,0]
	v_pk_mul_f32 v[20:21], v[20:21], v[44:45] op_sel_hi:[1,0]
	v_cvt_pk_bf16_f32 v26, v26, v27
	v_cvt_pk_bf16_f32 v27, v24, v25
	global_store_dwordx2 v[46:47], v[26:27], off offset:64
	v_pk_mul_f32 v[24:25], v[42:43], v[44:45] op_sel_hi:[1,0]
	v_pk_mul_f32 v[26:27], v[40:41], v[44:45] op_sel_hi:[1,0]
	v_cvt_pk_bf16_f32 v20, v20, v21
	v_cvt_pk_bf16_f32 v26, v26, v27
	v_cvt_pk_bf16_f32 v27, v24, v25
	global_store_dwordx2 v[46:47], v[26:27], off offset:96
	v_pk_mul_f32 v[24:25], v[50:51], v[44:45] op_sel_hi:[1,0]
	v_pk_mul_f32 v[26:27], v[48:49], v[44:45] op_sel_hi:[1,0]
	v_cvt_pk_bf16_f32 v21, v22, v23
	v_cvt_pk_bf16_f32 v26, v26, v27
	v_cvt_pk_bf16_f32 v27, v24, v25
	global_store_dwordx2 v[46:47], v[26:27], off offset:128
	v_pk_mul_f32 v[24:25], v[30:31], v[44:45] op_sel_hi:[1,0]
	v_pk_mul_f32 v[26:27], v[28:29], v[44:45] op_sel_hi:[1,0]
	global_store_dwordx2 v[46:47], v[20:21], off offset:224
	v_cvt_pk_bf16_f32 v26, v26, v27
	v_cvt_pk_bf16_f32 v27, v24, v25
	global_store_dwordx2 v[46:47], v[26:27], off offset:160
	v_pk_mul_f32 v[24:25], v[54:55], v[44:45] op_sel_hi:[1,0]
	v_pk_mul_f32 v[26:27], v[52:53], v[44:45] op_sel_hi:[1,0]
	s_waitcnt vmcnt(7)
	v_mov_b64_e32 v[22:23], v[18:19]
	v_cvt_pk_bf16_f32 v26, v26, v27
	v_cvt_pk_bf16_f32 v27, v24, v25
	global_store_dwordx2 v[46:47], v[26:27], off offset:192
	v_mov_b64_e32 v[26:27], v[14:15]
	v_mov_b64_e32 v[30:31], v[10:11]
	v_mov_b64_e32 v[34:35], v[6:7]
	v_mov_b64_e32 v[20:21], v[16:17]
	v_mov_b64_e32 v[24:25], v[12:13]
	v_mov_b64_e32 v[28:29], v[8:9]
	v_mov_b64_e32 v[32:33], v[4:5]
	s_branch .LBB0_2039
